# residual-update GEMM epilogues: non-temporal hint on the streaming f32 residual loads and output stores
# baseline (speedup 1.0000x reference)
.LBB0_250:
	v_lshl_add_u32 v152, s52, 8, v142
	v_lshl_or_b32 v154, s53, 8, v144
	v_ashrrev_i32_e32 v153, 31, v152
	v_ashrrev_i32_e32 v155, 31, v154
	v_lshlrev_b64 v[140:141], 10, v[152:153]
	v_lshl_add_u64 v[140:141], v[140:141], 0, v[154:155]
	v_lshlrev_b64 v[140:141], 2, v[140:141]
	v_lshl_add_u64 v[156:157], s[6:7], 0, v[140:141]
	global_load_dwordx4 v[148:151], v[156:157], off nt
	v_lshl_add_u64 v[158:159], s[8:9], 0, v[140:141]
	s_and_b64 vcc, exec, s[2:3]
	s_mov_b64 s[2:3], -1
	s_waitcnt vmcnt(0)
	v_pk_fma_f32 v[126:127], v[126:127], 0.5, v[150:151] op_sel_hi:[1,0,1]
	v_pk_fma_f32 v[124:125], v[124:125], 0.5, v[148:149] op_sel_hi:[1,0,1]
	global_store_dwordx4 v[158:159], v[124:127], off nt
	global_load_dwordx4 v[124:127], v[156:157], off offset:64 nt
	s_waitcnt vmcnt(0)
	v_pk_fma_f32 v[122:123], v[122:123], 0.5, v[126:127] op_sel_hi:[1,0,1]
	v_pk_fma_f32 v[120:121], v[120:121], 0.5, v[124:125] op_sel_hi:[1,0,1]
	global_store_dwordx4 v[158:159], v[120:123], off offset:64 nt
	global_load_dwordx4 v[120:123], v[156:157], off offset:512 nt
	s_waitcnt vmcnt(0)
	v_pk_fma_f32 v[118:119], v[118:119], 0.5, v[122:123] op_sel_hi:[1,0,1]
	v_pk_fma_f32 v[116:117], v[116:117], 0.5, v[120:121] op_sel_hi:[1,0,1]
	global_store_dwordx4 v[158:159], v[116:119], off offset:512 nt
	global_load_dwordx4 v[116:119], v[156:157], off offset:576 nt
	v_or_b32_e32 v120, 16, v152
	v_ashrrev_i32_e32 v121, 31, v120
	v_lshlrev_b64 v[120:121], 10, v[120:121]
	v_lshl_add_u64 v[120:121], v[120:121], 0, v[154:155]
	v_lshlrev_b64 v[120:121], 2, v[120:121]
	v_lshl_add_u64 v[122:123], s[6:7], 0, v[120:121]
	s_waitcnt vmcnt(0)
	v_pk_fma_f32 v[106:107], v[106:107], 0.5, v[118:119] op_sel_hi:[1,0,1]
	v_pk_fma_f32 v[104:105], v[104:105], 0.5, v[116:117] op_sel_hi:[1,0,1]
	global_store_dwordx4 v[158:159], v[104:107], off offset:576 nt
	global_load_dwordx4 v[104:107], v[122:123], off nt
	v_lshl_add_u64 v[116:117], s[8:9], 0, v[120:121]
	s_waitcnt vmcnt(0)
	v_pk_fma_f32 v[106:107], v[114:115], 0.5, v[106:107] op_sel_hi:[1,0,1]
	v_pk_fma_f32 v[104:105], v[112:113], 0.5, v[104:105] op_sel_hi:[1,0,1]
	global_store_dwordx4 v[116:117], v[104:107], off nt
	global_load_dwordx4 v[104:107], v[122:123], off offset:64 nt
	s_waitcnt vmcnt(0)
	v_pk_fma_f32 v[106:107], v[110:111], 0.5, v[106:107] op_sel_hi:[1,0,1]
	v_pk_fma_f32 v[104:105], v[108:109], 0.5, v[104:105] op_sel_hi:[1,0,1]
	global_store_dwordx4 v[116:117], v[104:107], off offset:64 nt
	global_load_dwordx4 v[104:107], v[122:123], off offset:512 nt
	s_waitcnt vmcnt(0)
	v_pk_fma_f32 v[102:103], v[102:103], 0.5, v[106:107] op_sel_hi:[1,0,1]
	v_pk_fma_f32 v[100:101], v[100:101], 0.5, v[104:105] op_sel_hi:[1,0,1]
	global_store_dwordx4 v[116:117], v[100:103], off offset:512 nt
	global_load_dwordx4 v[100:103], v[122:123], off offset:576 nt
	v_or_b32_e32 v104, 32, v152
	v_ashrrev_i32_e32 v105, 31, v104
	v_lshlrev_b64 v[104:105], 10, v[104:105]
	v_lshl_add_u64 v[104:105], v[104:105], 0, v[154:155]
	v_lshlrev_b64 v[104:105], 2, v[104:105]
	v_lshl_add_u64 v[106:107], s[6:7], 0, v[104:105]
	s_waitcnt vmcnt(0)
	v_pk_fma_f32 v[90:91], v[90:91], 0.5, v[102:103] op_sel_hi:[1,0,1]
	v_pk_fma_f32 v[88:89], v[88:89], 0.5, v[100:101] op_sel_hi:[1,0,1]
	global_store_dwordx4 v[116:117], v[88:91], off offset:576 nt
	global_load_dwordx4 v[88:91], v[106:107], off nt
	v_lshl_add_u64 v[100:101], s[8:9], 0, v[104:105]
	s_waitcnt vmcnt(0)
	v_pk_fma_f32 v[90:91], v[98:99], 0.5, v[90:91] op_sel_hi:[1,0,1]
	v_pk_fma_f32 v[88:89], v[96:97], 0.5, v[88:89] op_sel_hi:[1,0,1]
	global_store_dwordx4 v[100:101], v[88:91], off nt
	global_load_dwordx4 v[88:91], v[106:107], off offset:64 nt
	s_waitcnt vmcnt(0)
	v_pk_fma_f32 v[90:91], v[94:95], 0.5, v[90:91] op_sel_hi:[1,0,1]
	v_pk_fma_f32 v[88:89], v[92:93], 0.5, v[88:89] op_sel_hi:[1,0,1]
	global_store_dwordx4 v[100:101], v[88:91], off offset:64 nt
	global_load_dwordx4 v[88:91], v[106:107], off offset:512 nt
	s_waitcnt vmcnt(0)
	v_pk_fma_f32 v[86:87], v[86:87], 0.5, v[90:91] op_sel_hi:[1,0,1]
	v_pk_fma_f32 v[84:85], v[84:85], 0.5, v[88:89] op_sel_hi:[1,0,1]
	global_store_dwordx4 v[100:101], v[84:87], off offset:512 nt
	global_load_dwordx4 v[84:87], v[106:107], off offset:576 nt
	v_or_b32_e32 v88, 48, v152
	v_ashrrev_i32_e32 v89, 31, v88
	v_lshlrev_b64 v[88:89], 10, v[88:89]
	v_lshl_add_u64 v[88:89], v[88:89], 0, v[154:155]
	v_lshlrev_b64 v[88:89], 2, v[88:89]
	v_lshl_add_u64 v[90:91], s[6:7], 0, v[88:89]
	s_waitcnt vmcnt(0)
	v_pk_fma_f32 v[74:75], v[74:75], 0.5, v[86:87] op_sel_hi:[1,0,1]
	v_pk_fma_f32 v[72:73], v[72:73], 0.5, v[84:85] op_sel_hi:[1,0,1]
	global_store_dwordx4 v[100:101], v[72:75], off offset:576 nt
	global_load_dwordx4 v[72:75], v[90:91], off nt
	v_lshl_add_u64 v[84:85], s[8:9], 0, v[88:89]
	s_waitcnt vmcnt(0)
	v_pk_fma_f32 v[74:75], v[82:83], 0.5, v[74:75] op_sel_hi:[1,0,1]
	v_pk_fma_f32 v[72:73], v[80:81], 0.5, v[72:73] op_sel_hi:[1,0,1]
	global_store_dwordx4 v[84:85], v[72:75], off nt
	global_load_dwordx4 v[72:75], v[90:91], off offset:64 nt
	s_waitcnt vmcnt(0)
	v_pk_fma_f32 v[74:75], v[78:79], 0.5, v[74:75] op_sel_hi:[1,0,1]
	v_pk_fma_f32 v[72:73], v[76:77], 0.5, v[72:73] op_sel_hi:[1,0,1]
	global_store_dwordx4 v[84:85], v[72:75], off offset:64 nt
	global_load_dwordx4 v[72:75], v[90:91], off offset:512 nt
	s_waitcnt vmcnt(0)
	v_pk_fma_f32 v[70:71], v[70:71], 0.5, v[74:75] op_sel_hi:[1,0,1]
	v_pk_fma_f32 v[68:69], v[68:69], 0.5, v[72:73] op_sel_hi:[1,0,1]
	global_store_dwordx4 v[84:85], v[68:71], off offset:512 nt
	global_load_dwordx4 v[68:71], v[90:91], off offset:576 nt
	v_lshl_add_u64 v[72:73], v[140:141], 0, s[18:19]
	v_lshl_add_u64 v[74:75], s[6:7], 0, v[72:73]
	s_waitcnt vmcnt(0)
	v_pk_fma_f32 v[66:67], v[66:67], 0.5, v[70:71] op_sel_hi:[1,0,1]
	v_pk_fma_f32 v[64:65], v[64:65], 0.5, v[68:69] op_sel_hi:[1,0,1]
	global_store_dwordx4 v[84:85], v[64:67], off offset:576 nt
	global_load_dwordx4 v[64:67], v[74:75], off nt
	v_lshl_add_u64 v[68:69], s[8:9], 0, v[72:73]
	s_waitcnt vmcnt(0)
	v_pk_fma_f32 v[62:63], v[62:63], 0.5, v[66:67] op_sel_hi:[1,0,1]
	v_pk_fma_f32 v[60:61], v[60:61], 0.5, v[64:65] op_sel_hi:[1,0,1]
	global_store_dwordx4 v[68:69], v[60:63], off nt
	global_load_dwordx4 v[60:63], v[74:75], off offset:64 nt
	s_waitcnt vmcnt(0)
	v_pk_fma_f32 v[58:59], v[58:59], 0.5, v[62:63] op_sel_hi:[1,0,1]
	v_pk_fma_f32 v[56:57], v[56:57], 0.5, v[60:61] op_sel_hi:[1,0,1]
	global_store_dwordx4 v[68:69], v[56:59], off offset:64 nt
	global_load_dwordx4 v[56:59], v[74:75], off offset:512 nt
	s_waitcnt vmcnt(0)
	v_pk_fma_f32 v[54:55], v[54:55], 0.5, v[58:59] op_sel_hi:[1,0,1]
	v_pk_fma_f32 v[52:53], v[52:53], 0.5, v[56:57] op_sel_hi:[1,0,1]
	global_store_dwordx4 v[68:69], v[52:55], off offset:512 nt
	global_load_dwordx4 v[52:55], v[74:75], off offset:576 nt
	v_lshl_add_u64 v[56:57], v[140:141], 0, s[20:21]
	v_lshl_add_u64 v[58:59], s[6:7], 0, v[56:57]
	s_waitcnt vmcnt(0)
	v_pk_fma_f32 v[42:43], v[42:43], 0.5, v[54:55] op_sel_hi:[1,0,1]
	v_pk_fma_f32 v[40:41], v[40:41], 0.5, v[52:53] op_sel_hi:[1,0,1]
	global_store_dwordx4 v[68:69], v[40:43], off offset:576 nt
	global_load_dwordx4 v[40:43], v[58:59], off nt
	v_lshl_add_u64 v[52:53], s[8:9], 0, v[56:57]
	s_waitcnt vmcnt(0)
	v_pk_fma_f32 v[42:43], v[50:51], 0.5, v[42:43] op_sel_hi:[1,0,1]
	v_pk_fma_f32 v[40:41], v[48:49], 0.5, v[40:41] op_sel_hi:[1,0,1]
	global_store_dwordx4 v[52:53], v[40:43], off nt
	global_load_dwordx4 v[40:43], v[58:59], off offset:64 nt
	s_waitcnt vmcnt(0)
	v_pk_fma_f32 v[42:43], v[46:47], 0.5, v[42:43] op_sel_hi:[1,0,1]
	v_pk_fma_f32 v[40:41], v[44:45], 0.5, v[40:41] op_sel_hi:[1,0,1]
	global_store_dwordx4 v[52:53], v[40:43], off offset:64 nt
	global_load_dwordx4 v[40:43], v[58:59], off offset:512 nt
	s_waitcnt vmcnt(0)
	v_pk_fma_f32 v[38:39], v[38:39], 0.5, v[42:43] op_sel_hi:[1,0,1]
	v_pk_fma_f32 v[36:37], v[36:37], 0.5, v[40:41] op_sel_hi:[1,0,1]
	global_store_dwordx4 v[52:53], v[36:39], off offset:512 nt
	global_load_dwordx4 v[36:39], v[58:59], off offset:576 nt
	v_lshl_add_u64 v[40:41], v[140:141], 0, s[22:23]
	v_lshl_add_u64 v[42:43], s[6:7], 0, v[40:41]
	s_waitcnt vmcnt(0)
	v_pk_fma_f32 v[26:27], v[26:27], 0.5, v[38:39] op_sel_hi:[1,0,1]
	v_pk_fma_f32 v[24:25], v[24:25], 0.5, v[36:37] op_sel_hi:[1,0,1]
	global_store_dwordx4 v[52:53], v[24:27], off offset:576 nt
	global_load_dwordx4 v[24:27], v[42:43], off nt
	v_lshl_add_u64 v[36:37], s[8:9], 0, v[40:41]
	s_waitcnt vmcnt(0)
	v_pk_fma_f32 v[26:27], v[34:35], 0.5, v[26:27] op_sel_hi:[1,0,1]
	v_pk_fma_f32 v[24:25], v[32:33], 0.5, v[24:25] op_sel_hi:[1,0,1]
	global_store_dwordx4 v[36:37], v[24:27], off nt
	global_load_dwordx4 v[24:27], v[42:43], off offset:64 nt
	s_waitcnt vmcnt(0)
	v_pk_fma_f32 v[26:27], v[30:31], 0.5, v[26:27] op_sel_hi:[1,0,1]
	v_pk_fma_f32 v[24:25], v[28:29], 0.5, v[24:25] op_sel_hi:[1,0,1]
	global_store_dwordx4 v[36:37], v[24:27], off offset:64 nt
	global_load_dwordx4 v[24:27], v[42:43], off offset:512 nt
	s_waitcnt vmcnt(0)
	v_pk_fma_f32 v[22:23], v[22:23], 0.5, v[26:27] op_sel_hi:[1,0,1]
	v_pk_fma_f32 v[20:21], v[20:21], 0.5, v[24:25] op_sel_hi:[1,0,1]
	global_store_dwordx4 v[36:37], v[20:23], off offset:512 nt
	global_load_dwordx4 v[20:23], v[42:43], off offset:576 nt
	v_lshl_add_u64 v[24:25], v[140:141], 0, s[10:11]
	v_lshl_add_u64 v[26:27], s[6:7], 0, v[24:25]
	s_waitcnt vmcnt(0)
	v_pk_fma_f32 v[10:11], v[10:11], 0.5, v[22:23] op_sel_hi:[1,0,1]
	v_pk_fma_f32 v[8:9], v[8:9], 0.5, v[20:21] op_sel_hi:[1,0,1]
	global_store_dwordx4 v[36:37], v[8:11], off offset:576 nt
	global_load_dwordx4 v[8:11], v[26:27], off nt
	v_lshl_add_u64 v[20:21], s[8:9], 0, v[24:25]
	s_waitcnt vmcnt(0)
	v_pk_fma_f32 v[10:11], v[18:19], 0.5, v[10:11] op_sel_hi:[1,0,1]
	v_pk_fma_f32 v[8:9], v[16:17], 0.5, v[8:9] op_sel_hi:[1,0,1]
	global_store_dwordx4 v[20:21], v[8:11], off nt
	global_load_dwordx4 v[8:11], v[26:27], off offset:64 nt
	s_waitcnt vmcnt(0)
	v_pk_fma_f32 v[10:11], v[14:15], 0.5, v[10:11] op_sel_hi:[1,0,1]
	v_pk_fma_f32 v[8:9], v[12:13], 0.5, v[8:9] op_sel_hi:[1,0,1]
	global_store_dwordx4 v[20:21], v[8:11], off offset:64 nt
	global_load_dwordx4 v[8:11], v[26:27], off offset:512 nt
	s_waitcnt vmcnt(0)
	v_pk_fma_f32 v[6:7], v[6:7], 0.5, v[10:11] op_sel_hi:[1,0,1]
	v_pk_fma_f32 v[4:5], v[4:5], 0.5, v[8:9] op_sel_hi:[1,0,1]
	global_store_dwordx4 v[20:21], v[4:7], off offset:512 nt
	global_load_dwordx4 v[4:7], v[26:27], off offset:576 nt
	s_waitcnt vmcnt(0)
	v_pk_fma_f32 v[2:3], v[2:3], 0.5, v[6:7] op_sel_hi:[1,0,1]
	v_pk_fma_f32 v[0:1], v[0:1], 0.5, v[4:5] op_sel_hi:[1,0,1]
	global_store_dwordx4 v[20:21], v[0:3], off offset:576 nt
	s_cbranch_vccnz .LBB0_235
	s_andn2_b64 vcc, exec, s[12:13]
	s_cbranch_vccnz .LBB0_234
	s_barrier
	s_branch .LBB0_234

.LBB0_914:
	v_lshl_add_u32 v142, s26, 8, v144
	v_lshl_or_b32 v140, s10, 8, v146
	v_ashrrev_i32_e32 v143, 31, v142
	v_ashrrev_i32_e32 v141, 31, v140
	v_lshlrev_b64 v[152:153], 10, v[142:143]
	v_lshl_add_u64 v[156:157], v[152:153], 0, v[140:141]
	v_lshl_add_u64 v[160:161], v[156:157], 2, s[8:9]
	global_load_dwordx4 v[152:155], v[160:161], off nt
	v_lshlrev_b64 v[162:163], 1, v[156:157]
	v_lshl_add_u64 v[156:157], s[76:77], 0, v[162:163]
	v_xor_b32_e32 v151, 32, v150
	s_lshl_b32 s26, s10, 2
	s_ashr_i32 s27, s26, 31
	s_waitcnt vmcnt(0)
	v_pk_add_f32 v[126:127], v[126:127], v[154:155]
	v_pk_add_f32 v[124:125], v[124:125], v[152:153]
	global_store_dwordx4 v[160:161], v[124:127], off nt
	v_cvt_pk_bf16_f32 v152, v124, v125
	v_cvt_pk_bf16_f32 v153, v126, v127
	global_store_dwordx2 v[156:157], v[152:153], off
	global_load_dwordx4 v[152:155], v[160:161], off offset:64 nt
	v_or_b32_e32 v156, 32, v162
	v_mov_b32_e32 v157, v163
	v_lshl_add_u64 v[156:157], s[76:77], 0, v[156:157]
	s_waitcnt vmcnt(0)
	v_pk_add_f32 v[122:123], v[122:123], v[154:155]
	v_pk_add_f32 v[120:121], v[120:121], v[152:153]
	global_store_dwordx4 v[160:161], v[120:123], off offset:64 nt
	v_cvt_pk_bf16_f32 v152, v120, v121
	v_cvt_pk_bf16_f32 v153, v122, v123
	global_store_dwordx2 v[156:157], v[152:153], off
	global_load_dwordx4 v[152:155], v[160:161], off offset:512 nt
	v_or_b32_e32 v156, 0x100, v162
	v_mov_b32_e32 v157, v163
	v_lshl_add_u64 v[156:157], s[76:77], 0, v[156:157]
	v_or_b32_e32 v162, 0x120, v162
	s_waitcnt vmcnt(0)
	v_pk_add_f32 v[154:155], v[118:119], v[154:155]
	v_pk_add_f32 v[152:153], v[116:117], v[152:153]
	global_store_dwordx4 v[160:161], v[152:155], off offset:512 nt
	v_cvt_pk_bf16_f32 v116, v152, v153
	v_cvt_pk_bf16_f32 v117, v154, v155
	global_store_dwordx2 v[156:157], v[116:117], off
	global_load_dwordx4 v[156:159], v[160:161], off offset:576 nt
	v_mul_f32_e32 v118, v125, v125
	v_mul_f32_e32 v119, v127, v127
	v_fmac_f32_e32 v118, v124, v124
	v_fmac_f32_e32 v119, v126, v126
	v_add_f32_e32 v118, v118, v119
	v_mul_f32_e32 v119, v121, v121
	v_mul_f32_e32 v121, v123, v123
	v_fmac_f32_e32 v119, v120, v120
	v_fmac_f32_e32 v121, v122, v122
	v_add_f32_e32 v119, v119, v121
	v_add_f32_e32 v118, v118, v119
	v_mul_f32_e32 v119, v153, v153
	v_mul_f32_e32 v120, v155, v155
	v_fmac_f32_e32 v119, v152, v152
	v_fmac_f32_e32 v120, v154, v154
	v_add_f32_e32 v119, v119, v120
	v_and_b32_e32 v117, 64, v150
	v_add_f32_e32 v122, v118, v119
	v_xor_b32_e32 v116, 16, v150
	v_add_u32_e32 v117, 64, v117
	v_cmp_lt_i32_e32 vcc, v116, v117
	s_waitcnt vmcnt(0)
	v_pk_add_f32 v[120:121], v[114:115], v[158:159]
	v_pk_add_f32 v[118:119], v[112:113], v[156:157]
	v_mul_f32_e32 v113, v121, v121
	v_mul_f32_e32 v112, v119, v119
	v_fmac_f32_e32 v112, v118, v118
	v_fmac_f32_e32 v113, v120, v120
	v_cndmask_b32_e32 v116, v150, v116, vcc
	v_add_f32_e32 v112, v112, v113
	v_lshlrev_b32_e32 v116, 2, v116
	v_add_f32_e32 v112, v122, v112
	ds_bpermute_b32 v113, v116, v112
	v_cmp_lt_i32_e32 vcc, v151, v117
	global_store_dwordx4 v[160:161], v[118:121], off offset:576 nt
	s_waitcnt lgkmcnt(0)
	v_add_f32_e32 v112, v112, v113
	v_cndmask_b32_e32 v114, v150, v151, vcc
	v_lshlrev_b32_e32 v114, 2, v114
	ds_bpermute_b32 v113, v114, v112
	v_cvt_pk_bf16_f32 v118, v118, v119
	v_cvt_pk_bf16_f32 v119, v120, v121
	v_lshl_add_u64 v[120:121], s[76:77], 0, v[162:163]
	global_store_dwordx2 v[120:121], v[118:119], off
	s_and_saveexec_b64 s[28:29], s[2:3]
	s_cbranch_execz .LBB0_916
	v_lshlrev_b64 v[118:119], 6, v[142:143]
	v_lshl_add_u64 v[118:119], s[74:75], 0, v[118:119]
	v_lshl_add_u64 v[118:119], s[26:27], 2, v[118:119]
	s_lshl_b32 s10, s45, 2
	v_lshl_add_u64 v[118:119], v[118:119], 0, s[10:11]
	s_waitcnt lgkmcnt(0)
	v_add_f32_e32 v112, v112, v113
	global_store_dword v[118:119], v112, off
.LBB0_916:
	s_or_b64 exec, exec, s[28:29]
	v_or_b32_e32 v112, 16, v142
	s_waitcnt lgkmcnt(0)
	v_ashrrev_i32_e32 v113, 31, v112
	v_lshlrev_b64 v[118:119], 10, v[112:113]
	v_lshl_add_u64 v[122:123], v[118:119], 0, v[140:141]
	v_lshl_add_u64 v[124:125], v[122:123], 2, s[8:9]
	global_load_dwordx4 v[118:121], v[124:125], off nt
	v_lshlrev_b64 v[122:123], 1, v[122:123]
	v_lshl_add_u64 v[126:127], s[76:77], 0, v[122:123]
	s_waitcnt vmcnt(0)
	v_pk_add_f32 v[110:111], v[110:111], v[120:121]
	v_pk_add_f32 v[108:109], v[108:109], v[118:119]
	global_store_dwordx4 v[124:125], v[108:111], off nt
	v_cvt_pk_bf16_f32 v118, v108, v109
	v_cvt_pk_bf16_f32 v119, v110, v111
	global_store_dwordx2 v[126:127], v[118:119], off
	global_load_dwordx4 v[118:121], v[124:125], off offset:64 nt
	v_or_b32_e32 v126, 32, v122
	v_mov_b32_e32 v127, v123
	v_lshl_add_u64 v[126:127], s[76:77], 0, v[126:127]
	v_mul_f32_e32 v109, v109, v109
	v_mul_f32_e32 v111, v111, v111
	v_fmac_f32_e32 v109, v108, v108
	v_fmac_f32_e32 v111, v110, v110
	v_add_f32_e32 v108, v109, v111
	s_waitcnt vmcnt(0)
	v_pk_add_f32 v[106:107], v[106:107], v[120:121]
	v_pk_add_f32 v[104:105], v[104:105], v[118:119]
	global_store_dwordx4 v[124:125], v[104:107], off offset:64 nt
	v_cvt_pk_bf16_f32 v118, v104, v105
	v_cvt_pk_bf16_f32 v119, v106, v107
	global_store_dwordx2 v[126:127], v[118:119], off
	global_load_dwordx4 v[118:121], v[124:125], off offset:512 nt
	v_or_b32_e32 v126, 0x100, v122
	v_mov_b32_e32 v127, v123
	v_lshl_add_u64 v[126:127], s[76:77], 0, v[126:127]
	v_mul_f32_e32 v105, v105, v105
	v_mul_f32_e32 v107, v107, v107
	v_fmac_f32_e32 v105, v104, v104
	v_fmac_f32_e32 v107, v106, v106
	v_add_f32_e32 v104, v105, v107
	v_add_f32_e32 v104, v108, v104
	v_or_b32_e32 v122, 0x120, v122
	s_waitcnt vmcnt(0)
	v_pk_add_f32 v[102:103], v[102:103], v[120:121]
	v_pk_add_f32 v[100:101], v[100:101], v[118:119]
	global_store_dwordx4 v[124:125], v[100:103], off offset:512 nt
	v_cvt_pk_bf16_f32 v118, v100, v101
	v_cvt_pk_bf16_f32 v119, v102, v103
	global_store_dwordx2 v[126:127], v[118:119], off
	global_load_dwordx4 v[118:121], v[124:125], off offset:576 nt
	v_mul_f32_e32 v101, v101, v101
	v_mul_f32_e32 v103, v103, v103
	v_fmac_f32_e32 v101, v100, v100
	v_fmac_f32_e32 v103, v102, v102
	v_add_f32_e32 v100, v101, v103
	v_add_f32_e32 v100, v104, v100
	s_waitcnt vmcnt(0)
	v_pk_add_f32 v[98:99], v[98:99], v[120:121]
	v_pk_add_f32 v[96:97], v[96:97], v[118:119]
	v_mul_f32_e32 v102, v99, v99
	v_mul_f32_e32 v101, v97, v97
	v_fmac_f32_e32 v101, v96, v96
	v_fmac_f32_e32 v102, v98, v98
	v_add_f32_e32 v101, v101, v102
	v_add_f32_e32 v101, v100, v101
	ds_bpermute_b32 v102, v116, v101
	global_store_dwordx4 v[124:125], v[96:99], off offset:576 nt
	v_cvt_pk_bf16_f32 v100, v96, v97
	s_waitcnt lgkmcnt(0)
	s_nop 0
	v_add_f32_e32 v96, v101, v102
	ds_bpermute_b32 v97, v114, v96
	v_cvt_pk_bf16_f32 v101, v98, v99
	v_lshl_add_u64 v[98:99], s[76:77], 0, v[122:123]
	global_store_dwordx2 v[98:99], v[100:101], off
	s_and_saveexec_b64 s[28:29], s[2:3]
	s_cbranch_execz .LBB0_918
	v_lshlrev_b64 v[98:99], 6, v[112:113]
	v_lshl_add_u64 v[98:99], s[74:75], 0, v[98:99]
	v_lshl_add_u64 v[98:99], s[26:27], 2, v[98:99]
	s_lshl_b32 s10, s45, 2
	v_lshl_add_u64 v[98:99], v[98:99], 0, s[10:11]
	s_waitcnt lgkmcnt(0)
	v_add_f32_e32 v96, v96, v97
	global_store_dword v[98:99], v96, off
.LBB0_918:
	s_or_b64 exec, exec, s[28:29]
	v_or_b32_e32 v96, 32, v142
	s_waitcnt lgkmcnt(0)
	v_ashrrev_i32_e32 v97, 31, v96
	v_lshlrev_b64 v[98:99], 10, v[96:97]
	v_lshl_add_u64 v[102:103], v[98:99], 0, v[140:141]
	v_lshl_add_u64 v[104:105], v[102:103], 2, s[8:9]
	global_load_dwordx4 v[98:101], v[104:105], off nt
	v_lshlrev_b64 v[102:103], 1, v[102:103]
	v_lshl_add_u64 v[106:107], s[76:77], 0, v[102:103]
	s_waitcnt vmcnt(0)
	v_pk_add_f32 v[94:95], v[94:95], v[100:101]
	v_pk_add_f32 v[92:93], v[92:93], v[98:99]
	global_store_dwordx4 v[104:105], v[92:95], off nt
	v_cvt_pk_bf16_f32 v98, v92, v93
	v_cvt_pk_bf16_f32 v99, v94, v95
	global_store_dwordx2 v[106:107], v[98:99], off
	global_load_dwordx4 v[98:101], v[104:105], off offset:64 nt
	v_or_b32_e32 v106, 32, v102
	v_mov_b32_e32 v107, v103
	v_lshl_add_u64 v[106:107], s[76:77], 0, v[106:107]
	v_mul_f32_e32 v93, v93, v93
	v_mul_f32_e32 v95, v95, v95
	v_fmac_f32_e32 v93, v92, v92
	v_fmac_f32_e32 v95, v94, v94
	v_add_f32_e32 v92, v93, v95
	s_waitcnt vmcnt(0)
	v_pk_add_f32 v[90:91], v[90:91], v[100:101]
	v_pk_add_f32 v[88:89], v[88:89], v[98:99]
	global_store_dwordx4 v[104:105], v[88:91], off offset:64 nt
	v_cvt_pk_bf16_f32 v98, v88, v89
	v_cvt_pk_bf16_f32 v99, v90, v91
	global_store_dwordx2 v[106:107], v[98:99], off
	global_load_dwordx4 v[98:101], v[104:105], off offset:512 nt
	v_or_b32_e32 v106, 0x100, v102
	v_mov_b32_e32 v107, v103
	v_lshl_add_u64 v[106:107], s[76:77], 0, v[106:107]
	v_mul_f32_e32 v89, v89, v89
	v_mul_f32_e32 v91, v91, v91
	v_fmac_f32_e32 v89, v88, v88
	v_fmac_f32_e32 v91, v90, v90
	v_add_f32_e32 v88, v89, v91
	v_add_f32_e32 v88, v92, v88
	v_or_b32_e32 v102, 0x120, v102
	s_waitcnt vmcnt(0)
	v_pk_add_f32 v[86:87], v[86:87], v[100:101]
	v_pk_add_f32 v[84:85], v[84:85], v[98:99]
	global_store_dwordx4 v[104:105], v[84:87], off offset:512 nt
	v_cvt_pk_bf16_f32 v98, v84, v85
	v_cvt_pk_bf16_f32 v99, v86, v87
	global_store_dwordx2 v[106:107], v[98:99], off
	global_load_dwordx4 v[98:101], v[104:105], off offset:576 nt
	v_mul_f32_e32 v85, v85, v85
	v_mul_f32_e32 v87, v87, v87
	v_fmac_f32_e32 v85, v84, v84
	v_fmac_f32_e32 v87, v86, v86
	v_add_f32_e32 v84, v85, v87
	v_add_f32_e32 v84, v88, v84
	s_waitcnt vmcnt(0)
	v_pk_add_f32 v[82:83], v[82:83], v[100:101]
	v_pk_add_f32 v[80:81], v[80:81], v[98:99]
	v_mul_f32_e32 v86, v83, v83
	v_mul_f32_e32 v85, v81, v81
	v_fmac_f32_e32 v85, v80, v80
	v_fmac_f32_e32 v86, v82, v82
	v_add_f32_e32 v85, v85, v86
	v_add_f32_e32 v85, v84, v85
	ds_bpermute_b32 v86, v116, v85
	global_store_dwordx4 v[104:105], v[80:83], off offset:576 nt
	v_cvt_pk_bf16_f32 v84, v80, v81
	s_waitcnt lgkmcnt(0)
	s_nop 0
	v_add_f32_e32 v80, v85, v86
	ds_bpermute_b32 v81, v114, v80
	v_cvt_pk_bf16_f32 v85, v82, v83
	v_lshl_add_u64 v[82:83], s[76:77], 0, v[102:103]
	global_store_dwordx2 v[82:83], v[84:85], off
	s_and_saveexec_b64 s[28:29], s[2:3]
	s_cbranch_execz .LBB0_920
	v_lshlrev_b64 v[82:83], 6, v[96:97]
	v_lshl_add_u64 v[82:83], s[74:75], 0, v[82:83]
	v_lshl_add_u64 v[82:83], s[26:27], 2, v[82:83]
	s_lshl_b32 s10, s45, 2
	v_lshl_add_u64 v[82:83], v[82:83], 0, s[10:11]
	s_waitcnt lgkmcnt(0)
	v_add_f32_e32 v80, v80, v81
	global_store_dword v[82:83], v80, off
.LBB0_920:
	s_or_b64 exec, exec, s[28:29]
	v_or_b32_e32 v80, 48, v142
	s_waitcnt lgkmcnt(0)
	v_ashrrev_i32_e32 v81, 31, v80
	v_lshlrev_b64 v[82:83], 10, v[80:81]
	v_lshl_add_u64 v[86:87], v[82:83], 0, v[140:141]
	v_lshl_add_u64 v[88:89], v[86:87], 2, s[8:9]
	global_load_dwordx4 v[82:85], v[88:89], off nt
	v_lshlrev_b64 v[86:87], 1, v[86:87]
	v_lshl_add_u64 v[90:91], s[76:77], 0, v[86:87]
	s_waitcnt vmcnt(0)
	v_pk_add_f32 v[78:79], v[78:79], v[84:85]
	v_pk_add_f32 v[76:77], v[76:77], v[82:83]
	global_store_dwordx4 v[88:89], v[76:79], off nt
	v_cvt_pk_bf16_f32 v82, v76, v77
	v_cvt_pk_bf16_f32 v83, v78, v79
	global_store_dwordx2 v[90:91], v[82:83], off
	global_load_dwordx4 v[82:85], v[88:89], off offset:64 nt
	v_or_b32_e32 v90, 32, v86
	v_mov_b32_e32 v91, v87
	v_lshl_add_u64 v[90:91], s[76:77], 0, v[90:91]
	v_mul_f32_e32 v77, v77, v77
	v_mul_f32_e32 v79, v79, v79
	v_fmac_f32_e32 v77, v76, v76
	v_fmac_f32_e32 v79, v78, v78
	v_add_f32_e32 v76, v77, v79
	s_waitcnt vmcnt(0)
	v_pk_add_f32 v[74:75], v[74:75], v[84:85]
	v_pk_add_f32 v[72:73], v[72:73], v[82:83]
	global_store_dwordx4 v[88:89], v[72:75], off offset:64 nt
	v_cvt_pk_bf16_f32 v82, v72, v73
	v_cvt_pk_bf16_f32 v83, v74, v75
	global_store_dwordx2 v[90:91], v[82:83], off
	global_load_dwordx4 v[82:85], v[88:89], off offset:512 nt
	v_or_b32_e32 v90, 0x100, v86
	v_mov_b32_e32 v91, v87
	v_lshl_add_u64 v[90:91], s[76:77], 0, v[90:91]
	v_mul_f32_e32 v73, v73, v73
	v_mul_f32_e32 v75, v75, v75
	v_fmac_f32_e32 v73, v72, v72
	v_fmac_f32_e32 v75, v74, v74
	v_add_f32_e32 v72, v73, v75
	v_add_f32_e32 v72, v76, v72
	v_or_b32_e32 v86, 0x120, v86
	s_waitcnt vmcnt(0)
	v_pk_add_f32 v[70:71], v[70:71], v[84:85]
	v_pk_add_f32 v[68:69], v[68:69], v[82:83]
	global_store_dwordx4 v[88:89], v[68:71], off offset:512 nt
	v_cvt_pk_bf16_f32 v82, v68, v69
	v_cvt_pk_bf16_f32 v83, v70, v71
	global_store_dwordx2 v[90:91], v[82:83], off
	global_load_dwordx4 v[82:85], v[88:89], off offset:576 nt
	v_mul_f32_e32 v69, v69, v69
	v_mul_f32_e32 v71, v71, v71
	v_fmac_f32_e32 v69, v68, v68
	v_fmac_f32_e32 v71, v70, v70
	v_add_f32_e32 v68, v69, v71
	v_add_f32_e32 v68, v72, v68
	s_waitcnt vmcnt(0)
	v_pk_add_f32 v[66:67], v[66:67], v[84:85]
	v_pk_add_f32 v[64:65], v[64:65], v[82:83]
	v_mul_f32_e32 v70, v67, v67
	v_mul_f32_e32 v69, v65, v65
	v_fmac_f32_e32 v69, v64, v64
	v_fmac_f32_e32 v70, v66, v66
	v_add_f32_e32 v69, v69, v70
	v_add_f32_e32 v69, v68, v69
	ds_bpermute_b32 v70, v116, v69
	global_store_dwordx4 v[88:89], v[64:67], off offset:576 nt
	v_cvt_pk_bf16_f32 v68, v64, v65
	s_waitcnt lgkmcnt(0)
	s_nop 0
	v_add_f32_e32 v64, v69, v70
	ds_bpermute_b32 v65, v114, v64
	v_cvt_pk_bf16_f32 v69, v66, v67
	v_lshl_add_u64 v[66:67], s[76:77], 0, v[86:87]
	global_store_dwordx2 v[66:67], v[68:69], off
	s_and_saveexec_b64 s[28:29], s[2:3]
	s_cbranch_execz .LBB0_922
	v_lshlrev_b64 v[66:67], 6, v[80:81]
	v_lshl_add_u64 v[66:67], s[74:75], 0, v[66:67]
	v_lshl_add_u64 v[66:67], s[26:27], 2, v[66:67]
	s_lshl_b32 s10, s45, 2
	v_lshl_add_u64 v[66:67], v[66:67], 0, s[10:11]
	s_waitcnt lgkmcnt(0)
	v_add_f32_e32 v64, v64, v65
	global_store_dword v[66:67], v64, off
.LBB0_922:
	s_or_b64 exec, exec, s[28:29]
	v_add_u32_e32 v64, 0x80, v142
	s_waitcnt lgkmcnt(0)
	v_ashrrev_i32_e32 v65, 31, v64
	v_lshlrev_b64 v[66:67], 10, v[64:65]
	v_lshl_add_u64 v[70:71], v[66:67], 0, v[140:141]
	v_lshl_add_u64 v[72:73], v[70:71], 2, s[8:9]
	global_load_dwordx4 v[66:69], v[72:73], off nt
	v_lshlrev_b64 v[70:71], 1, v[70:71]
	v_lshl_add_u64 v[74:75], s[76:77], 0, v[70:71]
	s_waitcnt vmcnt(0)
	v_pk_add_f32 v[62:63], v[62:63], v[68:69]
	v_pk_add_f32 v[60:61], v[60:61], v[66:67]
	global_store_dwordx4 v[72:73], v[60:63], off nt
	v_cvt_pk_bf16_f32 v66, v60, v61
	v_cvt_pk_bf16_f32 v67, v62, v63
	global_store_dwordx2 v[74:75], v[66:67], off
	global_load_dwordx4 v[66:69], v[72:73], off offset:64 nt
	v_or_b32_e32 v74, 32, v70
	v_mov_b32_e32 v75, v71
	v_lshl_add_u64 v[74:75], s[76:77], 0, v[74:75]
	v_mul_f32_e32 v61, v61, v61
	v_mul_f32_e32 v63, v63, v63
	v_fmac_f32_e32 v61, v60, v60
	v_fmac_f32_e32 v63, v62, v62
	v_add_f32_e32 v60, v61, v63
	s_waitcnt vmcnt(0)
	v_pk_add_f32 v[58:59], v[58:59], v[68:69]
	v_pk_add_f32 v[56:57], v[56:57], v[66:67]
	global_store_dwordx4 v[72:73], v[56:59], off offset:64 nt
	v_cvt_pk_bf16_f32 v66, v56, v57
	v_cvt_pk_bf16_f32 v67, v58, v59
	global_store_dwordx2 v[74:75], v[66:67], off
	global_load_dwordx4 v[66:69], v[72:73], off offset:512 nt
	v_or_b32_e32 v74, 0x100, v70
	v_mov_b32_e32 v75, v71
	v_lshl_add_u64 v[74:75], s[76:77], 0, v[74:75]
	v_mul_f32_e32 v57, v57, v57
	v_mul_f32_e32 v59, v59, v59
	v_fmac_f32_e32 v57, v56, v56
	v_fmac_f32_e32 v59, v58, v58
	v_add_f32_e32 v56, v57, v59
	v_add_f32_e32 v56, v60, v56
	v_or_b32_e32 v70, 0x120, v70
	s_waitcnt vmcnt(0)
	v_pk_add_f32 v[54:55], v[54:55], v[68:69]
	v_pk_add_f32 v[52:53], v[52:53], v[66:67]
	global_store_dwordx4 v[72:73], v[52:55], off offset:512 nt
	v_cvt_pk_bf16_f32 v66, v52, v53
	v_cvt_pk_bf16_f32 v67, v54, v55
	global_store_dwordx2 v[74:75], v[66:67], off
	global_load_dwordx4 v[66:69], v[72:73], off offset:576 nt
	v_mul_f32_e32 v53, v53, v53
	v_mul_f32_e32 v55, v55, v55
	v_fmac_f32_e32 v53, v52, v52
	v_fmac_f32_e32 v55, v54, v54
	v_add_f32_e32 v52, v53, v55
	v_add_f32_e32 v52, v56, v52
	s_waitcnt vmcnt(0)
	v_pk_add_f32 v[50:51], v[50:51], v[68:69]
	v_pk_add_f32 v[48:49], v[48:49], v[66:67]
	v_mul_f32_e32 v54, v51, v51
	v_mul_f32_e32 v53, v49, v49
	v_fmac_f32_e32 v53, v48, v48
	v_fmac_f32_e32 v54, v50, v50
	v_add_f32_e32 v53, v53, v54
	v_add_f32_e32 v53, v52, v53
	ds_bpermute_b32 v54, v116, v53
	global_store_dwordx4 v[72:73], v[48:51], off offset:576 nt
	v_cvt_pk_bf16_f32 v52, v48, v49
	s_waitcnt lgkmcnt(0)
	s_nop 0
	v_add_f32_e32 v48, v53, v54
	ds_bpermute_b32 v49, v114, v48
	v_cvt_pk_bf16_f32 v53, v50, v51
	v_lshl_add_u64 v[50:51], s[76:77], 0, v[70:71]
	global_store_dwordx2 v[50:51], v[52:53], off
	s_and_saveexec_b64 s[28:29], s[2:3]
	s_cbranch_execz .LBB0_924
	v_lshlrev_b64 v[50:51], 6, v[64:65]
	v_lshl_add_u64 v[50:51], s[74:75], 0, v[50:51]
	v_lshl_add_u64 v[50:51], s[26:27], 2, v[50:51]
	s_lshl_b32 s10, s45, 2
	v_lshl_add_u64 v[50:51], v[50:51], 0, s[10:11]
	s_waitcnt lgkmcnt(0)
	v_add_f32_e32 v48, v48, v49
	global_store_dword v[50:51], v48, off
.LBB0_924:
	s_or_b64 exec, exec, s[28:29]
	v_add_u32_e32 v48, 0x90, v142
	s_waitcnt lgkmcnt(0)
	v_ashrrev_i32_e32 v49, 31, v48
	v_lshlrev_b64 v[50:51], 10, v[48:49]
	v_lshl_add_u64 v[54:55], v[50:51], 0, v[140:141]
	v_lshl_add_u64 v[56:57], v[54:55], 2, s[8:9]
	global_load_dwordx4 v[50:53], v[56:57], off nt
	v_lshlrev_b64 v[54:55], 1, v[54:55]
	v_lshl_add_u64 v[58:59], s[76:77], 0, v[54:55]
	s_waitcnt vmcnt(0)
	v_pk_add_f32 v[46:47], v[46:47], v[52:53]
	v_pk_add_f32 v[44:45], v[44:45], v[50:51]
	global_store_dwordx4 v[56:57], v[44:47], off nt
	v_cvt_pk_bf16_f32 v50, v44, v45
	v_cvt_pk_bf16_f32 v51, v46, v47
	global_store_dwordx2 v[58:59], v[50:51], off
	global_load_dwordx4 v[50:53], v[56:57], off offset:64 nt
	v_or_b32_e32 v58, 32, v54
	v_mov_b32_e32 v59, v55
	v_lshl_add_u64 v[58:59], s[76:77], 0, v[58:59]
	v_mul_f32_e32 v45, v45, v45
	v_mul_f32_e32 v47, v47, v47
	v_fmac_f32_e32 v45, v44, v44
	v_fmac_f32_e32 v47, v46, v46
	v_add_f32_e32 v44, v45, v47
	s_waitcnt vmcnt(0)
	v_pk_add_f32 v[42:43], v[42:43], v[52:53]
	v_pk_add_f32 v[40:41], v[40:41], v[50:51]
	global_store_dwordx4 v[56:57], v[40:43], off offset:64 nt
	v_cvt_pk_bf16_f32 v50, v40, v41
	v_cvt_pk_bf16_f32 v51, v42, v43
	global_store_dwordx2 v[58:59], v[50:51], off
	global_load_dwordx4 v[50:53], v[56:57], off offset:512 nt
	v_or_b32_e32 v58, 0x100, v54
	v_mov_b32_e32 v59, v55
	v_lshl_add_u64 v[58:59], s[76:77], 0, v[58:59]
	v_mul_f32_e32 v41, v41, v41
	v_mul_f32_e32 v43, v43, v43
	v_fmac_f32_e32 v41, v40, v40
	v_fmac_f32_e32 v43, v42, v42
	v_add_f32_e32 v40, v41, v43
	v_add_f32_e32 v40, v44, v40
	v_or_b32_e32 v54, 0x120, v54
	s_waitcnt vmcnt(0)
	v_pk_add_f32 v[38:39], v[38:39], v[52:53]
	v_pk_add_f32 v[36:37], v[36:37], v[50:51]
	global_store_dwordx4 v[56:57], v[36:39], off offset:512 nt
	v_cvt_pk_bf16_f32 v50, v36, v37
	v_cvt_pk_bf16_f32 v51, v38, v39
	global_store_dwordx2 v[58:59], v[50:51], off
	global_load_dwordx4 v[50:53], v[56:57], off offset:576 nt
	v_mul_f32_e32 v37, v37, v37
	v_mul_f32_e32 v39, v39, v39
	v_fmac_f32_e32 v37, v36, v36
	v_fmac_f32_e32 v39, v38, v38
	v_add_f32_e32 v36, v37, v39
	v_add_f32_e32 v36, v40, v36
	s_waitcnt vmcnt(0)
	v_pk_add_f32 v[34:35], v[34:35], v[52:53]
	v_pk_add_f32 v[32:33], v[32:33], v[50:51]
	v_mul_f32_e32 v38, v35, v35
	v_mul_f32_e32 v37, v33, v33
	v_fmac_f32_e32 v37, v32, v32
	v_fmac_f32_e32 v38, v34, v34
	v_add_f32_e32 v37, v37, v38
	v_add_f32_e32 v37, v36, v37
	ds_bpermute_b32 v38, v116, v37
	global_store_dwordx4 v[56:57], v[32:35], off offset:576 nt
	v_cvt_pk_bf16_f32 v36, v32, v33
	s_waitcnt lgkmcnt(0)
	s_nop 0
	v_add_f32_e32 v32, v37, v38
	ds_bpermute_b32 v33, v114, v32
	v_cvt_pk_bf16_f32 v37, v34, v35
	v_lshl_add_u64 v[34:35], s[76:77], 0, v[54:55]
	global_store_dwordx2 v[34:35], v[36:37], off
	s_and_saveexec_b64 s[28:29], s[2:3]
	s_cbranch_execz .LBB0_926
	v_lshlrev_b64 v[34:35], 6, v[48:49]
	v_lshl_add_u64 v[34:35], s[74:75], 0, v[34:35]
	v_lshl_add_u64 v[34:35], s[26:27], 2, v[34:35]
	s_lshl_b32 s10, s45, 2
	v_lshl_add_u64 v[34:35], v[34:35], 0, s[10:11]
	s_waitcnt lgkmcnt(0)
	v_add_f32_e32 v32, v32, v33
	global_store_dword v[34:35], v32, off
.LBB0_926:
	s_or_b64 exec, exec, s[28:29]
	v_add_u32_e32 v32, 0xa0, v142
	s_waitcnt lgkmcnt(0)
	v_ashrrev_i32_e32 v33, 31, v32
	v_lshlrev_b64 v[34:35], 10, v[32:33]
	v_lshl_add_u64 v[38:39], v[34:35], 0, v[140:141]
	v_lshl_add_u64 v[40:41], v[38:39], 2, s[8:9]
	global_load_dwordx4 v[34:37], v[40:41], off nt
	v_lshlrev_b64 v[38:39], 1, v[38:39]
	v_lshl_add_u64 v[42:43], s[76:77], 0, v[38:39]
	s_waitcnt vmcnt(0)
	v_pk_add_f32 v[30:31], v[30:31], v[36:37]
	v_pk_add_f32 v[28:29], v[28:29], v[34:35]
	global_store_dwordx4 v[40:41], v[28:31], off nt
	v_cvt_pk_bf16_f32 v34, v28, v29
	v_cvt_pk_bf16_f32 v35, v30, v31
	global_store_dwordx2 v[42:43], v[34:35], off
	global_load_dwordx4 v[34:37], v[40:41], off offset:64 nt
	v_or_b32_e32 v42, 32, v38
	v_mov_b32_e32 v43, v39
	v_lshl_add_u64 v[42:43], s[76:77], 0, v[42:43]
	v_mul_f32_e32 v29, v29, v29
	v_mul_f32_e32 v31, v31, v31
	v_fmac_f32_e32 v29, v28, v28
	v_fmac_f32_e32 v31, v30, v30
	v_add_f32_e32 v28, v29, v31
	s_waitcnt vmcnt(0)
	v_pk_add_f32 v[26:27], v[26:27], v[36:37]
	v_pk_add_f32 v[24:25], v[24:25], v[34:35]
	global_store_dwordx4 v[40:41], v[24:27], off offset:64 nt
	v_cvt_pk_bf16_f32 v34, v24, v25
	v_cvt_pk_bf16_f32 v35, v26, v27
	global_store_dwordx2 v[42:43], v[34:35], off
	global_load_dwordx4 v[34:37], v[40:41], off offset:512 nt
	v_or_b32_e32 v42, 0x100, v38
	v_mov_b32_e32 v43, v39
	v_lshl_add_u64 v[42:43], s[76:77], 0, v[42:43]
	v_mul_f32_e32 v25, v25, v25
	v_mul_f32_e32 v27, v27, v27
	v_fmac_f32_e32 v25, v24, v24
	v_fmac_f32_e32 v27, v26, v26
	v_add_f32_e32 v24, v25, v27
	v_add_f32_e32 v24, v28, v24
	v_or_b32_e32 v38, 0x120, v38
	s_waitcnt vmcnt(0)
	v_pk_add_f32 v[22:23], v[22:23], v[36:37]
	v_pk_add_f32 v[20:21], v[20:21], v[34:35]
	global_store_dwordx4 v[40:41], v[20:23], off offset:512 nt
	v_cvt_pk_bf16_f32 v34, v20, v21
	v_cvt_pk_bf16_f32 v35, v22, v23
	global_store_dwordx2 v[42:43], v[34:35], off
	global_load_dwordx4 v[34:37], v[40:41], off offset:576 nt
	v_mul_f32_e32 v21, v21, v21
	v_mul_f32_e32 v23, v23, v23
	v_fmac_f32_e32 v21, v20, v20
	v_fmac_f32_e32 v23, v22, v22
	v_add_f32_e32 v20, v21, v23
	v_add_f32_e32 v20, v24, v20
	s_waitcnt vmcnt(0)
	v_pk_add_f32 v[18:19], v[18:19], v[36:37]
	v_pk_add_f32 v[16:17], v[16:17], v[34:35]
	v_mul_f32_e32 v22, v19, v19
	v_mul_f32_e32 v21, v17, v17
	v_fmac_f32_e32 v21, v16, v16
	v_fmac_f32_e32 v22, v18, v18
	v_add_f32_e32 v21, v21, v22
	v_add_f32_e32 v21, v20, v21
	ds_bpermute_b32 v22, v116, v21
	global_store_dwordx4 v[40:41], v[16:19], off offset:576 nt
	v_cvt_pk_bf16_f32 v20, v16, v17
	s_waitcnt lgkmcnt(0)
	s_nop 0
	v_add_f32_e32 v16, v21, v22
	ds_bpermute_b32 v17, v114, v16
	v_cvt_pk_bf16_f32 v21, v18, v19
	v_lshl_add_u64 v[18:19], s[76:77], 0, v[38:39]
	global_store_dwordx2 v[18:19], v[20:21], off
	s_and_saveexec_b64 s[28:29], s[2:3]
	s_cbranch_execz .LBB0_928
	v_lshlrev_b64 v[18:19], 6, v[32:33]
	v_lshl_add_u64 v[18:19], s[74:75], 0, v[18:19]
	v_lshl_add_u64 v[18:19], s[26:27], 2, v[18:19]
	s_lshl_b32 s10, s45, 2
	v_lshl_add_u64 v[18:19], v[18:19], 0, s[10:11]
	s_waitcnt lgkmcnt(0)
	v_add_f32_e32 v16, v16, v17
	global_store_dword v[18:19], v16, off
.LBB0_928:
	s_or_b64 exec, exec, s[28:29]
	v_add_u32_e32 v16, 0xb0, v142
	s_waitcnt lgkmcnt(0)
	v_ashrrev_i32_e32 v17, 31, v16
	v_lshlrev_b64 v[18:19], 10, v[16:17]
	v_lshl_add_u64 v[22:23], v[18:19], 0, v[140:141]
	v_lshl_add_u64 v[24:25], v[22:23], 2, s[8:9]
	global_load_dwordx4 v[18:21], v[24:25], off nt
	v_lshlrev_b64 v[22:23], 1, v[22:23]
	v_lshl_add_u64 v[26:27], s[76:77], 0, v[22:23]
	s_waitcnt vmcnt(0)
	v_pk_add_f32 v[14:15], v[14:15], v[20:21]
	v_pk_add_f32 v[12:13], v[12:13], v[18:19]
	global_store_dwordx4 v[24:25], v[12:15], off nt
	v_cvt_pk_bf16_f32 v18, v12, v13
	v_cvt_pk_bf16_f32 v19, v14, v15
	global_store_dwordx2 v[26:27], v[18:19], off
	global_load_dwordx4 v[18:21], v[24:25], off offset:64 nt
	v_or_b32_e32 v26, 32, v22
	v_mov_b32_e32 v27, v23
	v_lshl_add_u64 v[26:27], s[76:77], 0, v[26:27]
	v_mul_f32_e32 v13, v13, v13
	v_mul_f32_e32 v15, v15, v15
	v_fmac_f32_e32 v13, v12, v12
	v_fmac_f32_e32 v15, v14, v14
	v_add_f32_e32 v12, v13, v15
	s_waitcnt vmcnt(0)
	v_pk_add_f32 v[10:11], v[10:11], v[20:21]
	v_pk_add_f32 v[8:9], v[8:9], v[18:19]
	global_store_dwordx4 v[24:25], v[8:11], off offset:64 nt
	v_cvt_pk_bf16_f32 v18, v8, v9
	v_cvt_pk_bf16_f32 v19, v10, v11
	global_store_dwordx2 v[26:27], v[18:19], off
	global_load_dwordx4 v[18:21], v[24:25], off offset:512 nt
	v_or_b32_e32 v26, 0x100, v22
	v_mov_b32_e32 v27, v23
	v_lshl_add_u64 v[26:27], s[76:77], 0, v[26:27]
	v_mul_f32_e32 v9, v9, v9
	v_mul_f32_e32 v11, v11, v11
	v_fmac_f32_e32 v9, v8, v8
	v_fmac_f32_e32 v11, v10, v10
	v_add_f32_e32 v8, v9, v11
	v_add_f32_e32 v8, v12, v8
	v_or_b32_e32 v22, 0x120, v22
	s_waitcnt vmcnt(0)
	v_pk_add_f32 v[6:7], v[6:7], v[20:21]
	v_pk_add_f32 v[4:5], v[4:5], v[18:19]
	global_store_dwordx4 v[24:25], v[4:7], off offset:512 nt
	v_cvt_pk_bf16_f32 v18, v4, v5
	v_cvt_pk_bf16_f32 v19, v6, v7
	global_store_dwordx2 v[26:27], v[18:19], off
	global_load_dwordx4 v[18:21], v[24:25], off offset:576 nt
	v_mul_f32_e32 v5, v5, v5
	v_mul_f32_e32 v7, v7, v7
	v_fmac_f32_e32 v5, v4, v4
	v_fmac_f32_e32 v7, v6, v6
	v_add_f32_e32 v4, v5, v7
	v_add_f32_e32 v4, v8, v4
	s_waitcnt vmcnt(0)
	v_pk_add_f32 v[2:3], v[2:3], v[20:21]
	v_pk_add_f32 v[0:1], v[0:1], v[18:19]
	v_mul_f32_e32 v6, v3, v3
	v_mul_f32_e32 v5, v1, v1
	v_fmac_f32_e32 v5, v0, v0
	v_fmac_f32_e32 v6, v2, v2
	v_add_f32_e32 v5, v5, v6
	v_add_f32_e32 v5, v4, v5
	ds_bpermute_b32 v6, v116, v5
	global_store_dwordx4 v[24:25], v[0:3], off offset:576 nt
	v_cvt_pk_bf16_f32 v4, v0, v1
	s_waitcnt lgkmcnt(0)
	s_nop 0
	v_add_f32_e32 v0, v5, v6
	ds_bpermute_b32 v1, v114, v0
	v_cvt_pk_bf16_f32 v5, v2, v3
	v_lshl_add_u64 v[2:3], s[76:77], 0, v[22:23]
	global_store_dwordx2 v[2:3], v[4:5], off
	s_and_saveexec_b64 s[28:29], s[2:3]
	s_cbranch_execz .LBB0_930
	v_lshlrev_b64 v[2:3], 6, v[16:17]
	v_lshl_add_u64 v[2:3], s[74:75], 0, v[2:3]
	v_lshl_add_u64 v[2:3], s[26:27], 2, v[2:3]
	s_lshl_b32 s10, s45, 2
	v_lshl_add_u64 v[2:3], v[2:3], 0, s[10:11]
	s_waitcnt lgkmcnt(0)
	v_add_f32_e32 v0, v0, v1
	global_store_dword v[2:3], v0, off

.LBB0_1068:
	v_lshl_add_u32 v142, s49, 8, v144
	v_lshl_or_b32 v140, s12, 8, v146
	v_ashrrev_i32_e32 v143, 31, v142
	v_ashrrev_i32_e32 v141, 31, v140
	v_lshlrev_b64 v[152:153], 10, v[142:143]
	v_lshl_add_u64 v[156:157], v[152:153], 0, v[140:141]
	v_lshl_add_u64 v[160:161], v[156:157], 2, s[10:11]
	global_load_dwordx4 v[152:155], v[160:161], off nt
	v_lshlrev_b64 v[162:163], 1, v[156:157]
	v_lshl_add_u64 v[156:157], s[76:77], 0, v[162:163]
	v_xor_b32_e32 v151, 32, v150
	s_lshl_b32 s22, s12, 2
	s_ashr_i32 s23, s22, 31
	s_waitcnt vmcnt(0)
	v_pk_fma_f32 v[126:127], v[126:127], 0.5, v[154:155] op_sel_hi:[1,0,1]
	v_pk_fma_f32 v[124:125], v[124:125], 0.5, v[152:153] op_sel_hi:[1,0,1]
	global_store_dwordx4 v[160:161], v[124:127], off nt
	v_cvt_pk_bf16_f32 v152, v124, v125
	v_cvt_pk_bf16_f32 v153, v126, v127
	global_store_dwordx2 v[156:157], v[152:153], off
	global_load_dwordx4 v[152:155], v[160:161], off offset:64 nt
	v_or_b32_e32 v156, 32, v162
	v_mov_b32_e32 v157, v163
	v_lshl_add_u64 v[156:157], s[76:77], 0, v[156:157]
	s_waitcnt vmcnt(0)
	v_pk_fma_f32 v[122:123], v[122:123], 0.5, v[154:155] op_sel_hi:[1,0,1]
	v_pk_fma_f32 v[120:121], v[120:121], 0.5, v[152:153] op_sel_hi:[1,0,1]
	global_store_dwordx4 v[160:161], v[120:123], off offset:64 nt
	v_cvt_pk_bf16_f32 v152, v120, v121
	v_cvt_pk_bf16_f32 v153, v122, v123
	global_store_dwordx2 v[156:157], v[152:153], off
	global_load_dwordx4 v[152:155], v[160:161], off offset:512 nt
	v_or_b32_e32 v156, 0x100, v162
	v_mov_b32_e32 v157, v163
	v_lshl_add_u64 v[156:157], s[76:77], 0, v[156:157]
	v_or_b32_e32 v162, 0x120, v162
	s_waitcnt vmcnt(0)
	v_pk_fma_f32 v[154:155], v[118:119], 0.5, v[154:155] op_sel_hi:[1,0,1]
	v_pk_fma_f32 v[152:153], v[116:117], 0.5, v[152:153] op_sel_hi:[1,0,1]
	global_store_dwordx4 v[160:161], v[152:155], off offset:512 nt
	v_cvt_pk_bf16_f32 v116, v152, v153
	v_cvt_pk_bf16_f32 v117, v154, v155
	global_store_dwordx2 v[156:157], v[116:117], off
	global_load_dwordx4 v[156:159], v[160:161], off offset:576 nt
	v_mul_f32_e32 v118, v125, v125
	v_mul_f32_e32 v119, v127, v127
	v_fmac_f32_e32 v118, v124, v124
	v_fmac_f32_e32 v119, v126, v126
	v_add_f32_e32 v118, v118, v119
	v_mul_f32_e32 v119, v121, v121
	v_mul_f32_e32 v121, v123, v123
	v_fmac_f32_e32 v119, v120, v120
	v_fmac_f32_e32 v121, v122, v122
	v_add_f32_e32 v119, v119, v121
	v_add_f32_e32 v118, v118, v119
	v_mul_f32_e32 v119, v153, v153
	v_mul_f32_e32 v120, v155, v155
	v_fmac_f32_e32 v119, v152, v152
	v_fmac_f32_e32 v120, v154, v154
	v_add_f32_e32 v119, v119, v120
	v_and_b32_e32 v117, 64, v150
	v_add_f32_e32 v122, v118, v119
	v_xor_b32_e32 v116, 16, v150
	v_add_u32_e32 v117, 64, v117
	v_cmp_lt_i32_e32 vcc, v116, v117
	s_waitcnt vmcnt(0)
	v_pk_fma_f32 v[120:121], v[114:115], 0.5, v[158:159] op_sel_hi:[1,0,1]
	v_pk_fma_f32 v[118:119], v[112:113], 0.5, v[156:157] op_sel_hi:[1,0,1]
	v_mul_f32_e32 v113, v121, v121
	v_mul_f32_e32 v112, v119, v119
	v_fmac_f32_e32 v112, v118, v118
	v_fmac_f32_e32 v113, v120, v120
	v_cndmask_b32_e32 v116, v150, v116, vcc
	v_add_f32_e32 v112, v112, v113
	v_lshlrev_b32_e32 v116, 2, v116
	v_add_f32_e32 v112, v122, v112
	ds_bpermute_b32 v113, v116, v112
	v_cmp_lt_i32_e32 vcc, v151, v117
	global_store_dwordx4 v[160:161], v[118:121], off offset:576 nt
	s_waitcnt lgkmcnt(0)
	v_add_f32_e32 v112, v112, v113
	v_cndmask_b32_e32 v114, v150, v151, vcc
	v_lshlrev_b32_e32 v114, 2, v114
	ds_bpermute_b32 v113, v114, v112
	v_cvt_pk_bf16_f32 v118, v118, v119
	v_cvt_pk_bf16_f32 v119, v120, v121
	v_lshl_add_u64 v[120:121], s[76:77], 0, v[162:163]
	global_store_dwordx2 v[120:121], v[118:119], off
	s_and_saveexec_b64 s[24:25], s[2:3]
	s_cbranch_execz .LBB0_1070
	v_lshlrev_b64 v[118:119], 6, v[142:143]
	v_lshl_add_u64 v[118:119], s[74:75], 0, v[118:119]
	v_lshl_add_u64 v[118:119], s[22:23], 2, v[118:119]
	s_lshl_b32 s12, s39, 2
	v_lshl_add_u64 v[118:119], v[118:119], 0, s[12:13]
	s_waitcnt lgkmcnt(0)
	v_add_f32_e32 v112, v112, v113
	global_store_dword v[118:119], v112, off
.LBB0_1070:
	s_or_b64 exec, exec, s[24:25]
	v_or_b32_e32 v112, 16, v142
	s_waitcnt lgkmcnt(0)
	v_ashrrev_i32_e32 v113, 31, v112
	v_lshlrev_b64 v[118:119], 10, v[112:113]
	v_lshl_add_u64 v[122:123], v[118:119], 0, v[140:141]
	v_lshl_add_u64 v[124:125], v[122:123], 2, s[10:11]
	global_load_dwordx4 v[118:121], v[124:125], off nt
	v_lshlrev_b64 v[122:123], 1, v[122:123]
	v_lshl_add_u64 v[126:127], s[76:77], 0, v[122:123]
	s_waitcnt vmcnt(0)
	v_pk_fma_f32 v[110:111], v[110:111], 0.5, v[120:121] op_sel_hi:[1,0,1]
	v_pk_fma_f32 v[108:109], v[108:109], 0.5, v[118:119] op_sel_hi:[1,0,1]
	global_store_dwordx4 v[124:125], v[108:111], off nt
	v_cvt_pk_bf16_f32 v118, v108, v109
	v_cvt_pk_bf16_f32 v119, v110, v111
	global_store_dwordx2 v[126:127], v[118:119], off
	global_load_dwordx4 v[118:121], v[124:125], off offset:64 nt
	v_or_b32_e32 v126, 32, v122
	v_mov_b32_e32 v127, v123
	v_lshl_add_u64 v[126:127], s[76:77], 0, v[126:127]
	v_mul_f32_e32 v109, v109, v109
	v_mul_f32_e32 v111, v111, v111
	v_fmac_f32_e32 v109, v108, v108
	v_fmac_f32_e32 v111, v110, v110
	v_add_f32_e32 v108, v109, v111
	s_waitcnt vmcnt(0)
	v_pk_fma_f32 v[106:107], v[106:107], 0.5, v[120:121] op_sel_hi:[1,0,1]
	v_pk_fma_f32 v[104:105], v[104:105], 0.5, v[118:119] op_sel_hi:[1,0,1]
	global_store_dwordx4 v[124:125], v[104:107], off offset:64 nt
	v_cvt_pk_bf16_f32 v118, v104, v105
	v_cvt_pk_bf16_f32 v119, v106, v107
	global_store_dwordx2 v[126:127], v[118:119], off
	global_load_dwordx4 v[118:121], v[124:125], off offset:512 nt
	v_or_b32_e32 v126, 0x100, v122
	v_mov_b32_e32 v127, v123
	v_lshl_add_u64 v[126:127], s[76:77], 0, v[126:127]
	v_mul_f32_e32 v105, v105, v105
	v_mul_f32_e32 v107, v107, v107
	v_fmac_f32_e32 v105, v104, v104
	v_fmac_f32_e32 v107, v106, v106
	v_add_f32_e32 v104, v105, v107
	v_add_f32_e32 v104, v108, v104
	v_or_b32_e32 v122, 0x120, v122
	s_waitcnt vmcnt(0)
	v_pk_fma_f32 v[102:103], v[102:103], 0.5, v[120:121] op_sel_hi:[1,0,1]
	v_pk_fma_f32 v[100:101], v[100:101], 0.5, v[118:119] op_sel_hi:[1,0,1]
	global_store_dwordx4 v[124:125], v[100:103], off offset:512 nt
	v_cvt_pk_bf16_f32 v118, v100, v101
	v_cvt_pk_bf16_f32 v119, v102, v103
	global_store_dwordx2 v[126:127], v[118:119], off
	global_load_dwordx4 v[118:121], v[124:125], off offset:576 nt
	v_mul_f32_e32 v101, v101, v101
	v_mul_f32_e32 v103, v103, v103
	v_fmac_f32_e32 v101, v100, v100
	v_fmac_f32_e32 v103, v102, v102
	v_add_f32_e32 v100, v101, v103
	v_add_f32_e32 v100, v104, v100
	s_waitcnt vmcnt(0)
	v_pk_fma_f32 v[98:99], v[98:99], 0.5, v[120:121] op_sel_hi:[1,0,1]
	v_pk_fma_f32 v[96:97], v[96:97], 0.5, v[118:119] op_sel_hi:[1,0,1]
	v_mul_f32_e32 v102, v99, v99
	v_mul_f32_e32 v101, v97, v97
	v_fmac_f32_e32 v101, v96, v96
	v_fmac_f32_e32 v102, v98, v98
	v_add_f32_e32 v101, v101, v102
	v_add_f32_e32 v101, v100, v101
	ds_bpermute_b32 v102, v116, v101
	global_store_dwordx4 v[124:125], v[96:99], off offset:576 nt
	v_cvt_pk_bf16_f32 v100, v96, v97
	s_waitcnt lgkmcnt(0)
	s_nop 0
	v_add_f32_e32 v96, v101, v102
	ds_bpermute_b32 v97, v114, v96
	v_cvt_pk_bf16_f32 v101, v98, v99
	v_lshl_add_u64 v[98:99], s[76:77], 0, v[122:123]
	global_store_dwordx2 v[98:99], v[100:101], off
	s_and_saveexec_b64 s[24:25], s[2:3]
	s_cbranch_execz .LBB0_1072
	v_lshlrev_b64 v[98:99], 6, v[112:113]
	v_lshl_add_u64 v[98:99], s[74:75], 0, v[98:99]
	v_lshl_add_u64 v[98:99], s[22:23], 2, v[98:99]
	s_lshl_b32 s12, s39, 2
	v_lshl_add_u64 v[98:99], v[98:99], 0, s[12:13]
	s_waitcnt lgkmcnt(0)
	v_add_f32_e32 v96, v96, v97
	global_store_dword v[98:99], v96, off
.LBB0_1072:
	s_or_b64 exec, exec, s[24:25]
	v_or_b32_e32 v96, 32, v142
	s_waitcnt lgkmcnt(0)
	v_ashrrev_i32_e32 v97, 31, v96
	v_lshlrev_b64 v[98:99], 10, v[96:97]
	v_lshl_add_u64 v[102:103], v[98:99], 0, v[140:141]
	v_lshl_add_u64 v[104:105], v[102:103], 2, s[10:11]
	global_load_dwordx4 v[98:101], v[104:105], off nt
	v_lshlrev_b64 v[102:103], 1, v[102:103]
	v_lshl_add_u64 v[106:107], s[76:77], 0, v[102:103]
	s_waitcnt vmcnt(0)
	v_pk_fma_f32 v[94:95], v[94:95], 0.5, v[100:101] op_sel_hi:[1,0,1]
	v_pk_fma_f32 v[92:93], v[92:93], 0.5, v[98:99] op_sel_hi:[1,0,1]
	global_store_dwordx4 v[104:105], v[92:95], off nt
	v_cvt_pk_bf16_f32 v98, v92, v93
	v_cvt_pk_bf16_f32 v99, v94, v95
	global_store_dwordx2 v[106:107], v[98:99], off
	global_load_dwordx4 v[98:101], v[104:105], off offset:64 nt
	v_or_b32_e32 v106, 32, v102
	v_mov_b32_e32 v107, v103
	v_lshl_add_u64 v[106:107], s[76:77], 0, v[106:107]
	v_mul_f32_e32 v93, v93, v93
	v_mul_f32_e32 v95, v95, v95
	v_fmac_f32_e32 v93, v92, v92
	v_fmac_f32_e32 v95, v94, v94
	v_add_f32_e32 v92, v93, v95
	s_waitcnt vmcnt(0)
	v_pk_fma_f32 v[90:91], v[90:91], 0.5, v[100:101] op_sel_hi:[1,0,1]
	v_pk_fma_f32 v[88:89], v[88:89], 0.5, v[98:99] op_sel_hi:[1,0,1]
	global_store_dwordx4 v[104:105], v[88:91], off offset:64 nt
	v_cvt_pk_bf16_f32 v98, v88, v89
	v_cvt_pk_bf16_f32 v99, v90, v91
	global_store_dwordx2 v[106:107], v[98:99], off
	global_load_dwordx4 v[98:101], v[104:105], off offset:512 nt
	v_or_b32_e32 v106, 0x100, v102
	v_mov_b32_e32 v107, v103
	v_lshl_add_u64 v[106:107], s[76:77], 0, v[106:107]
	v_mul_f32_e32 v89, v89, v89
	v_mul_f32_e32 v91, v91, v91
	v_fmac_f32_e32 v89, v88, v88
	v_fmac_f32_e32 v91, v90, v90
	v_add_f32_e32 v88, v89, v91
	v_add_f32_e32 v88, v92, v88
	v_or_b32_e32 v102, 0x120, v102
	s_waitcnt vmcnt(0)
	v_pk_fma_f32 v[86:87], v[86:87], 0.5, v[100:101] op_sel_hi:[1,0,1]
	v_pk_fma_f32 v[84:85], v[84:85], 0.5, v[98:99] op_sel_hi:[1,0,1]
	global_store_dwordx4 v[104:105], v[84:87], off offset:512 nt
	v_cvt_pk_bf16_f32 v98, v84, v85
	v_cvt_pk_bf16_f32 v99, v86, v87
	global_store_dwordx2 v[106:107], v[98:99], off
	global_load_dwordx4 v[98:101], v[104:105], off offset:576 nt
	v_mul_f32_e32 v85, v85, v85
	v_mul_f32_e32 v87, v87, v87
	v_fmac_f32_e32 v85, v84, v84
	v_fmac_f32_e32 v87, v86, v86
	v_add_f32_e32 v84, v85, v87
	v_add_f32_e32 v84, v88, v84
	s_waitcnt vmcnt(0)
	v_pk_fma_f32 v[82:83], v[82:83], 0.5, v[100:101] op_sel_hi:[1,0,1]
	v_pk_fma_f32 v[80:81], v[80:81], 0.5, v[98:99] op_sel_hi:[1,0,1]
	v_mul_f32_e32 v86, v83, v83
	v_mul_f32_e32 v85, v81, v81
	v_fmac_f32_e32 v85, v80, v80
	v_fmac_f32_e32 v86, v82, v82
	v_add_f32_e32 v85, v85, v86
	v_add_f32_e32 v85, v84, v85
	ds_bpermute_b32 v86, v116, v85
	global_store_dwordx4 v[104:105], v[80:83], off offset:576 nt
	v_cvt_pk_bf16_f32 v84, v80, v81
	s_waitcnt lgkmcnt(0)
	s_nop 0
	v_add_f32_e32 v80, v85, v86
	ds_bpermute_b32 v81, v114, v80
	v_cvt_pk_bf16_f32 v85, v82, v83
	v_lshl_add_u64 v[82:83], s[76:77], 0, v[102:103]
	global_store_dwordx2 v[82:83], v[84:85], off
	s_and_saveexec_b64 s[24:25], s[2:3]
	s_cbranch_execz .LBB0_1074
	v_lshlrev_b64 v[82:83], 6, v[96:97]
	v_lshl_add_u64 v[82:83], s[74:75], 0, v[82:83]
	v_lshl_add_u64 v[82:83], s[22:23], 2, v[82:83]
	s_lshl_b32 s12, s39, 2
	v_lshl_add_u64 v[82:83], v[82:83], 0, s[12:13]
	s_waitcnt lgkmcnt(0)
	v_add_f32_e32 v80, v80, v81
	global_store_dword v[82:83], v80, off
.LBB0_1074:
	s_or_b64 exec, exec, s[24:25]
	v_or_b32_e32 v80, 48, v142
	s_waitcnt lgkmcnt(0)
	v_ashrrev_i32_e32 v81, 31, v80
	v_lshlrev_b64 v[82:83], 10, v[80:81]
	v_lshl_add_u64 v[86:87], v[82:83], 0, v[140:141]
	v_lshl_add_u64 v[88:89], v[86:87], 2, s[10:11]
	global_load_dwordx4 v[82:85], v[88:89], off nt
	v_lshlrev_b64 v[86:87], 1, v[86:87]
	v_lshl_add_u64 v[90:91], s[76:77], 0, v[86:87]
	s_waitcnt vmcnt(0)
	v_pk_fma_f32 v[78:79], v[78:79], 0.5, v[84:85] op_sel_hi:[1,0,1]
	v_pk_fma_f32 v[76:77], v[76:77], 0.5, v[82:83] op_sel_hi:[1,0,1]
	global_store_dwordx4 v[88:89], v[76:79], off nt
	v_cvt_pk_bf16_f32 v82, v76, v77
	v_cvt_pk_bf16_f32 v83, v78, v79
	global_store_dwordx2 v[90:91], v[82:83], off
	global_load_dwordx4 v[82:85], v[88:89], off offset:64 nt
	v_or_b32_e32 v90, 32, v86
	v_mov_b32_e32 v91, v87
	v_lshl_add_u64 v[90:91], s[76:77], 0, v[90:91]
	v_mul_f32_e32 v77, v77, v77
	v_mul_f32_e32 v79, v79, v79
	v_fmac_f32_e32 v77, v76, v76
	v_fmac_f32_e32 v79, v78, v78
	v_add_f32_e32 v76, v77, v79
	s_waitcnt vmcnt(0)
	v_pk_fma_f32 v[74:75], v[74:75], 0.5, v[84:85] op_sel_hi:[1,0,1]
	v_pk_fma_f32 v[72:73], v[72:73], 0.5, v[82:83] op_sel_hi:[1,0,1]
	global_store_dwordx4 v[88:89], v[72:75], off offset:64 nt
	v_cvt_pk_bf16_f32 v82, v72, v73
	v_cvt_pk_bf16_f32 v83, v74, v75
	global_store_dwordx2 v[90:91], v[82:83], off
	global_load_dwordx4 v[82:85], v[88:89], off offset:512 nt
	v_or_b32_e32 v90, 0x100, v86
	v_mov_b32_e32 v91, v87
	v_lshl_add_u64 v[90:91], s[76:77], 0, v[90:91]
	v_mul_f32_e32 v73, v73, v73
	v_mul_f32_e32 v75, v75, v75
	v_fmac_f32_e32 v73, v72, v72
	v_fmac_f32_e32 v75, v74, v74
	v_add_f32_e32 v72, v73, v75
	v_add_f32_e32 v72, v76, v72
	v_or_b32_e32 v86, 0x120, v86
	s_waitcnt vmcnt(0)
	v_pk_fma_f32 v[70:71], v[70:71], 0.5, v[84:85] op_sel_hi:[1,0,1]
	v_pk_fma_f32 v[68:69], v[68:69], 0.5, v[82:83] op_sel_hi:[1,0,1]
	global_store_dwordx4 v[88:89], v[68:71], off offset:512 nt
	v_cvt_pk_bf16_f32 v82, v68, v69
	v_cvt_pk_bf16_f32 v83, v70, v71
	global_store_dwordx2 v[90:91], v[82:83], off
	global_load_dwordx4 v[82:85], v[88:89], off offset:576 nt
	v_mul_f32_e32 v69, v69, v69
	v_mul_f32_e32 v71, v71, v71
	v_fmac_f32_e32 v69, v68, v68
	v_fmac_f32_e32 v71, v70, v70
	v_add_f32_e32 v68, v69, v71
	v_add_f32_e32 v68, v72, v68
	s_waitcnt vmcnt(0)
	v_pk_fma_f32 v[66:67], v[66:67], 0.5, v[84:85] op_sel_hi:[1,0,1]
	v_pk_fma_f32 v[64:65], v[64:65], 0.5, v[82:83] op_sel_hi:[1,0,1]
	v_mul_f32_e32 v70, v67, v67
	v_mul_f32_e32 v69, v65, v65
	v_fmac_f32_e32 v69, v64, v64
	v_fmac_f32_e32 v70, v66, v66
	v_add_f32_e32 v69, v69, v70
	v_add_f32_e32 v69, v68, v69
	ds_bpermute_b32 v70, v116, v69
	global_store_dwordx4 v[88:89], v[64:67], off offset:576 nt
	v_cvt_pk_bf16_f32 v68, v64, v65
	s_waitcnt lgkmcnt(0)
	s_nop 0
	v_add_f32_e32 v64, v69, v70
	ds_bpermute_b32 v65, v114, v64
	v_cvt_pk_bf16_f32 v69, v66, v67
	v_lshl_add_u64 v[66:67], s[76:77], 0, v[86:87]
	global_store_dwordx2 v[66:67], v[68:69], off
	s_and_saveexec_b64 s[24:25], s[2:3]
	s_cbranch_execz .LBB0_1076
	v_lshlrev_b64 v[66:67], 6, v[80:81]
	v_lshl_add_u64 v[66:67], s[74:75], 0, v[66:67]
	v_lshl_add_u64 v[66:67], s[22:23], 2, v[66:67]
	s_lshl_b32 s12, s39, 2
	v_lshl_add_u64 v[66:67], v[66:67], 0, s[12:13]
	s_waitcnt lgkmcnt(0)
	v_add_f32_e32 v64, v64, v65
	global_store_dword v[66:67], v64, off
.LBB0_1076:
	s_or_b64 exec, exec, s[24:25]
	v_add_u32_e32 v64, 0x80, v142
	s_waitcnt lgkmcnt(0)
	v_ashrrev_i32_e32 v65, 31, v64
	v_lshlrev_b64 v[66:67], 10, v[64:65]
	v_lshl_add_u64 v[70:71], v[66:67], 0, v[140:141]
	v_lshl_add_u64 v[72:73], v[70:71], 2, s[10:11]
	global_load_dwordx4 v[66:69], v[72:73], off nt
	v_lshlrev_b64 v[70:71], 1, v[70:71]
	v_lshl_add_u64 v[74:75], s[76:77], 0, v[70:71]
	s_waitcnt vmcnt(0)
	v_pk_fma_f32 v[62:63], v[62:63], 0.5, v[68:69] op_sel_hi:[1,0,1]
	v_pk_fma_f32 v[60:61], v[60:61], 0.5, v[66:67] op_sel_hi:[1,0,1]
	global_store_dwordx4 v[72:73], v[60:63], off nt
	v_cvt_pk_bf16_f32 v66, v60, v61
	v_cvt_pk_bf16_f32 v67, v62, v63
	global_store_dwordx2 v[74:75], v[66:67], off
	global_load_dwordx4 v[66:69], v[72:73], off offset:64 nt
	v_or_b32_e32 v74, 32, v70
	v_mov_b32_e32 v75, v71
	v_lshl_add_u64 v[74:75], s[76:77], 0, v[74:75]
	v_mul_f32_e32 v61, v61, v61
	v_mul_f32_e32 v63, v63, v63
	v_fmac_f32_e32 v61, v60, v60
	v_fmac_f32_e32 v63, v62, v62
	v_add_f32_e32 v60, v61, v63
	s_waitcnt vmcnt(0)
	v_pk_fma_f32 v[58:59], v[58:59], 0.5, v[68:69] op_sel_hi:[1,0,1]
	v_pk_fma_f32 v[56:57], v[56:57], 0.5, v[66:67] op_sel_hi:[1,0,1]
	global_store_dwordx4 v[72:73], v[56:59], off offset:64 nt
	v_cvt_pk_bf16_f32 v66, v56, v57
	v_cvt_pk_bf16_f32 v67, v58, v59
	global_store_dwordx2 v[74:75], v[66:67], off
	global_load_dwordx4 v[66:69], v[72:73], off offset:512 nt
	v_or_b32_e32 v74, 0x100, v70
	v_mov_b32_e32 v75, v71
	v_lshl_add_u64 v[74:75], s[76:77], 0, v[74:75]
	v_mul_f32_e32 v57, v57, v57
	v_mul_f32_e32 v59, v59, v59
	v_fmac_f32_e32 v57, v56, v56
	v_fmac_f32_e32 v59, v58, v58
	v_add_f32_e32 v56, v57, v59
	v_add_f32_e32 v56, v60, v56
	v_or_b32_e32 v70, 0x120, v70
	s_waitcnt vmcnt(0)
	v_pk_fma_f32 v[54:55], v[54:55], 0.5, v[68:69] op_sel_hi:[1,0,1]
	v_pk_fma_f32 v[52:53], v[52:53], 0.5, v[66:67] op_sel_hi:[1,0,1]
	global_store_dwordx4 v[72:73], v[52:55], off offset:512 nt
	v_cvt_pk_bf16_f32 v66, v52, v53
	v_cvt_pk_bf16_f32 v67, v54, v55
	global_store_dwordx2 v[74:75], v[66:67], off
	global_load_dwordx4 v[66:69], v[72:73], off offset:576 nt
	v_mul_f32_e32 v53, v53, v53
	v_mul_f32_e32 v55, v55, v55
	v_fmac_f32_e32 v53, v52, v52
	v_fmac_f32_e32 v55, v54, v54
	v_add_f32_e32 v52, v53, v55
	v_add_f32_e32 v52, v56, v52
	s_waitcnt vmcnt(0)
	v_pk_fma_f32 v[50:51], v[50:51], 0.5, v[68:69] op_sel_hi:[1,0,1]
	v_pk_fma_f32 v[48:49], v[48:49], 0.5, v[66:67] op_sel_hi:[1,0,1]
	v_mul_f32_e32 v54, v51, v51
	v_mul_f32_e32 v53, v49, v49
	v_fmac_f32_e32 v53, v48, v48
	v_fmac_f32_e32 v54, v50, v50
	v_add_f32_e32 v53, v53, v54
	v_add_f32_e32 v53, v52, v53
	ds_bpermute_b32 v54, v116, v53
	global_store_dwordx4 v[72:73], v[48:51], off offset:576 nt
	v_cvt_pk_bf16_f32 v52, v48, v49
	s_waitcnt lgkmcnt(0)
	s_nop 0
	v_add_f32_e32 v48, v53, v54
	ds_bpermute_b32 v49, v114, v48
	v_cvt_pk_bf16_f32 v53, v50, v51
	v_lshl_add_u64 v[50:51], s[76:77], 0, v[70:71]
	global_store_dwordx2 v[50:51], v[52:53], off
	s_and_saveexec_b64 s[24:25], s[2:3]
	s_cbranch_execz .LBB0_1078
	v_lshlrev_b64 v[50:51], 6, v[64:65]
	v_lshl_add_u64 v[50:51], s[74:75], 0, v[50:51]
	v_lshl_add_u64 v[50:51], s[22:23], 2, v[50:51]
	s_lshl_b32 s12, s39, 2
	v_lshl_add_u64 v[50:51], v[50:51], 0, s[12:13]
	s_waitcnt lgkmcnt(0)
	v_add_f32_e32 v48, v48, v49
	global_store_dword v[50:51], v48, off
.LBB0_1078:
	s_or_b64 exec, exec, s[24:25]
	v_add_u32_e32 v48, 0x90, v142
	s_waitcnt lgkmcnt(0)
	v_ashrrev_i32_e32 v49, 31, v48
	v_lshlrev_b64 v[50:51], 10, v[48:49]
	v_lshl_add_u64 v[54:55], v[50:51], 0, v[140:141]
	v_lshl_add_u64 v[56:57], v[54:55], 2, s[10:11]
	global_load_dwordx4 v[50:53], v[56:57], off nt
	v_lshlrev_b64 v[54:55], 1, v[54:55]
	v_lshl_add_u64 v[58:59], s[76:77], 0, v[54:55]
	s_waitcnt vmcnt(0)
	v_pk_fma_f32 v[46:47], v[46:47], 0.5, v[52:53] op_sel_hi:[1,0,1]
	v_pk_fma_f32 v[44:45], v[44:45], 0.5, v[50:51] op_sel_hi:[1,0,1]
	global_store_dwordx4 v[56:57], v[44:47], off nt
	v_cvt_pk_bf16_f32 v50, v44, v45
	v_cvt_pk_bf16_f32 v51, v46, v47
	global_store_dwordx2 v[58:59], v[50:51], off
	global_load_dwordx4 v[50:53], v[56:57], off offset:64 nt
	v_or_b32_e32 v58, 32, v54
	v_mov_b32_e32 v59, v55
	v_lshl_add_u64 v[58:59], s[76:77], 0, v[58:59]
	v_mul_f32_e32 v45, v45, v45
	v_mul_f32_e32 v47, v47, v47
	v_fmac_f32_e32 v45, v44, v44
	v_fmac_f32_e32 v47, v46, v46
	v_add_f32_e32 v44, v45, v47
	s_waitcnt vmcnt(0)
	v_pk_fma_f32 v[42:43], v[42:43], 0.5, v[52:53] op_sel_hi:[1,0,1]
	v_pk_fma_f32 v[40:41], v[40:41], 0.5, v[50:51] op_sel_hi:[1,0,1]
	global_store_dwordx4 v[56:57], v[40:43], off offset:64 nt
	v_cvt_pk_bf16_f32 v50, v40, v41
	v_cvt_pk_bf16_f32 v51, v42, v43
	global_store_dwordx2 v[58:59], v[50:51], off
	global_load_dwordx4 v[50:53], v[56:57], off offset:512 nt
	v_or_b32_e32 v58, 0x100, v54
	v_mov_b32_e32 v59, v55
	v_lshl_add_u64 v[58:59], s[76:77], 0, v[58:59]
	v_mul_f32_e32 v41, v41, v41
	v_mul_f32_e32 v43, v43, v43
	v_fmac_f32_e32 v41, v40, v40
	v_fmac_f32_e32 v43, v42, v42
	v_add_f32_e32 v40, v41, v43
	v_add_f32_e32 v40, v44, v40
	v_or_b32_e32 v54, 0x120, v54
	s_waitcnt vmcnt(0)
	v_pk_fma_f32 v[38:39], v[38:39], 0.5, v[52:53] op_sel_hi:[1,0,1]
	v_pk_fma_f32 v[36:37], v[36:37], 0.5, v[50:51] op_sel_hi:[1,0,1]
	global_store_dwordx4 v[56:57], v[36:39], off offset:512 nt
	v_cvt_pk_bf16_f32 v50, v36, v37
	v_cvt_pk_bf16_f32 v51, v38, v39
	global_store_dwordx2 v[58:59], v[50:51], off
	global_load_dwordx4 v[50:53], v[56:57], off offset:576 nt
	v_mul_f32_e32 v37, v37, v37
	v_mul_f32_e32 v39, v39, v39
	v_fmac_f32_e32 v37, v36, v36
	v_fmac_f32_e32 v39, v38, v38
	v_add_f32_e32 v36, v37, v39
	v_add_f32_e32 v36, v40, v36
	s_waitcnt vmcnt(0)
	v_pk_fma_f32 v[34:35], v[34:35], 0.5, v[52:53] op_sel_hi:[1,0,1]
	v_pk_fma_f32 v[32:33], v[32:33], 0.5, v[50:51] op_sel_hi:[1,0,1]
	v_mul_f32_e32 v38, v35, v35
	v_mul_f32_e32 v37, v33, v33
	v_fmac_f32_e32 v37, v32, v32
	v_fmac_f32_e32 v38, v34, v34
	v_add_f32_e32 v37, v37, v38
	v_add_f32_e32 v37, v36, v37
	ds_bpermute_b32 v38, v116, v37
	global_store_dwordx4 v[56:57], v[32:35], off offset:576 nt
	v_cvt_pk_bf16_f32 v36, v32, v33
	s_waitcnt lgkmcnt(0)
	s_nop 0
	v_add_f32_e32 v32, v37, v38
	ds_bpermute_b32 v33, v114, v32
	v_cvt_pk_bf16_f32 v37, v34, v35
	v_lshl_add_u64 v[34:35], s[76:77], 0, v[54:55]
	global_store_dwordx2 v[34:35], v[36:37], off
	s_and_saveexec_b64 s[24:25], s[2:3]
	s_cbranch_execz .LBB0_1080
	v_lshlrev_b64 v[34:35], 6, v[48:49]
	v_lshl_add_u64 v[34:35], s[74:75], 0, v[34:35]
	v_lshl_add_u64 v[34:35], s[22:23], 2, v[34:35]
	s_lshl_b32 s12, s39, 2
	v_lshl_add_u64 v[34:35], v[34:35], 0, s[12:13]
	s_waitcnt lgkmcnt(0)
	v_add_f32_e32 v32, v32, v33
	global_store_dword v[34:35], v32, off
.LBB0_1080:
	s_or_b64 exec, exec, s[24:25]
	v_add_u32_e32 v32, 0xa0, v142
	s_waitcnt lgkmcnt(0)
	v_ashrrev_i32_e32 v33, 31, v32
	v_lshlrev_b64 v[34:35], 10, v[32:33]
	v_lshl_add_u64 v[38:39], v[34:35], 0, v[140:141]
	v_lshl_add_u64 v[40:41], v[38:39], 2, s[10:11]
	global_load_dwordx4 v[34:37], v[40:41], off nt
	v_lshlrev_b64 v[38:39], 1, v[38:39]
	v_lshl_add_u64 v[42:43], s[76:77], 0, v[38:39]
	s_waitcnt vmcnt(0)
	v_pk_fma_f32 v[30:31], v[30:31], 0.5, v[36:37] op_sel_hi:[1,0,1]
	v_pk_fma_f32 v[28:29], v[28:29], 0.5, v[34:35] op_sel_hi:[1,0,1]
	global_store_dwordx4 v[40:41], v[28:31], off nt
	v_cvt_pk_bf16_f32 v34, v28, v29
	v_cvt_pk_bf16_f32 v35, v30, v31
	global_store_dwordx2 v[42:43], v[34:35], off
	global_load_dwordx4 v[34:37], v[40:41], off offset:64 nt
	v_or_b32_e32 v42, 32, v38
	v_mov_b32_e32 v43, v39
	v_lshl_add_u64 v[42:43], s[76:77], 0, v[42:43]
	v_mul_f32_e32 v29, v29, v29
	v_mul_f32_e32 v31, v31, v31
	v_fmac_f32_e32 v29, v28, v28
	v_fmac_f32_e32 v31, v30, v30
	v_add_f32_e32 v28, v29, v31
	s_waitcnt vmcnt(0)
	v_pk_fma_f32 v[26:27], v[26:27], 0.5, v[36:37] op_sel_hi:[1,0,1]
	v_pk_fma_f32 v[24:25], v[24:25], 0.5, v[34:35] op_sel_hi:[1,0,1]
	global_store_dwordx4 v[40:41], v[24:27], off offset:64 nt
	v_cvt_pk_bf16_f32 v34, v24, v25
	v_cvt_pk_bf16_f32 v35, v26, v27
	global_store_dwordx2 v[42:43], v[34:35], off
	global_load_dwordx4 v[34:37], v[40:41], off offset:512 nt
	v_or_b32_e32 v42, 0x100, v38
	v_mov_b32_e32 v43, v39
	v_lshl_add_u64 v[42:43], s[76:77], 0, v[42:43]
	v_mul_f32_e32 v25, v25, v25
	v_mul_f32_e32 v27, v27, v27
	v_fmac_f32_e32 v25, v24, v24
	v_fmac_f32_e32 v27, v26, v26
	v_add_f32_e32 v24, v25, v27
	v_add_f32_e32 v24, v28, v24
	v_or_b32_e32 v38, 0x120, v38
	s_waitcnt vmcnt(0)
	v_pk_fma_f32 v[22:23], v[22:23], 0.5, v[36:37] op_sel_hi:[1,0,1]
	v_pk_fma_f32 v[20:21], v[20:21], 0.5, v[34:35] op_sel_hi:[1,0,1]
	global_store_dwordx4 v[40:41], v[20:23], off offset:512 nt
	v_cvt_pk_bf16_f32 v34, v20, v21
	v_cvt_pk_bf16_f32 v35, v22, v23
	global_store_dwordx2 v[42:43], v[34:35], off
	global_load_dwordx4 v[34:37], v[40:41], off offset:576 nt
	v_mul_f32_e32 v21, v21, v21
	v_mul_f32_e32 v23, v23, v23
	v_fmac_f32_e32 v21, v20, v20
	v_fmac_f32_e32 v23, v22, v22
	v_add_f32_e32 v20, v21, v23
	v_add_f32_e32 v20, v24, v20
	s_waitcnt vmcnt(0)
	v_pk_fma_f32 v[18:19], v[18:19], 0.5, v[36:37] op_sel_hi:[1,0,1]
	v_pk_fma_f32 v[16:17], v[16:17], 0.5, v[34:35] op_sel_hi:[1,0,1]
	v_mul_f32_e32 v22, v19, v19
	v_mul_f32_e32 v21, v17, v17
	v_fmac_f32_e32 v21, v16, v16
	v_fmac_f32_e32 v22, v18, v18
	v_add_f32_e32 v21, v21, v22
	v_add_f32_e32 v21, v20, v21
	ds_bpermute_b32 v22, v116, v21
	global_store_dwordx4 v[40:41], v[16:19], off offset:576 nt
	v_cvt_pk_bf16_f32 v20, v16, v17
	s_waitcnt lgkmcnt(0)
	s_nop 0
	v_add_f32_e32 v16, v21, v22
	ds_bpermute_b32 v17, v114, v16
	v_cvt_pk_bf16_f32 v21, v18, v19
	v_lshl_add_u64 v[18:19], s[76:77], 0, v[38:39]
	global_store_dwordx2 v[18:19], v[20:21], off
	s_and_saveexec_b64 s[24:25], s[2:3]
	s_cbranch_execz .LBB0_1082
	v_lshlrev_b64 v[18:19], 6, v[32:33]
	v_lshl_add_u64 v[18:19], s[74:75], 0, v[18:19]
	v_lshl_add_u64 v[18:19], s[22:23], 2, v[18:19]
	s_lshl_b32 s12, s39, 2
	v_lshl_add_u64 v[18:19], v[18:19], 0, s[12:13]
	s_waitcnt lgkmcnt(0)
	v_add_f32_e32 v16, v16, v17
	global_store_dword v[18:19], v16, off
.LBB0_1082:
	s_or_b64 exec, exec, s[24:25]
	v_add_u32_e32 v16, 0xb0, v142
	s_waitcnt lgkmcnt(0)
	v_ashrrev_i32_e32 v17, 31, v16
	v_lshlrev_b64 v[18:19], 10, v[16:17]
	v_lshl_add_u64 v[22:23], v[18:19], 0, v[140:141]
	v_lshl_add_u64 v[24:25], v[22:23], 2, s[10:11]
	global_load_dwordx4 v[18:21], v[24:25], off nt
	v_lshlrev_b64 v[22:23], 1, v[22:23]
	v_lshl_add_u64 v[26:27], s[76:77], 0, v[22:23]
	s_waitcnt vmcnt(0)
	v_pk_fma_f32 v[14:15], v[14:15], 0.5, v[20:21] op_sel_hi:[1,0,1]
	v_pk_fma_f32 v[12:13], v[12:13], 0.5, v[18:19] op_sel_hi:[1,0,1]
	global_store_dwordx4 v[24:25], v[12:15], off nt
	v_cvt_pk_bf16_f32 v18, v12, v13
	v_cvt_pk_bf16_f32 v19, v14, v15
	global_store_dwordx2 v[26:27], v[18:19], off
	global_load_dwordx4 v[18:21], v[24:25], off offset:64 nt
	v_or_b32_e32 v26, 32, v22
	v_mov_b32_e32 v27, v23
	v_lshl_add_u64 v[26:27], s[76:77], 0, v[26:27]
	v_mul_f32_e32 v13, v13, v13
	v_mul_f32_e32 v15, v15, v15
	v_fmac_f32_e32 v13, v12, v12
	v_fmac_f32_e32 v15, v14, v14
	v_add_f32_e32 v12, v13, v15
	s_waitcnt vmcnt(0)
	v_pk_fma_f32 v[10:11], v[10:11], 0.5, v[20:21] op_sel_hi:[1,0,1]
	v_pk_fma_f32 v[8:9], v[8:9], 0.5, v[18:19] op_sel_hi:[1,0,1]
	global_store_dwordx4 v[24:25], v[8:11], off offset:64 nt
	v_cvt_pk_bf16_f32 v18, v8, v9
	v_cvt_pk_bf16_f32 v19, v10, v11
	global_store_dwordx2 v[26:27], v[18:19], off
	global_load_dwordx4 v[18:21], v[24:25], off offset:512 nt
	v_or_b32_e32 v26, 0x100, v22
	v_mov_b32_e32 v27, v23
	v_lshl_add_u64 v[26:27], s[76:77], 0, v[26:27]
	v_mul_f32_e32 v9, v9, v9
	v_mul_f32_e32 v11, v11, v11
	v_fmac_f32_e32 v9, v8, v8
	v_fmac_f32_e32 v11, v10, v10
	v_add_f32_e32 v8, v9, v11
	v_add_f32_e32 v8, v12, v8
	v_or_b32_e32 v22, 0x120, v22
	s_waitcnt vmcnt(0)
	v_pk_fma_f32 v[6:7], v[6:7], 0.5, v[20:21] op_sel_hi:[1,0,1]
	v_pk_fma_f32 v[4:5], v[4:5], 0.5, v[18:19] op_sel_hi:[1,0,1]
	global_store_dwordx4 v[24:25], v[4:7], off offset:512 nt
	v_cvt_pk_bf16_f32 v18, v4, v5
	v_cvt_pk_bf16_f32 v19, v6, v7
	global_store_dwordx2 v[26:27], v[18:19], off
	global_load_dwordx4 v[18:21], v[24:25], off offset:576 nt
	v_mul_f32_e32 v5, v5, v5
	v_mul_f32_e32 v7, v7, v7
	v_fmac_f32_e32 v5, v4, v4
	v_fmac_f32_e32 v7, v6, v6
	v_add_f32_e32 v4, v5, v7
	v_add_f32_e32 v4, v8, v4
	s_waitcnt vmcnt(0)
	v_pk_fma_f32 v[2:3], v[2:3], 0.5, v[20:21] op_sel_hi:[1,0,1]
	v_pk_fma_f32 v[0:1], v[0:1], 0.5, v[18:19] op_sel_hi:[1,0,1]
	v_mul_f32_e32 v6, v3, v3
	v_mul_f32_e32 v5, v1, v1
	v_fmac_f32_e32 v5, v0, v0
	v_fmac_f32_e32 v6, v2, v2
	v_add_f32_e32 v5, v5, v6
	v_add_f32_e32 v5, v4, v5
	ds_bpermute_b32 v6, v116, v5
	global_store_dwordx4 v[24:25], v[0:3], off offset:576 nt
	v_cvt_pk_bf16_f32 v4, v0, v1
	s_waitcnt lgkmcnt(0)
	s_nop 0
	v_add_f32_e32 v0, v5, v6
	ds_bpermute_b32 v1, v114, v0
	v_cvt_pk_bf16_f32 v5, v2, v3
	v_lshl_add_u64 v[2:3], s[76:77], 0, v[22:23]
	global_store_dwordx2 v[2:3], v[4:5], off
	s_and_saveexec_b64 s[24:25], s[2:3]
	s_cbranch_execz .LBB0_1084
	v_lshlrev_b64 v[2:3], 6, v[16:17]
	v_lshl_add_u64 v[2:3], s[74:75], 0, v[2:3]
	v_lshl_add_u64 v[2:3], s[22:23], 2, v[2:3]
	s_lshl_b32 s12, s39, 2
	v_lshl_add_u64 v[2:3], v[2:3], 0, s[12:13]
	s_waitcnt lgkmcnt(0)
	v_add_f32_e32 v0, v0, v1
	global_store_dword v[2:3], v0, off

.LBB0_1222:
	v_lshl_add_u32 v142, s51, 8, v144
	v_lshl_or_b32 v140, s14, 8, v146
	v_ashrrev_i32_e32 v143, 31, v142
	v_ashrrev_i32_e32 v141, 31, v140
	v_lshlrev_b64 v[152:153], 10, v[142:143]
	v_lshl_add_u64 v[156:157], v[152:153], 0, v[140:141]
	v_lshl_add_u64 v[160:161], v[156:157], 2, s[12:13]
	global_load_dwordx4 v[152:155], v[160:161], off nt
	v_lshlrev_b64 v[162:163], 1, v[156:157]
	v_lshl_add_u64 v[156:157], s[76:77], 0, v[162:163]
	v_xor_b32_e32 v151, 32, v150
	s_lshl_b32 s24, s14, 2
	s_ashr_i32 s25, s24, 31
	s_waitcnt vmcnt(0)
	v_pk_fma_f32 v[126:127], v[126:127], 0.5, v[154:155] op_sel_hi:[1,0,1]
	v_pk_fma_f32 v[124:125], v[124:125], 0.5, v[152:153] op_sel_hi:[1,0,1]
	global_store_dwordx4 v[160:161], v[124:127], off nt
	v_cvt_pk_bf16_f32 v152, v124, v125
	v_cvt_pk_bf16_f32 v153, v126, v127
	global_store_dwordx2 v[156:157], v[152:153], off
	global_load_dwordx4 v[152:155], v[160:161], off offset:64 nt
	v_or_b32_e32 v156, 32, v162
	v_mov_b32_e32 v157, v163
	v_lshl_add_u64 v[156:157], s[76:77], 0, v[156:157]
	s_waitcnt vmcnt(0)
	v_pk_fma_f32 v[122:123], v[122:123], 0.5, v[154:155] op_sel_hi:[1,0,1]
	v_pk_fma_f32 v[120:121], v[120:121], 0.5, v[152:153] op_sel_hi:[1,0,1]
	global_store_dwordx4 v[160:161], v[120:123], off offset:64 nt
	v_cvt_pk_bf16_f32 v152, v120, v121
	v_cvt_pk_bf16_f32 v153, v122, v123
	global_store_dwordx2 v[156:157], v[152:153], off
	global_load_dwordx4 v[152:155], v[160:161], off offset:512 nt
	v_or_b32_e32 v156, 0x100, v162
	v_mov_b32_e32 v157, v163
	v_lshl_add_u64 v[156:157], s[76:77], 0, v[156:157]
	v_or_b32_e32 v162, 0x120, v162
	s_waitcnt vmcnt(0)
	v_pk_fma_f32 v[154:155], v[118:119], 0.5, v[154:155] op_sel_hi:[1,0,1]
	v_pk_fma_f32 v[152:153], v[116:117], 0.5, v[152:153] op_sel_hi:[1,0,1]
	global_store_dwordx4 v[160:161], v[152:155], off offset:512 nt
	v_cvt_pk_bf16_f32 v116, v152, v153
	v_cvt_pk_bf16_f32 v117, v154, v155
	global_store_dwordx2 v[156:157], v[116:117], off
	global_load_dwordx4 v[156:159], v[160:161], off offset:576 nt
	v_mul_f32_e32 v118, v125, v125
	v_mul_f32_e32 v119, v127, v127
	v_fmac_f32_e32 v118, v124, v124
	v_fmac_f32_e32 v119, v126, v126
	v_add_f32_e32 v118, v118, v119
	v_mul_f32_e32 v119, v121, v121
	v_mul_f32_e32 v121, v123, v123
	v_fmac_f32_e32 v119, v120, v120
	v_fmac_f32_e32 v121, v122, v122
	v_add_f32_e32 v119, v119, v121
	v_add_f32_e32 v118, v118, v119
	v_mul_f32_e32 v119, v153, v153
	v_mul_f32_e32 v120, v155, v155
	v_fmac_f32_e32 v119, v152, v152
	v_fmac_f32_e32 v120, v154, v154
	v_add_f32_e32 v119, v119, v120
	v_and_b32_e32 v117, 64, v150
	v_add_f32_e32 v122, v118, v119
	v_xor_b32_e32 v116, 16, v150
	v_add_u32_e32 v117, 64, v117
	v_cmp_lt_i32_e32 vcc, v116, v117
	s_waitcnt vmcnt(0)
	v_pk_fma_f32 v[120:121], v[114:115], 0.5, v[158:159] op_sel_hi:[1,0,1]
	v_pk_fma_f32 v[118:119], v[112:113], 0.5, v[156:157] op_sel_hi:[1,0,1]
	v_mul_f32_e32 v113, v121, v121
	v_mul_f32_e32 v112, v119, v119
	v_fmac_f32_e32 v112, v118, v118
	v_fmac_f32_e32 v113, v120, v120
	v_cndmask_b32_e32 v116, v150, v116, vcc
	v_add_f32_e32 v112, v112, v113
	v_lshlrev_b32_e32 v116, 2, v116
	v_add_f32_e32 v112, v122, v112
	ds_bpermute_b32 v113, v116, v112
	v_cmp_lt_i32_e32 vcc, v151, v117
	global_store_dwordx4 v[160:161], v[118:121], off offset:576 nt
	s_waitcnt lgkmcnt(0)
	v_add_f32_e32 v112, v112, v113
	v_cndmask_b32_e32 v114, v150, v151, vcc
	v_lshlrev_b32_e32 v114, 2, v114
	ds_bpermute_b32 v113, v114, v112
	v_cvt_pk_bf16_f32 v118, v118, v119
	v_cvt_pk_bf16_f32 v119, v120, v121
	v_lshl_add_u64 v[120:121], s[76:77], 0, v[162:163]
	global_store_dwordx2 v[120:121], v[118:119], off
	s_and_saveexec_b64 s[26:27], s[4:5]
	s_cbranch_execz .LBB0_1224
	v_lshlrev_b64 v[118:119], 6, v[142:143]
	v_lshl_add_u64 v[118:119], s[74:75], 0, v[118:119]
	v_lshl_add_u64 v[118:119], s[24:25], 2, v[118:119]
	s_lshl_b32 s14, s41, 2
	v_lshl_add_u64 v[118:119], v[118:119], 0, s[14:15]
	s_waitcnt lgkmcnt(0)
	v_add_f32_e32 v112, v112, v113
	global_store_dword v[118:119], v112, off
.LBB0_1224:
	s_or_b64 exec, exec, s[26:27]
	v_or_b32_e32 v112, 16, v142
	s_waitcnt lgkmcnt(0)
	v_ashrrev_i32_e32 v113, 31, v112
	v_lshlrev_b64 v[118:119], 10, v[112:113]
	v_lshl_add_u64 v[122:123], v[118:119], 0, v[140:141]
	v_lshl_add_u64 v[124:125], v[122:123], 2, s[12:13]
	global_load_dwordx4 v[118:121], v[124:125], off nt
	v_lshlrev_b64 v[122:123], 1, v[122:123]
	v_lshl_add_u64 v[126:127], s[76:77], 0, v[122:123]
	s_waitcnt vmcnt(0)
	v_pk_fma_f32 v[110:111], v[110:111], 0.5, v[120:121] op_sel_hi:[1,0,1]
	v_pk_fma_f32 v[108:109], v[108:109], 0.5, v[118:119] op_sel_hi:[1,0,1]
	global_store_dwordx4 v[124:125], v[108:111], off nt
	v_cvt_pk_bf16_f32 v118, v108, v109
	v_cvt_pk_bf16_f32 v119, v110, v111
	global_store_dwordx2 v[126:127], v[118:119], off
	global_load_dwordx4 v[118:121], v[124:125], off offset:64 nt
	v_or_b32_e32 v126, 32, v122
	v_mov_b32_e32 v127, v123
	v_lshl_add_u64 v[126:127], s[76:77], 0, v[126:127]
	v_mul_f32_e32 v109, v109, v109
	v_mul_f32_e32 v111, v111, v111
	v_fmac_f32_e32 v109, v108, v108
	v_fmac_f32_e32 v111, v110, v110
	v_add_f32_e32 v108, v109, v111
	s_waitcnt vmcnt(0)
	v_pk_fma_f32 v[106:107], v[106:107], 0.5, v[120:121] op_sel_hi:[1,0,1]
	v_pk_fma_f32 v[104:105], v[104:105], 0.5, v[118:119] op_sel_hi:[1,0,1]
	global_store_dwordx4 v[124:125], v[104:107], off offset:64 nt
	v_cvt_pk_bf16_f32 v118, v104, v105
	v_cvt_pk_bf16_f32 v119, v106, v107
	global_store_dwordx2 v[126:127], v[118:119], off
	global_load_dwordx4 v[118:121], v[124:125], off offset:512 nt
	v_or_b32_e32 v126, 0x100, v122
	v_mov_b32_e32 v127, v123
	v_lshl_add_u64 v[126:127], s[76:77], 0, v[126:127]
	v_mul_f32_e32 v105, v105, v105
	v_mul_f32_e32 v107, v107, v107
	v_fmac_f32_e32 v105, v104, v104
	v_fmac_f32_e32 v107, v106, v106
	v_add_f32_e32 v104, v105, v107
	v_add_f32_e32 v104, v108, v104
	v_or_b32_e32 v122, 0x120, v122
	s_waitcnt vmcnt(0)
	v_pk_fma_f32 v[102:103], v[102:103], 0.5, v[120:121] op_sel_hi:[1,0,1]
	v_pk_fma_f32 v[100:101], v[100:101], 0.5, v[118:119] op_sel_hi:[1,0,1]
	global_store_dwordx4 v[124:125], v[100:103], off offset:512 nt
	v_cvt_pk_bf16_f32 v118, v100, v101
	v_cvt_pk_bf16_f32 v119, v102, v103
	global_store_dwordx2 v[126:127], v[118:119], off
	global_load_dwordx4 v[118:121], v[124:125], off offset:576 nt
	v_mul_f32_e32 v101, v101, v101
	v_mul_f32_e32 v103, v103, v103
	v_fmac_f32_e32 v101, v100, v100
	v_fmac_f32_e32 v103, v102, v102
	v_add_f32_e32 v100, v101, v103
	v_add_f32_e32 v100, v104, v100
	s_waitcnt vmcnt(0)
	v_pk_fma_f32 v[98:99], v[98:99], 0.5, v[120:121] op_sel_hi:[1,0,1]
	v_pk_fma_f32 v[96:97], v[96:97], 0.5, v[118:119] op_sel_hi:[1,0,1]
	v_mul_f32_e32 v102, v99, v99
	v_mul_f32_e32 v101, v97, v97
	v_fmac_f32_e32 v101, v96, v96
	v_fmac_f32_e32 v102, v98, v98
	v_add_f32_e32 v101, v101, v102
	v_add_f32_e32 v101, v100, v101
	ds_bpermute_b32 v102, v116, v101
	global_store_dwordx4 v[124:125], v[96:99], off offset:576 nt
	v_cvt_pk_bf16_f32 v100, v96, v97
	s_waitcnt lgkmcnt(0)
	s_nop 0
	v_add_f32_e32 v96, v101, v102
	ds_bpermute_b32 v97, v114, v96
	v_cvt_pk_bf16_f32 v101, v98, v99
	v_lshl_add_u64 v[98:99], s[76:77], 0, v[122:123]
	global_store_dwordx2 v[98:99], v[100:101], off
	s_and_saveexec_b64 s[26:27], s[4:5]
	s_cbranch_execz .LBB0_1226
	v_lshlrev_b64 v[98:99], 6, v[112:113]
	v_lshl_add_u64 v[98:99], s[74:75], 0, v[98:99]
	v_lshl_add_u64 v[98:99], s[24:25], 2, v[98:99]
	s_lshl_b32 s14, s41, 2
	v_lshl_add_u64 v[98:99], v[98:99], 0, s[14:15]
	s_waitcnt lgkmcnt(0)
	v_add_f32_e32 v96, v96, v97
	global_store_dword v[98:99], v96, off
.LBB0_1226:
	s_or_b64 exec, exec, s[26:27]
	v_or_b32_e32 v96, 32, v142
	s_waitcnt lgkmcnt(0)
	v_ashrrev_i32_e32 v97, 31, v96
	v_lshlrev_b64 v[98:99], 10, v[96:97]
	v_lshl_add_u64 v[102:103], v[98:99], 0, v[140:141]
	v_lshl_add_u64 v[104:105], v[102:103], 2, s[12:13]
	global_load_dwordx4 v[98:101], v[104:105], off nt
	v_lshlrev_b64 v[102:103], 1, v[102:103]
	v_lshl_add_u64 v[106:107], s[76:77], 0, v[102:103]
	s_waitcnt vmcnt(0)
	v_pk_fma_f32 v[94:95], v[94:95], 0.5, v[100:101] op_sel_hi:[1,0,1]
	v_pk_fma_f32 v[92:93], v[92:93], 0.5, v[98:99] op_sel_hi:[1,0,1]
	global_store_dwordx4 v[104:105], v[92:95], off nt
	v_cvt_pk_bf16_f32 v98, v92, v93
	v_cvt_pk_bf16_f32 v99, v94, v95
	global_store_dwordx2 v[106:107], v[98:99], off
	global_load_dwordx4 v[98:101], v[104:105], off offset:64 nt
	v_or_b32_e32 v106, 32, v102
	v_mov_b32_e32 v107, v103
	v_lshl_add_u64 v[106:107], s[76:77], 0, v[106:107]
	v_mul_f32_e32 v93, v93, v93
	v_mul_f32_e32 v95, v95, v95
	v_fmac_f32_e32 v93, v92, v92
	v_fmac_f32_e32 v95, v94, v94
	v_add_f32_e32 v92, v93, v95
	s_waitcnt vmcnt(0)
	v_pk_fma_f32 v[90:91], v[90:91], 0.5, v[100:101] op_sel_hi:[1,0,1]
	v_pk_fma_f32 v[88:89], v[88:89], 0.5, v[98:99] op_sel_hi:[1,0,1]
	global_store_dwordx4 v[104:105], v[88:91], off offset:64 nt
	v_cvt_pk_bf16_f32 v98, v88, v89
	v_cvt_pk_bf16_f32 v99, v90, v91
	global_store_dwordx2 v[106:107], v[98:99], off
	global_load_dwordx4 v[98:101], v[104:105], off offset:512 nt
	v_or_b32_e32 v106, 0x100, v102
	v_mov_b32_e32 v107, v103
	v_lshl_add_u64 v[106:107], s[76:77], 0, v[106:107]
	v_mul_f32_e32 v89, v89, v89
	v_mul_f32_e32 v91, v91, v91
	v_fmac_f32_e32 v89, v88, v88
	v_fmac_f32_e32 v91, v90, v90
	v_add_f32_e32 v88, v89, v91
	v_add_f32_e32 v88, v92, v88
	v_or_b32_e32 v102, 0x120, v102
	s_waitcnt vmcnt(0)
	v_pk_fma_f32 v[86:87], v[86:87], 0.5, v[100:101] op_sel_hi:[1,0,1]
	v_pk_fma_f32 v[84:85], v[84:85], 0.5, v[98:99] op_sel_hi:[1,0,1]
	global_store_dwordx4 v[104:105], v[84:87], off offset:512 nt
	v_cvt_pk_bf16_f32 v98, v84, v85
	v_cvt_pk_bf16_f32 v99, v86, v87
	global_store_dwordx2 v[106:107], v[98:99], off
	global_load_dwordx4 v[98:101], v[104:105], off offset:576 nt
	v_mul_f32_e32 v85, v85, v85
	v_mul_f32_e32 v87, v87, v87
	v_fmac_f32_e32 v85, v84, v84
	v_fmac_f32_e32 v87, v86, v86
	v_add_f32_e32 v84, v85, v87
	v_add_f32_e32 v84, v88, v84
	s_waitcnt vmcnt(0)
	v_pk_fma_f32 v[82:83], v[82:83], 0.5, v[100:101] op_sel_hi:[1,0,1]
	v_pk_fma_f32 v[80:81], v[80:81], 0.5, v[98:99] op_sel_hi:[1,0,1]
	v_mul_f32_e32 v86, v83, v83
	v_mul_f32_e32 v85, v81, v81
	v_fmac_f32_e32 v85, v80, v80
	v_fmac_f32_e32 v86, v82, v82
	v_add_f32_e32 v85, v85, v86
	v_add_f32_e32 v85, v84, v85
	ds_bpermute_b32 v86, v116, v85
	global_store_dwordx4 v[104:105], v[80:83], off offset:576 nt
	v_cvt_pk_bf16_f32 v84, v80, v81
	s_waitcnt lgkmcnt(0)
	s_nop 0
	v_add_f32_e32 v80, v85, v86
	ds_bpermute_b32 v81, v114, v80
	v_cvt_pk_bf16_f32 v85, v82, v83
	v_lshl_add_u64 v[82:83], s[76:77], 0, v[102:103]
	global_store_dwordx2 v[82:83], v[84:85], off
	s_and_saveexec_b64 s[26:27], s[4:5]
	s_cbranch_execz .LBB0_1228
	v_lshlrev_b64 v[82:83], 6, v[96:97]
	v_lshl_add_u64 v[82:83], s[74:75], 0, v[82:83]
	v_lshl_add_u64 v[82:83], s[24:25], 2, v[82:83]
	s_lshl_b32 s14, s41, 2
	v_lshl_add_u64 v[82:83], v[82:83], 0, s[14:15]
	s_waitcnt lgkmcnt(0)
	v_add_f32_e32 v80, v80, v81
	global_store_dword v[82:83], v80, off
.LBB0_1228:
	s_or_b64 exec, exec, s[26:27]
	v_or_b32_e32 v80, 48, v142
	s_waitcnt lgkmcnt(0)
	v_ashrrev_i32_e32 v81, 31, v80
	v_lshlrev_b64 v[82:83], 10, v[80:81]
	v_lshl_add_u64 v[86:87], v[82:83], 0, v[140:141]
	v_lshl_add_u64 v[88:89], v[86:87], 2, s[12:13]
	global_load_dwordx4 v[82:85], v[88:89], off nt
	v_lshlrev_b64 v[86:87], 1, v[86:87]
	v_lshl_add_u64 v[90:91], s[76:77], 0, v[86:87]
	s_waitcnt vmcnt(0)
	v_pk_fma_f32 v[78:79], v[78:79], 0.5, v[84:85] op_sel_hi:[1,0,1]
	v_pk_fma_f32 v[76:77], v[76:77], 0.5, v[82:83] op_sel_hi:[1,0,1]
	global_store_dwordx4 v[88:89], v[76:79], off nt
	v_cvt_pk_bf16_f32 v82, v76, v77
	v_cvt_pk_bf16_f32 v83, v78, v79
	global_store_dwordx2 v[90:91], v[82:83], off
	global_load_dwordx4 v[82:85], v[88:89], off offset:64 nt
	v_or_b32_e32 v90, 32, v86
	v_mov_b32_e32 v91, v87
	v_lshl_add_u64 v[90:91], s[76:77], 0, v[90:91]
	v_mul_f32_e32 v77, v77, v77
	v_mul_f32_e32 v79, v79, v79
	v_fmac_f32_e32 v77, v76, v76
	v_fmac_f32_e32 v79, v78, v78
	v_add_f32_e32 v76, v77, v79
	s_waitcnt vmcnt(0)
	v_pk_fma_f32 v[74:75], v[74:75], 0.5, v[84:85] op_sel_hi:[1,0,1]
	v_pk_fma_f32 v[72:73], v[72:73], 0.5, v[82:83] op_sel_hi:[1,0,1]
	global_store_dwordx4 v[88:89], v[72:75], off offset:64 nt
	v_cvt_pk_bf16_f32 v82, v72, v73
	v_cvt_pk_bf16_f32 v83, v74, v75
	global_store_dwordx2 v[90:91], v[82:83], off
	global_load_dwordx4 v[82:85], v[88:89], off offset:512 nt
	v_or_b32_e32 v90, 0x100, v86
	v_mov_b32_e32 v91, v87
	v_lshl_add_u64 v[90:91], s[76:77], 0, v[90:91]
	v_mul_f32_e32 v73, v73, v73
	v_mul_f32_e32 v75, v75, v75
	v_fmac_f32_e32 v73, v72, v72
	v_fmac_f32_e32 v75, v74, v74
	v_add_f32_e32 v72, v73, v75
	v_add_f32_e32 v72, v76, v72
	v_or_b32_e32 v86, 0x120, v86
	s_waitcnt vmcnt(0)
	v_pk_fma_f32 v[70:71], v[70:71], 0.5, v[84:85] op_sel_hi:[1,0,1]
	v_pk_fma_f32 v[68:69], v[68:69], 0.5, v[82:83] op_sel_hi:[1,0,1]
	global_store_dwordx4 v[88:89], v[68:71], off offset:512 nt
	v_cvt_pk_bf16_f32 v82, v68, v69
	v_cvt_pk_bf16_f32 v83, v70, v71
	global_store_dwordx2 v[90:91], v[82:83], off
	global_load_dwordx4 v[82:85], v[88:89], off offset:576 nt
	v_mul_f32_e32 v69, v69, v69
	v_mul_f32_e32 v71, v71, v71
	v_fmac_f32_e32 v69, v68, v68
	v_fmac_f32_e32 v71, v70, v70
	v_add_f32_e32 v68, v69, v71
	v_add_f32_e32 v68, v72, v68
	s_waitcnt vmcnt(0)
	v_pk_fma_f32 v[66:67], v[66:67], 0.5, v[84:85] op_sel_hi:[1,0,1]
	v_pk_fma_f32 v[64:65], v[64:65], 0.5, v[82:83] op_sel_hi:[1,0,1]
	v_mul_f32_e32 v70, v67, v67
	v_mul_f32_e32 v69, v65, v65
	v_fmac_f32_e32 v69, v64, v64
	v_fmac_f32_e32 v70, v66, v66
	v_add_f32_e32 v69, v69, v70
	v_add_f32_e32 v69, v68, v69
	ds_bpermute_b32 v70, v116, v69
	global_store_dwordx4 v[88:89], v[64:67], off offset:576 nt
	v_cvt_pk_bf16_f32 v68, v64, v65
	s_waitcnt lgkmcnt(0)
	s_nop 0
	v_add_f32_e32 v64, v69, v70
	ds_bpermute_b32 v65, v114, v64
	v_cvt_pk_bf16_f32 v69, v66, v67
	v_lshl_add_u64 v[66:67], s[76:77], 0, v[86:87]
	global_store_dwordx2 v[66:67], v[68:69], off
	s_and_saveexec_b64 s[26:27], s[4:5]
	s_cbranch_execz .LBB0_1230
	v_lshlrev_b64 v[66:67], 6, v[80:81]
	v_lshl_add_u64 v[66:67], s[74:75], 0, v[66:67]
	v_lshl_add_u64 v[66:67], s[24:25], 2, v[66:67]
	s_lshl_b32 s14, s41, 2
	v_lshl_add_u64 v[66:67], v[66:67], 0, s[14:15]
	s_waitcnt lgkmcnt(0)
	v_add_f32_e32 v64, v64, v65
	global_store_dword v[66:67], v64, off
.LBB0_1230:
	s_or_b64 exec, exec, s[26:27]
	v_add_u32_e32 v64, 0x80, v142
	s_waitcnt lgkmcnt(0)
	v_ashrrev_i32_e32 v65, 31, v64
	v_lshlrev_b64 v[66:67], 10, v[64:65]
	v_lshl_add_u64 v[70:71], v[66:67], 0, v[140:141]
	v_lshl_add_u64 v[72:73], v[70:71], 2, s[12:13]
	global_load_dwordx4 v[66:69], v[72:73], off nt
	v_lshlrev_b64 v[70:71], 1, v[70:71]
	v_lshl_add_u64 v[74:75], s[76:77], 0, v[70:71]
	s_waitcnt vmcnt(0)
	v_pk_fma_f32 v[62:63], v[62:63], 0.5, v[68:69] op_sel_hi:[1,0,1]
	v_pk_fma_f32 v[60:61], v[60:61], 0.5, v[66:67] op_sel_hi:[1,0,1]
	global_store_dwordx4 v[72:73], v[60:63], off nt
	v_cvt_pk_bf16_f32 v66, v60, v61
	v_cvt_pk_bf16_f32 v67, v62, v63
	global_store_dwordx2 v[74:75], v[66:67], off
	global_load_dwordx4 v[66:69], v[72:73], off offset:64 nt
	v_or_b32_e32 v74, 32, v70
	v_mov_b32_e32 v75, v71
	v_lshl_add_u64 v[74:75], s[76:77], 0, v[74:75]
	v_mul_f32_e32 v61, v61, v61
	v_mul_f32_e32 v63, v63, v63
	v_fmac_f32_e32 v61, v60, v60
	v_fmac_f32_e32 v63, v62, v62
	v_add_f32_e32 v60, v61, v63
	s_waitcnt vmcnt(0)
	v_pk_fma_f32 v[58:59], v[58:59], 0.5, v[68:69] op_sel_hi:[1,0,1]
	v_pk_fma_f32 v[56:57], v[56:57], 0.5, v[66:67] op_sel_hi:[1,0,1]
	global_store_dwordx4 v[72:73], v[56:59], off offset:64 nt
	v_cvt_pk_bf16_f32 v66, v56, v57
	v_cvt_pk_bf16_f32 v67, v58, v59
	global_store_dwordx2 v[74:75], v[66:67], off
	global_load_dwordx4 v[66:69], v[72:73], off offset:512 nt
	v_or_b32_e32 v74, 0x100, v70
	v_mov_b32_e32 v75, v71
	v_lshl_add_u64 v[74:75], s[76:77], 0, v[74:75]
	v_mul_f32_e32 v57, v57, v57
	v_mul_f32_e32 v59, v59, v59
	v_fmac_f32_e32 v57, v56, v56
	v_fmac_f32_e32 v59, v58, v58
	v_add_f32_e32 v56, v57, v59
	v_add_f32_e32 v56, v60, v56
	v_or_b32_e32 v70, 0x120, v70
	s_waitcnt vmcnt(0)
	v_pk_fma_f32 v[54:55], v[54:55], 0.5, v[68:69] op_sel_hi:[1,0,1]
	v_pk_fma_f32 v[52:53], v[52:53], 0.5, v[66:67] op_sel_hi:[1,0,1]
	global_store_dwordx4 v[72:73], v[52:55], off offset:512 nt
	v_cvt_pk_bf16_f32 v66, v52, v53
	v_cvt_pk_bf16_f32 v67, v54, v55
	global_store_dwordx2 v[74:75], v[66:67], off
	global_load_dwordx4 v[66:69], v[72:73], off offset:576 nt
	v_mul_f32_e32 v53, v53, v53
	v_mul_f32_e32 v55, v55, v55
	v_fmac_f32_e32 v53, v52, v52
	v_fmac_f32_e32 v55, v54, v54
	v_add_f32_e32 v52, v53, v55
	v_add_f32_e32 v52, v56, v52
	s_waitcnt vmcnt(0)
	v_pk_fma_f32 v[50:51], v[50:51], 0.5, v[68:69] op_sel_hi:[1,0,1]
	v_pk_fma_f32 v[48:49], v[48:49], 0.5, v[66:67] op_sel_hi:[1,0,1]
	v_mul_f32_e32 v54, v51, v51
	v_mul_f32_e32 v53, v49, v49
	v_fmac_f32_e32 v53, v48, v48
	v_fmac_f32_e32 v54, v50, v50
	v_add_f32_e32 v53, v53, v54
	v_add_f32_e32 v53, v52, v53
	ds_bpermute_b32 v54, v116, v53
	global_store_dwordx4 v[72:73], v[48:51], off offset:576 nt
	v_cvt_pk_bf16_f32 v52, v48, v49
	s_waitcnt lgkmcnt(0)
	s_nop 0
	v_add_f32_e32 v48, v53, v54
	ds_bpermute_b32 v49, v114, v48
	v_cvt_pk_bf16_f32 v53, v50, v51
	v_lshl_add_u64 v[50:51], s[76:77], 0, v[70:71]
	global_store_dwordx2 v[50:51], v[52:53], off
	s_and_saveexec_b64 s[26:27], s[4:5]
	s_cbranch_execz .LBB0_1232
	v_lshlrev_b64 v[50:51], 6, v[64:65]
	v_lshl_add_u64 v[50:51], s[74:75], 0, v[50:51]
	v_lshl_add_u64 v[50:51], s[24:25], 2, v[50:51]
	s_lshl_b32 s14, s41, 2
	v_lshl_add_u64 v[50:51], v[50:51], 0, s[14:15]
	s_waitcnt lgkmcnt(0)
	v_add_f32_e32 v48, v48, v49
	global_store_dword v[50:51], v48, off
.LBB0_1232:
	s_or_b64 exec, exec, s[26:27]
	v_add_u32_e32 v48, 0x90, v142
	s_waitcnt lgkmcnt(0)
	v_ashrrev_i32_e32 v49, 31, v48
	v_lshlrev_b64 v[50:51], 10, v[48:49]
	v_lshl_add_u64 v[54:55], v[50:51], 0, v[140:141]
	v_lshl_add_u64 v[56:57], v[54:55], 2, s[12:13]
	global_load_dwordx4 v[50:53], v[56:57], off nt
	v_lshlrev_b64 v[54:55], 1, v[54:55]
	v_lshl_add_u64 v[58:59], s[76:77], 0, v[54:55]
	s_waitcnt vmcnt(0)
	v_pk_fma_f32 v[46:47], v[46:47], 0.5, v[52:53] op_sel_hi:[1,0,1]
	v_pk_fma_f32 v[44:45], v[44:45], 0.5, v[50:51] op_sel_hi:[1,0,1]
	global_store_dwordx4 v[56:57], v[44:47], off nt
	v_cvt_pk_bf16_f32 v50, v44, v45
	v_cvt_pk_bf16_f32 v51, v46, v47
	global_store_dwordx2 v[58:59], v[50:51], off
	global_load_dwordx4 v[50:53], v[56:57], off offset:64 nt
	v_or_b32_e32 v58, 32, v54
	v_mov_b32_e32 v59, v55
	v_lshl_add_u64 v[58:59], s[76:77], 0, v[58:59]
	v_mul_f32_e32 v45, v45, v45
	v_mul_f32_e32 v47, v47, v47
	v_fmac_f32_e32 v45, v44, v44
	v_fmac_f32_e32 v47, v46, v46
	v_add_f32_e32 v44, v45, v47
	s_waitcnt vmcnt(0)
	v_pk_fma_f32 v[42:43], v[42:43], 0.5, v[52:53] op_sel_hi:[1,0,1]
	v_pk_fma_f32 v[40:41], v[40:41], 0.5, v[50:51] op_sel_hi:[1,0,1]
	global_store_dwordx4 v[56:57], v[40:43], off offset:64 nt
	v_cvt_pk_bf16_f32 v50, v40, v41
	v_cvt_pk_bf16_f32 v51, v42, v43
	global_store_dwordx2 v[58:59], v[50:51], off
	global_load_dwordx4 v[50:53], v[56:57], off offset:512 nt
	v_or_b32_e32 v58, 0x100, v54
	v_mov_b32_e32 v59, v55
	v_lshl_add_u64 v[58:59], s[76:77], 0, v[58:59]
	v_mul_f32_e32 v41, v41, v41
	v_mul_f32_e32 v43, v43, v43
	v_fmac_f32_e32 v41, v40, v40
	v_fmac_f32_e32 v43, v42, v42
	v_add_f32_e32 v40, v41, v43
	v_add_f32_e32 v40, v44, v40
	v_or_b32_e32 v54, 0x120, v54
	s_waitcnt vmcnt(0)
	v_pk_fma_f32 v[38:39], v[38:39], 0.5, v[52:53] op_sel_hi:[1,0,1]
	v_pk_fma_f32 v[36:37], v[36:37], 0.5, v[50:51] op_sel_hi:[1,0,1]
	global_store_dwordx4 v[56:57], v[36:39], off offset:512 nt
	v_cvt_pk_bf16_f32 v50, v36, v37
	v_cvt_pk_bf16_f32 v51, v38, v39
	global_store_dwordx2 v[58:59], v[50:51], off
	global_load_dwordx4 v[50:53], v[56:57], off offset:576 nt
	v_mul_f32_e32 v37, v37, v37
	v_mul_f32_e32 v39, v39, v39
	v_fmac_f32_e32 v37, v36, v36
	v_fmac_f32_e32 v39, v38, v38
	v_add_f32_e32 v36, v37, v39
	v_add_f32_e32 v36, v40, v36
	s_waitcnt vmcnt(0)
	v_pk_fma_f32 v[34:35], v[34:35], 0.5, v[52:53] op_sel_hi:[1,0,1]
	v_pk_fma_f32 v[32:33], v[32:33], 0.5, v[50:51] op_sel_hi:[1,0,1]
	v_mul_f32_e32 v38, v35, v35
	v_mul_f32_e32 v37, v33, v33
	v_fmac_f32_e32 v37, v32, v32
	v_fmac_f32_e32 v38, v34, v34
	v_add_f32_e32 v37, v37, v38
	v_add_f32_e32 v37, v36, v37
	ds_bpermute_b32 v38, v116, v37
	global_store_dwordx4 v[56:57], v[32:35], off offset:576 nt
	v_cvt_pk_bf16_f32 v36, v32, v33
	s_waitcnt lgkmcnt(0)
	s_nop 0
	v_add_f32_e32 v32, v37, v38
	ds_bpermute_b32 v33, v114, v32
	v_cvt_pk_bf16_f32 v37, v34, v35
	v_lshl_add_u64 v[34:35], s[76:77], 0, v[54:55]
	global_store_dwordx2 v[34:35], v[36:37], off
	s_and_saveexec_b64 s[26:27], s[4:5]
	s_cbranch_execz .LBB0_1234
	v_lshlrev_b64 v[34:35], 6, v[48:49]
	v_lshl_add_u64 v[34:35], s[74:75], 0, v[34:35]
	v_lshl_add_u64 v[34:35], s[24:25], 2, v[34:35]
	s_lshl_b32 s14, s41, 2
	v_lshl_add_u64 v[34:35], v[34:35], 0, s[14:15]
	s_waitcnt lgkmcnt(0)
	v_add_f32_e32 v32, v32, v33
	global_store_dword v[34:35], v32, off
.LBB0_1234:
	s_or_b64 exec, exec, s[26:27]
	v_add_u32_e32 v32, 0xa0, v142
	s_waitcnt lgkmcnt(0)
	v_ashrrev_i32_e32 v33, 31, v32
	v_lshlrev_b64 v[34:35], 10, v[32:33]
	v_lshl_add_u64 v[38:39], v[34:35], 0, v[140:141]
	v_lshl_add_u64 v[40:41], v[38:39], 2, s[12:13]
	global_load_dwordx4 v[34:37], v[40:41], off nt
	v_lshlrev_b64 v[38:39], 1, v[38:39]
	v_lshl_add_u64 v[42:43], s[76:77], 0, v[38:39]
	s_waitcnt vmcnt(0)
	v_pk_fma_f32 v[30:31], v[30:31], 0.5, v[36:37] op_sel_hi:[1,0,1]
	v_pk_fma_f32 v[28:29], v[28:29], 0.5, v[34:35] op_sel_hi:[1,0,1]
	global_store_dwordx4 v[40:41], v[28:31], off nt
	v_cvt_pk_bf16_f32 v34, v28, v29
	v_cvt_pk_bf16_f32 v35, v30, v31
	global_store_dwordx2 v[42:43], v[34:35], off
	global_load_dwordx4 v[34:37], v[40:41], off offset:64 nt
	v_or_b32_e32 v42, 32, v38
	v_mov_b32_e32 v43, v39
	v_lshl_add_u64 v[42:43], s[76:77], 0, v[42:43]
	v_mul_f32_e32 v29, v29, v29
	v_mul_f32_e32 v31, v31, v31
	v_fmac_f32_e32 v29, v28, v28
	v_fmac_f32_e32 v31, v30, v30
	v_add_f32_e32 v28, v29, v31
	s_waitcnt vmcnt(0)
	v_pk_fma_f32 v[26:27], v[26:27], 0.5, v[36:37] op_sel_hi:[1,0,1]
	v_pk_fma_f32 v[24:25], v[24:25], 0.5, v[34:35] op_sel_hi:[1,0,1]
	global_store_dwordx4 v[40:41], v[24:27], off offset:64 nt
	v_cvt_pk_bf16_f32 v34, v24, v25
	v_cvt_pk_bf16_f32 v35, v26, v27
	global_store_dwordx2 v[42:43], v[34:35], off
	global_load_dwordx4 v[34:37], v[40:41], off offset:512 nt
	v_or_b32_e32 v42, 0x100, v38
	v_mov_b32_e32 v43, v39
	v_lshl_add_u64 v[42:43], s[76:77], 0, v[42:43]
	v_mul_f32_e32 v25, v25, v25
	v_mul_f32_e32 v27, v27, v27
	v_fmac_f32_e32 v25, v24, v24
	v_fmac_f32_e32 v27, v26, v26
	v_add_f32_e32 v24, v25, v27
	v_add_f32_e32 v24, v28, v24
	v_or_b32_e32 v38, 0x120, v38
	s_waitcnt vmcnt(0)
	v_pk_fma_f32 v[22:23], v[22:23], 0.5, v[36:37] op_sel_hi:[1,0,1]
	v_pk_fma_f32 v[20:21], v[20:21], 0.5, v[34:35] op_sel_hi:[1,0,1]
	global_store_dwordx4 v[40:41], v[20:23], off offset:512 nt
	v_cvt_pk_bf16_f32 v34, v20, v21
	v_cvt_pk_bf16_f32 v35, v22, v23
	global_store_dwordx2 v[42:43], v[34:35], off
	global_load_dwordx4 v[34:37], v[40:41], off offset:576 nt
	v_mul_f32_e32 v21, v21, v21
	v_mul_f32_e32 v23, v23, v23
	v_fmac_f32_e32 v21, v20, v20
	v_fmac_f32_e32 v23, v22, v22
	v_add_f32_e32 v20, v21, v23
	v_add_f32_e32 v20, v24, v20
	s_waitcnt vmcnt(0)
	v_pk_fma_f32 v[18:19], v[18:19], 0.5, v[36:37] op_sel_hi:[1,0,1]
	v_pk_fma_f32 v[16:17], v[16:17], 0.5, v[34:35] op_sel_hi:[1,0,1]
	v_mul_f32_e32 v22, v19, v19
	v_mul_f32_e32 v21, v17, v17
	v_fmac_f32_e32 v21, v16, v16
	v_fmac_f32_e32 v22, v18, v18
	v_add_f32_e32 v21, v21, v22
	v_add_f32_e32 v21, v20, v21
	ds_bpermute_b32 v22, v116, v21
	global_store_dwordx4 v[40:41], v[16:19], off offset:576 nt
	v_cvt_pk_bf16_f32 v20, v16, v17
	s_waitcnt lgkmcnt(0)
	s_nop 0
	v_add_f32_e32 v16, v21, v22
	ds_bpermute_b32 v17, v114, v16
	v_cvt_pk_bf16_f32 v21, v18, v19
	v_lshl_add_u64 v[18:19], s[76:77], 0, v[38:39]
	global_store_dwordx2 v[18:19], v[20:21], off
	s_and_saveexec_b64 s[26:27], s[4:5]
	s_cbranch_execz .LBB0_1236
	v_lshlrev_b64 v[18:19], 6, v[32:33]
	v_lshl_add_u64 v[18:19], s[74:75], 0, v[18:19]
	v_lshl_add_u64 v[18:19], s[24:25], 2, v[18:19]
	s_lshl_b32 s14, s41, 2
	v_lshl_add_u64 v[18:19], v[18:19], 0, s[14:15]
	s_waitcnt lgkmcnt(0)
	v_add_f32_e32 v16, v16, v17
	global_store_dword v[18:19], v16, off
.LBB0_1236:
	s_or_b64 exec, exec, s[26:27]
	v_add_u32_e32 v16, 0xb0, v142
	s_waitcnt lgkmcnt(0)
	v_ashrrev_i32_e32 v17, 31, v16
	v_lshlrev_b64 v[18:19], 10, v[16:17]
	v_lshl_add_u64 v[22:23], v[18:19], 0, v[140:141]
	v_lshl_add_u64 v[24:25], v[22:23], 2, s[12:13]
	global_load_dwordx4 v[18:21], v[24:25], off nt
	v_lshlrev_b64 v[22:23], 1, v[22:23]
	v_lshl_add_u64 v[26:27], s[76:77], 0, v[22:23]
	s_waitcnt vmcnt(0)
	v_pk_fma_f32 v[14:15], v[14:15], 0.5, v[20:21] op_sel_hi:[1,0,1]
	v_pk_fma_f32 v[12:13], v[12:13], 0.5, v[18:19] op_sel_hi:[1,0,1]
	global_store_dwordx4 v[24:25], v[12:15], off nt
	v_cvt_pk_bf16_f32 v18, v12, v13
	v_cvt_pk_bf16_f32 v19, v14, v15
	global_store_dwordx2 v[26:27], v[18:19], off
	global_load_dwordx4 v[18:21], v[24:25], off offset:64 nt
	v_or_b32_e32 v26, 32, v22
	v_mov_b32_e32 v27, v23
	v_lshl_add_u64 v[26:27], s[76:77], 0, v[26:27]
	v_mul_f32_e32 v13, v13, v13
	v_mul_f32_e32 v15, v15, v15
	v_fmac_f32_e32 v13, v12, v12
	v_fmac_f32_e32 v15, v14, v14
	v_add_f32_e32 v12, v13, v15
	s_waitcnt vmcnt(0)
	v_pk_fma_f32 v[10:11], v[10:11], 0.5, v[20:21] op_sel_hi:[1,0,1]
	v_pk_fma_f32 v[8:9], v[8:9], 0.5, v[18:19] op_sel_hi:[1,0,1]
	global_store_dwordx4 v[24:25], v[8:11], off offset:64 nt
	v_cvt_pk_bf16_f32 v18, v8, v9
	v_cvt_pk_bf16_f32 v19, v10, v11
	global_store_dwordx2 v[26:27], v[18:19], off
	global_load_dwordx4 v[18:21], v[24:25], off offset:512 nt
	v_or_b32_e32 v26, 0x100, v22
	v_mov_b32_e32 v27, v23
	v_lshl_add_u64 v[26:27], s[76:77], 0, v[26:27]
	v_mul_f32_e32 v9, v9, v9
	v_mul_f32_e32 v11, v11, v11
	v_fmac_f32_e32 v9, v8, v8
	v_fmac_f32_e32 v11, v10, v10
	v_add_f32_e32 v8, v9, v11
	v_add_f32_e32 v8, v12, v8
	v_or_b32_e32 v22, 0x120, v22
	s_waitcnt vmcnt(0)
	v_pk_fma_f32 v[6:7], v[6:7], 0.5, v[20:21] op_sel_hi:[1,0,1]
	v_pk_fma_f32 v[4:5], v[4:5], 0.5, v[18:19] op_sel_hi:[1,0,1]
	global_store_dwordx4 v[24:25], v[4:7], off offset:512 nt
	v_cvt_pk_bf16_f32 v18, v4, v5
	v_cvt_pk_bf16_f32 v19, v6, v7
	global_store_dwordx2 v[26:27], v[18:19], off
	global_load_dwordx4 v[18:21], v[24:25], off offset:576 nt
	v_mul_f32_e32 v5, v5, v5
	v_mul_f32_e32 v7, v7, v7
	v_fmac_f32_e32 v5, v4, v4
	v_fmac_f32_e32 v7, v6, v6
	v_add_f32_e32 v4, v5, v7
	v_add_f32_e32 v4, v8, v4
	s_waitcnt vmcnt(0)
	v_pk_fma_f32 v[2:3], v[2:3], 0.5, v[20:21] op_sel_hi:[1,0,1]
	v_pk_fma_f32 v[0:1], v[0:1], 0.5, v[18:19] op_sel_hi:[1,0,1]
	v_mul_f32_e32 v6, v3, v3
	v_mul_f32_e32 v5, v1, v1
	v_fmac_f32_e32 v5, v0, v0
	v_fmac_f32_e32 v6, v2, v2
	v_add_f32_e32 v5, v5, v6
	v_add_f32_e32 v5, v4, v5
	ds_bpermute_b32 v6, v116, v5
	global_store_dwordx4 v[24:25], v[0:3], off offset:576 nt
	v_cvt_pk_bf16_f32 v4, v0, v1
	s_waitcnt lgkmcnt(0)
	s_nop 0
	v_add_f32_e32 v0, v5, v6
	ds_bpermute_b32 v1, v114, v0
	v_cvt_pk_bf16_f32 v5, v2, v3
	v_lshl_add_u64 v[2:3], s[76:77], 0, v[22:23]
	global_store_dwordx2 v[2:3], v[4:5], off
	s_and_saveexec_b64 s[26:27], s[4:5]
	s_cbranch_execz .LBB0_1238
	v_lshlrev_b64 v[2:3], 6, v[16:17]
	v_lshl_add_u64 v[2:3], s[74:75], 0, v[2:3]
	v_lshl_add_u64 v[2:3], s[24:25], 2, v[2:3]
	s_lshl_b32 s14, s41, 2
	v_lshl_add_u64 v[2:3], v[2:3], 0, s[14:15]
	s_waitcnt lgkmcnt(0)
	v_add_f32_e32 v0, v0, v1
	global_store_dword v[2:3], v0, off

.LBB0_1556:
	v_lshl_add_u32 v142, s24, 8, v144
	v_lshl_or_b32 v140, s8, 8, v146
	v_ashrrev_i32_e32 v143, 31, v142
	v_ashrrev_i32_e32 v141, 31, v140
	v_lshlrev_b64 v[152:153], 10, v[142:143]
	v_lshl_add_u64 v[156:157], v[152:153], 0, v[140:141]
	v_lshl_add_u64 v[160:161], v[156:157], 2, s[6:7]
	global_load_dwordx4 v[152:155], v[160:161], off nt
	v_lshlrev_b64 v[162:163], 1, v[156:157]
	v_lshl_add_u64 v[156:157], s[76:77], 0, v[162:163]
	v_xor_b32_e32 v151, 32, v150
	s_lshl_b32 s24, s8, 2
	s_ashr_i32 s25, s24, 31
	s_waitcnt vmcnt(0)
	v_pk_add_f32 v[126:127], v[126:127], v[154:155]
	v_pk_add_f32 v[124:125], v[124:125], v[152:153]
	global_store_dwordx4 v[160:161], v[124:127], off nt
	v_cvt_pk_bf16_f32 v152, v124, v125
	v_cvt_pk_bf16_f32 v153, v126, v127
	global_store_dwordx2 v[156:157], v[152:153], off
	global_load_dwordx4 v[152:155], v[160:161], off offset:64 nt
	v_or_b32_e32 v156, 32, v162
	v_mov_b32_e32 v157, v163
	v_lshl_add_u64 v[156:157], s[76:77], 0, v[156:157]
	s_waitcnt vmcnt(0)
	v_pk_add_f32 v[122:123], v[122:123], v[154:155]
	v_pk_add_f32 v[120:121], v[120:121], v[152:153]
	global_store_dwordx4 v[160:161], v[120:123], off offset:64 nt
	v_cvt_pk_bf16_f32 v152, v120, v121
	v_cvt_pk_bf16_f32 v153, v122, v123
	global_store_dwordx2 v[156:157], v[152:153], off
	global_load_dwordx4 v[152:155], v[160:161], off offset:512 nt
	v_or_b32_e32 v156, 0x100, v162
	v_mov_b32_e32 v157, v163
	v_lshl_add_u64 v[156:157], s[76:77], 0, v[156:157]
	v_or_b32_e32 v162, 0x120, v162
	s_waitcnt vmcnt(0)
	v_pk_add_f32 v[154:155], v[118:119], v[154:155]
	v_pk_add_f32 v[152:153], v[116:117], v[152:153]
	global_store_dwordx4 v[160:161], v[152:155], off offset:512 nt
	v_cvt_pk_bf16_f32 v116, v152, v153
	v_cvt_pk_bf16_f32 v117, v154, v155
	global_store_dwordx2 v[156:157], v[116:117], off
	global_load_dwordx4 v[156:159], v[160:161], off offset:576 nt
	v_mul_f32_e32 v118, v125, v125
	v_mul_f32_e32 v119, v127, v127
	v_fmac_f32_e32 v118, v124, v124
	v_fmac_f32_e32 v119, v126, v126
	v_add_f32_e32 v118, v118, v119
	v_mul_f32_e32 v119, v121, v121
	v_mul_f32_e32 v121, v123, v123
	v_fmac_f32_e32 v119, v120, v120
	v_fmac_f32_e32 v121, v122, v122
	v_add_f32_e32 v119, v119, v121
	v_add_f32_e32 v118, v118, v119
	v_mul_f32_e32 v119, v153, v153
	v_mul_f32_e32 v120, v155, v155
	v_fmac_f32_e32 v119, v152, v152
	v_fmac_f32_e32 v120, v154, v154
	v_add_f32_e32 v119, v119, v120
	v_and_b32_e32 v117, 64, v150
	v_add_f32_e32 v122, v118, v119
	v_xor_b32_e32 v116, 16, v150
	v_add_u32_e32 v117, 64, v117
	v_cmp_lt_i32_e32 vcc, v116, v117
	s_waitcnt vmcnt(0)
	v_pk_add_f32 v[120:121], v[114:115], v[158:159]
	v_pk_add_f32 v[118:119], v[112:113], v[156:157]
	v_mul_f32_e32 v113, v121, v121
	v_mul_f32_e32 v112, v119, v119
	v_fmac_f32_e32 v112, v118, v118
	v_fmac_f32_e32 v113, v120, v120
	v_cndmask_b32_e32 v116, v150, v116, vcc
	v_add_f32_e32 v112, v112, v113
	v_lshlrev_b32_e32 v116, 2, v116
	v_add_f32_e32 v112, v122, v112
	ds_bpermute_b32 v113, v116, v112
	v_cmp_lt_i32_e32 vcc, v151, v117
	global_store_dwordx4 v[160:161], v[118:121], off offset:576 nt
	s_waitcnt lgkmcnt(0)
	v_add_f32_e32 v112, v112, v113
	v_cndmask_b32_e32 v114, v150, v151, vcc
	v_lshlrev_b32_e32 v114, 2, v114
	ds_bpermute_b32 v113, v114, v112
	v_cvt_pk_bf16_f32 v118, v118, v119
	v_cvt_pk_bf16_f32 v119, v120, v121
	v_lshl_add_u64 v[120:121], s[76:77], 0, v[162:163]
	global_store_dwordx2 v[120:121], v[118:119], off
	s_and_saveexec_b64 s[26:27], s[2:3]
	s_cbranch_execz .LBB0_1558
	v_lshlrev_b64 v[118:119], 6, v[142:143]
	v_lshl_add_u64 v[118:119], s[74:75], 0, v[118:119]
	v_lshl_add_u64 v[118:119], s[24:25], 2, v[118:119]
	s_lshl_b32 s8, s43, 2
	v_lshl_add_u64 v[118:119], v[118:119], 0, s[8:9]
	s_waitcnt lgkmcnt(0)
	v_add_f32_e32 v112, v112, v113
	global_store_dword v[118:119], v112, off
.LBB0_1558:
	s_or_b64 exec, exec, s[26:27]
	v_or_b32_e32 v112, 16, v142
	s_waitcnt lgkmcnt(0)
	v_ashrrev_i32_e32 v113, 31, v112
	v_lshlrev_b64 v[118:119], 10, v[112:113]
	v_lshl_add_u64 v[122:123], v[118:119], 0, v[140:141]
	v_lshl_add_u64 v[124:125], v[122:123], 2, s[6:7]
	global_load_dwordx4 v[118:121], v[124:125], off nt
	v_lshlrev_b64 v[122:123], 1, v[122:123]
	v_lshl_add_u64 v[126:127], s[76:77], 0, v[122:123]
	s_waitcnt vmcnt(0)
	v_pk_add_f32 v[110:111], v[110:111], v[120:121]
	v_pk_add_f32 v[108:109], v[108:109], v[118:119]
	global_store_dwordx4 v[124:125], v[108:111], off nt
	v_cvt_pk_bf16_f32 v118, v108, v109
	v_cvt_pk_bf16_f32 v119, v110, v111
	global_store_dwordx2 v[126:127], v[118:119], off
	global_load_dwordx4 v[118:121], v[124:125], off offset:64 nt
	v_or_b32_e32 v126, 32, v122
	v_mov_b32_e32 v127, v123
	v_lshl_add_u64 v[126:127], s[76:77], 0, v[126:127]
	v_mul_f32_e32 v109, v109, v109
	v_mul_f32_e32 v111, v111, v111
	v_fmac_f32_e32 v109, v108, v108
	v_fmac_f32_e32 v111, v110, v110
	v_add_f32_e32 v108, v109, v111
	s_waitcnt vmcnt(0)
	v_pk_add_f32 v[106:107], v[106:107], v[120:121]
	v_pk_add_f32 v[104:105], v[104:105], v[118:119]
	global_store_dwordx4 v[124:125], v[104:107], off offset:64 nt
	v_cvt_pk_bf16_f32 v118, v104, v105
	v_cvt_pk_bf16_f32 v119, v106, v107
	global_store_dwordx2 v[126:127], v[118:119], off
	global_load_dwordx4 v[118:121], v[124:125], off offset:512 nt
	v_or_b32_e32 v126, 0x100, v122
	v_mov_b32_e32 v127, v123
	v_lshl_add_u64 v[126:127], s[76:77], 0, v[126:127]
	v_mul_f32_e32 v105, v105, v105
	v_mul_f32_e32 v107, v107, v107
	v_fmac_f32_e32 v105, v104, v104
	v_fmac_f32_e32 v107, v106, v106
	v_add_f32_e32 v104, v105, v107
	v_add_f32_e32 v104, v108, v104
	v_or_b32_e32 v122, 0x120, v122
	s_waitcnt vmcnt(0)
	v_pk_add_f32 v[102:103], v[102:103], v[120:121]
	v_pk_add_f32 v[100:101], v[100:101], v[118:119]
	global_store_dwordx4 v[124:125], v[100:103], off offset:512 nt
	v_cvt_pk_bf16_f32 v118, v100, v101
	v_cvt_pk_bf16_f32 v119, v102, v103
	global_store_dwordx2 v[126:127], v[118:119], off
	global_load_dwordx4 v[118:121], v[124:125], off offset:576 nt
	v_mul_f32_e32 v101, v101, v101
	v_mul_f32_e32 v103, v103, v103
	v_fmac_f32_e32 v101, v100, v100
	v_fmac_f32_e32 v103, v102, v102
	v_add_f32_e32 v100, v101, v103
	v_add_f32_e32 v100, v104, v100
	s_waitcnt vmcnt(0)
	v_pk_add_f32 v[98:99], v[98:99], v[120:121]
	v_pk_add_f32 v[96:97], v[96:97], v[118:119]
	v_mul_f32_e32 v102, v99, v99
	v_mul_f32_e32 v101, v97, v97
	v_fmac_f32_e32 v101, v96, v96
	v_fmac_f32_e32 v102, v98, v98
	v_add_f32_e32 v101, v101, v102
	v_add_f32_e32 v101, v100, v101
	ds_bpermute_b32 v102, v116, v101
	global_store_dwordx4 v[124:125], v[96:99], off offset:576 nt
	v_cvt_pk_bf16_f32 v100, v96, v97
	s_waitcnt lgkmcnt(0)
	s_nop 0
	v_add_f32_e32 v96, v101, v102
	ds_bpermute_b32 v97, v114, v96
	v_cvt_pk_bf16_f32 v101, v98, v99
	v_lshl_add_u64 v[98:99], s[76:77], 0, v[122:123]
	global_store_dwordx2 v[98:99], v[100:101], off
	s_and_saveexec_b64 s[26:27], s[2:3]
	s_cbranch_execz .LBB0_1560
	v_lshlrev_b64 v[98:99], 6, v[112:113]
	v_lshl_add_u64 v[98:99], s[74:75], 0, v[98:99]
	v_lshl_add_u64 v[98:99], s[24:25], 2, v[98:99]
	s_lshl_b32 s8, s43, 2
	v_lshl_add_u64 v[98:99], v[98:99], 0, s[8:9]
	s_waitcnt lgkmcnt(0)
	v_add_f32_e32 v96, v96, v97
	global_store_dword v[98:99], v96, off
.LBB0_1560:
	s_or_b64 exec, exec, s[26:27]
	v_or_b32_e32 v96, 32, v142
	s_waitcnt lgkmcnt(0)
	v_ashrrev_i32_e32 v97, 31, v96
	v_lshlrev_b64 v[98:99], 10, v[96:97]
	v_lshl_add_u64 v[102:103], v[98:99], 0, v[140:141]
	v_lshl_add_u64 v[104:105], v[102:103], 2, s[6:7]
	global_load_dwordx4 v[98:101], v[104:105], off nt
	v_lshlrev_b64 v[102:103], 1, v[102:103]
	v_lshl_add_u64 v[106:107], s[76:77], 0, v[102:103]
	s_waitcnt vmcnt(0)
	v_pk_add_f32 v[94:95], v[94:95], v[100:101]
	v_pk_add_f32 v[92:93], v[92:93], v[98:99]
	global_store_dwordx4 v[104:105], v[92:95], off nt
	v_cvt_pk_bf16_f32 v98, v92, v93
	v_cvt_pk_bf16_f32 v99, v94, v95
	global_store_dwordx2 v[106:107], v[98:99], off
	global_load_dwordx4 v[98:101], v[104:105], off offset:64 nt
	v_or_b32_e32 v106, 32, v102
	v_mov_b32_e32 v107, v103
	v_lshl_add_u64 v[106:107], s[76:77], 0, v[106:107]
	v_mul_f32_e32 v93, v93, v93
	v_mul_f32_e32 v95, v95, v95
	v_fmac_f32_e32 v93, v92, v92
	v_fmac_f32_e32 v95, v94, v94
	v_add_f32_e32 v92, v93, v95
	s_waitcnt vmcnt(0)
	v_pk_add_f32 v[90:91], v[90:91], v[100:101]
	v_pk_add_f32 v[88:89], v[88:89], v[98:99]
	global_store_dwordx4 v[104:105], v[88:91], off offset:64 nt
	v_cvt_pk_bf16_f32 v98, v88, v89
	v_cvt_pk_bf16_f32 v99, v90, v91
	global_store_dwordx2 v[106:107], v[98:99], off
	global_load_dwordx4 v[98:101], v[104:105], off offset:512 nt
	v_or_b32_e32 v106, 0x100, v102
	v_mov_b32_e32 v107, v103
	v_lshl_add_u64 v[106:107], s[76:77], 0, v[106:107]
	v_mul_f32_e32 v89, v89, v89
	v_mul_f32_e32 v91, v91, v91
	v_fmac_f32_e32 v89, v88, v88
	v_fmac_f32_e32 v91, v90, v90
	v_add_f32_e32 v88, v89, v91
	v_add_f32_e32 v88, v92, v88
	v_or_b32_e32 v102, 0x120, v102
	s_waitcnt vmcnt(0)
	v_pk_add_f32 v[86:87], v[86:87], v[100:101]
	v_pk_add_f32 v[84:85], v[84:85], v[98:99]
	global_store_dwordx4 v[104:105], v[84:87], off offset:512 nt
	v_cvt_pk_bf16_f32 v98, v84, v85
	v_cvt_pk_bf16_f32 v99, v86, v87
	global_store_dwordx2 v[106:107], v[98:99], off
	global_load_dwordx4 v[98:101], v[104:105], off offset:576 nt
	v_mul_f32_e32 v85, v85, v85
	v_mul_f32_e32 v87, v87, v87
	v_fmac_f32_e32 v85, v84, v84
	v_fmac_f32_e32 v87, v86, v86
	v_add_f32_e32 v84, v85, v87
	v_add_f32_e32 v84, v88, v84
	s_waitcnt vmcnt(0)
	v_pk_add_f32 v[82:83], v[82:83], v[100:101]
	v_pk_add_f32 v[80:81], v[80:81], v[98:99]
	v_mul_f32_e32 v86, v83, v83
	v_mul_f32_e32 v85, v81, v81
	v_fmac_f32_e32 v85, v80, v80
	v_fmac_f32_e32 v86, v82, v82
	v_add_f32_e32 v85, v85, v86
	v_add_f32_e32 v85, v84, v85
	ds_bpermute_b32 v86, v116, v85
	global_store_dwordx4 v[104:105], v[80:83], off offset:576 nt
	v_cvt_pk_bf16_f32 v84, v80, v81
	s_waitcnt lgkmcnt(0)
	s_nop 0
	v_add_f32_e32 v80, v85, v86
	ds_bpermute_b32 v81, v114, v80
	v_cvt_pk_bf16_f32 v85, v82, v83
	v_lshl_add_u64 v[82:83], s[76:77], 0, v[102:103]
	global_store_dwordx2 v[82:83], v[84:85], off
	s_and_saveexec_b64 s[26:27], s[2:3]
	s_cbranch_execz .LBB0_1562
	v_lshlrev_b64 v[82:83], 6, v[96:97]
	v_lshl_add_u64 v[82:83], s[74:75], 0, v[82:83]
	v_lshl_add_u64 v[82:83], s[24:25], 2, v[82:83]
	s_lshl_b32 s8, s43, 2
	v_lshl_add_u64 v[82:83], v[82:83], 0, s[8:9]
	s_waitcnt lgkmcnt(0)
	v_add_f32_e32 v80, v80, v81
	global_store_dword v[82:83], v80, off
.LBB0_1562:
	s_or_b64 exec, exec, s[26:27]
	v_or_b32_e32 v80, 48, v142
	s_waitcnt lgkmcnt(0)
	v_ashrrev_i32_e32 v81, 31, v80
	v_lshlrev_b64 v[82:83], 10, v[80:81]
	v_lshl_add_u64 v[86:87], v[82:83], 0, v[140:141]
	v_lshl_add_u64 v[88:89], v[86:87], 2, s[6:7]
	global_load_dwordx4 v[82:85], v[88:89], off nt
	v_lshlrev_b64 v[86:87], 1, v[86:87]
	v_lshl_add_u64 v[90:91], s[76:77], 0, v[86:87]
	s_waitcnt vmcnt(0)
	v_pk_add_f32 v[78:79], v[78:79], v[84:85]
	v_pk_add_f32 v[76:77], v[76:77], v[82:83]
	global_store_dwordx4 v[88:89], v[76:79], off nt
	v_cvt_pk_bf16_f32 v82, v76, v77
	v_cvt_pk_bf16_f32 v83, v78, v79
	global_store_dwordx2 v[90:91], v[82:83], off
	global_load_dwordx4 v[82:85], v[88:89], off offset:64 nt
	v_or_b32_e32 v90, 32, v86
	v_mov_b32_e32 v91, v87
	v_lshl_add_u64 v[90:91], s[76:77], 0, v[90:91]
	v_mul_f32_e32 v77, v77, v77
	v_mul_f32_e32 v79, v79, v79
	v_fmac_f32_e32 v77, v76, v76
	v_fmac_f32_e32 v79, v78, v78
	v_add_f32_e32 v76, v77, v79
	s_waitcnt vmcnt(0)
	v_pk_add_f32 v[74:75], v[74:75], v[84:85]
	v_pk_add_f32 v[72:73], v[72:73], v[82:83]
	global_store_dwordx4 v[88:89], v[72:75], off offset:64 nt
	v_cvt_pk_bf16_f32 v82, v72, v73
	v_cvt_pk_bf16_f32 v83, v74, v75
	global_store_dwordx2 v[90:91], v[82:83], off
	global_load_dwordx4 v[82:85], v[88:89], off offset:512 nt
	v_or_b32_e32 v90, 0x100, v86
	v_mov_b32_e32 v91, v87
	v_lshl_add_u64 v[90:91], s[76:77], 0, v[90:91]
	v_mul_f32_e32 v73, v73, v73
	v_mul_f32_e32 v75, v75, v75
	v_fmac_f32_e32 v73, v72, v72
	v_fmac_f32_e32 v75, v74, v74
	v_add_f32_e32 v72, v73, v75
	v_add_f32_e32 v72, v76, v72
	v_or_b32_e32 v86, 0x120, v86
	s_waitcnt vmcnt(0)
	v_pk_add_f32 v[70:71], v[70:71], v[84:85]
	v_pk_add_f32 v[68:69], v[68:69], v[82:83]
	global_store_dwordx4 v[88:89], v[68:71], off offset:512 nt
	v_cvt_pk_bf16_f32 v82, v68, v69
	v_cvt_pk_bf16_f32 v83, v70, v71
	global_store_dwordx2 v[90:91], v[82:83], off
	global_load_dwordx4 v[82:85], v[88:89], off offset:576 nt
	v_mul_f32_e32 v69, v69, v69
	v_mul_f32_e32 v71, v71, v71
	v_fmac_f32_e32 v69, v68, v68
	v_fmac_f32_e32 v71, v70, v70
	v_add_f32_e32 v68, v69, v71
	v_add_f32_e32 v68, v72, v68
	s_waitcnt vmcnt(0)
	v_pk_add_f32 v[66:67], v[66:67], v[84:85]
	v_pk_add_f32 v[64:65], v[64:65], v[82:83]
	v_mul_f32_e32 v70, v67, v67
	v_mul_f32_e32 v69, v65, v65
	v_fmac_f32_e32 v69, v64, v64
	v_fmac_f32_e32 v70, v66, v66
	v_add_f32_e32 v69, v69, v70
	v_add_f32_e32 v69, v68, v69
	ds_bpermute_b32 v70, v116, v69
	global_store_dwordx4 v[88:89], v[64:67], off offset:576 nt
	v_cvt_pk_bf16_f32 v68, v64, v65
	s_waitcnt lgkmcnt(0)
	s_nop 0
	v_add_f32_e32 v64, v69, v70
	ds_bpermute_b32 v65, v114, v64
	v_cvt_pk_bf16_f32 v69, v66, v67
	v_lshl_add_u64 v[66:67], s[76:77], 0, v[86:87]
	global_store_dwordx2 v[66:67], v[68:69], off
	s_and_saveexec_b64 s[26:27], s[2:3]
	s_cbranch_execz .LBB0_1564
	v_lshlrev_b64 v[66:67], 6, v[80:81]
	v_lshl_add_u64 v[66:67], s[74:75], 0, v[66:67]
	v_lshl_add_u64 v[66:67], s[24:25], 2, v[66:67]
	s_lshl_b32 s8, s43, 2
	v_lshl_add_u64 v[66:67], v[66:67], 0, s[8:9]
	s_waitcnt lgkmcnt(0)
	v_add_f32_e32 v64, v64, v65
	global_store_dword v[66:67], v64, off
.LBB0_1564:
	s_or_b64 exec, exec, s[26:27]
	v_add_u32_e32 v64, 0x80, v142
	s_waitcnt lgkmcnt(0)
	v_ashrrev_i32_e32 v65, 31, v64
	v_lshlrev_b64 v[66:67], 10, v[64:65]
	v_lshl_add_u64 v[70:71], v[66:67], 0, v[140:141]
	v_lshl_add_u64 v[72:73], v[70:71], 2, s[6:7]
	global_load_dwordx4 v[66:69], v[72:73], off nt
	v_lshlrev_b64 v[70:71], 1, v[70:71]
	v_lshl_add_u64 v[74:75], s[76:77], 0, v[70:71]
	s_waitcnt vmcnt(0)
	v_pk_add_f32 v[62:63], v[62:63], v[68:69]
	v_pk_add_f32 v[60:61], v[60:61], v[66:67]
	global_store_dwordx4 v[72:73], v[60:63], off nt
	v_cvt_pk_bf16_f32 v66, v60, v61
	v_cvt_pk_bf16_f32 v67, v62, v63
	global_store_dwordx2 v[74:75], v[66:67], off
	global_load_dwordx4 v[66:69], v[72:73], off offset:64 nt
	v_or_b32_e32 v74, 32, v70
	v_mov_b32_e32 v75, v71
	v_lshl_add_u64 v[74:75], s[76:77], 0, v[74:75]
	v_mul_f32_e32 v61, v61, v61
	v_mul_f32_e32 v63, v63, v63
	v_fmac_f32_e32 v61, v60, v60
	v_fmac_f32_e32 v63, v62, v62
	v_add_f32_e32 v60, v61, v63
	s_waitcnt vmcnt(0)
	v_pk_add_f32 v[58:59], v[58:59], v[68:69]
	v_pk_add_f32 v[56:57], v[56:57], v[66:67]
	global_store_dwordx4 v[72:73], v[56:59], off offset:64 nt
	v_cvt_pk_bf16_f32 v66, v56, v57
	v_cvt_pk_bf16_f32 v67, v58, v59
	global_store_dwordx2 v[74:75], v[66:67], off
	global_load_dwordx4 v[66:69], v[72:73], off offset:512 nt
	v_or_b32_e32 v74, 0x100, v70
	v_mov_b32_e32 v75, v71
	v_lshl_add_u64 v[74:75], s[76:77], 0, v[74:75]
	v_mul_f32_e32 v57, v57, v57
	v_mul_f32_e32 v59, v59, v59
	v_fmac_f32_e32 v57, v56, v56
	v_fmac_f32_e32 v59, v58, v58
	v_add_f32_e32 v56, v57, v59
	v_add_f32_e32 v56, v60, v56
	v_or_b32_e32 v70, 0x120, v70
	s_waitcnt vmcnt(0)
	v_pk_add_f32 v[54:55], v[54:55], v[68:69]
	v_pk_add_f32 v[52:53], v[52:53], v[66:67]
	global_store_dwordx4 v[72:73], v[52:55], off offset:512 nt
	v_cvt_pk_bf16_f32 v66, v52, v53
	v_cvt_pk_bf16_f32 v67, v54, v55
	global_store_dwordx2 v[74:75], v[66:67], off
	global_load_dwordx4 v[66:69], v[72:73], off offset:576 nt
	v_mul_f32_e32 v53, v53, v53
	v_mul_f32_e32 v55, v55, v55
	v_fmac_f32_e32 v53, v52, v52
	v_fmac_f32_e32 v55, v54, v54
	v_add_f32_e32 v52, v53, v55
	v_add_f32_e32 v52, v56, v52
	s_waitcnt vmcnt(0)
	v_pk_add_f32 v[50:51], v[50:51], v[68:69]
	v_pk_add_f32 v[48:49], v[48:49], v[66:67]
	v_mul_f32_e32 v54, v51, v51
	v_mul_f32_e32 v53, v49, v49
	v_fmac_f32_e32 v53, v48, v48
	v_fmac_f32_e32 v54, v50, v50
	v_add_f32_e32 v53, v53, v54
	v_add_f32_e32 v53, v52, v53
	ds_bpermute_b32 v54, v116, v53
	global_store_dwordx4 v[72:73], v[48:51], off offset:576 nt
	v_cvt_pk_bf16_f32 v52, v48, v49
	s_waitcnt lgkmcnt(0)
	s_nop 0
	v_add_f32_e32 v48, v53, v54
	ds_bpermute_b32 v49, v114, v48
	v_cvt_pk_bf16_f32 v53, v50, v51
	v_lshl_add_u64 v[50:51], s[76:77], 0, v[70:71]
	global_store_dwordx2 v[50:51], v[52:53], off
	s_and_saveexec_b64 s[26:27], s[2:3]
	s_cbranch_execz .LBB0_1566
	v_lshlrev_b64 v[50:51], 6, v[64:65]
	v_lshl_add_u64 v[50:51], s[74:75], 0, v[50:51]
	v_lshl_add_u64 v[50:51], s[24:25], 2, v[50:51]
	s_lshl_b32 s8, s43, 2
	v_lshl_add_u64 v[50:51], v[50:51], 0, s[8:9]
	s_waitcnt lgkmcnt(0)
	v_add_f32_e32 v48, v48, v49
	global_store_dword v[50:51], v48, off
.LBB0_1566:
	s_or_b64 exec, exec, s[26:27]
	v_add_u32_e32 v48, 0x90, v142
	s_waitcnt lgkmcnt(0)
	v_ashrrev_i32_e32 v49, 31, v48
	v_lshlrev_b64 v[50:51], 10, v[48:49]
	v_lshl_add_u64 v[54:55], v[50:51], 0, v[140:141]
	v_lshl_add_u64 v[56:57], v[54:55], 2, s[6:7]
	global_load_dwordx4 v[50:53], v[56:57], off nt
	v_lshlrev_b64 v[54:55], 1, v[54:55]
	v_lshl_add_u64 v[58:59], s[76:77], 0, v[54:55]
	s_waitcnt vmcnt(0)
	v_pk_add_f32 v[46:47], v[46:47], v[52:53]
	v_pk_add_f32 v[44:45], v[44:45], v[50:51]
	global_store_dwordx4 v[56:57], v[44:47], off nt
	v_cvt_pk_bf16_f32 v50, v44, v45
	v_cvt_pk_bf16_f32 v51, v46, v47
	global_store_dwordx2 v[58:59], v[50:51], off
	global_load_dwordx4 v[50:53], v[56:57], off offset:64 nt
	v_or_b32_e32 v58, 32, v54
	v_mov_b32_e32 v59, v55
	v_lshl_add_u64 v[58:59], s[76:77], 0, v[58:59]
	v_mul_f32_e32 v45, v45, v45
	v_mul_f32_e32 v47, v47, v47
	v_fmac_f32_e32 v45, v44, v44
	v_fmac_f32_e32 v47, v46, v46
	v_add_f32_e32 v44, v45, v47
	s_waitcnt vmcnt(0)
	v_pk_add_f32 v[42:43], v[42:43], v[52:53]
	v_pk_add_f32 v[40:41], v[40:41], v[50:51]
	global_store_dwordx4 v[56:57], v[40:43], off offset:64 nt
	v_cvt_pk_bf16_f32 v50, v40, v41
	v_cvt_pk_bf16_f32 v51, v42, v43
	global_store_dwordx2 v[58:59], v[50:51], off
	global_load_dwordx4 v[50:53], v[56:57], off offset:512 nt
	v_or_b32_e32 v58, 0x100, v54
	v_mov_b32_e32 v59, v55
	v_lshl_add_u64 v[58:59], s[76:77], 0, v[58:59]
	v_mul_f32_e32 v41, v41, v41
	v_mul_f32_e32 v43, v43, v43
	v_fmac_f32_e32 v41, v40, v40
	v_fmac_f32_e32 v43, v42, v42
	v_add_f32_e32 v40, v41, v43
	v_add_f32_e32 v40, v44, v40
	v_or_b32_e32 v54, 0x120, v54
	s_waitcnt vmcnt(0)
	v_pk_add_f32 v[38:39], v[38:39], v[52:53]
	v_pk_add_f32 v[36:37], v[36:37], v[50:51]
	global_store_dwordx4 v[56:57], v[36:39], off offset:512 nt
	v_cvt_pk_bf16_f32 v50, v36, v37
	v_cvt_pk_bf16_f32 v51, v38, v39
	global_store_dwordx2 v[58:59], v[50:51], off
	global_load_dwordx4 v[50:53], v[56:57], off offset:576 nt
	v_mul_f32_e32 v37, v37, v37
	v_mul_f32_e32 v39, v39, v39
	v_fmac_f32_e32 v37, v36, v36
	v_fmac_f32_e32 v39, v38, v38
	v_add_f32_e32 v36, v37, v39
	v_add_f32_e32 v36, v40, v36
	s_waitcnt vmcnt(0)
	v_pk_add_f32 v[34:35], v[34:35], v[52:53]
	v_pk_add_f32 v[32:33], v[32:33], v[50:51]
	v_mul_f32_e32 v38, v35, v35
	v_mul_f32_e32 v37, v33, v33
	v_fmac_f32_e32 v37, v32, v32
	v_fmac_f32_e32 v38, v34, v34
	v_add_f32_e32 v37, v37, v38
	v_add_f32_e32 v37, v36, v37
	ds_bpermute_b32 v38, v116, v37
	global_store_dwordx4 v[56:57], v[32:35], off offset:576 nt
	v_cvt_pk_bf16_f32 v36, v32, v33
	s_waitcnt lgkmcnt(0)
	s_nop 0
	v_add_f32_e32 v32, v37, v38
	ds_bpermute_b32 v33, v114, v32
	v_cvt_pk_bf16_f32 v37, v34, v35
	v_lshl_add_u64 v[34:35], s[76:77], 0, v[54:55]
	global_store_dwordx2 v[34:35], v[36:37], off
	s_and_saveexec_b64 s[26:27], s[2:3]
	s_cbranch_execz .LBB0_1568
	v_lshlrev_b64 v[34:35], 6, v[48:49]
	v_lshl_add_u64 v[34:35], s[74:75], 0, v[34:35]
	v_lshl_add_u64 v[34:35], s[24:25], 2, v[34:35]
	s_lshl_b32 s8, s43, 2
	v_lshl_add_u64 v[34:35], v[34:35], 0, s[8:9]
	s_waitcnt lgkmcnt(0)
	v_add_f32_e32 v32, v32, v33
	global_store_dword v[34:35], v32, off
.LBB0_1568:
	s_or_b64 exec, exec, s[26:27]
	v_add_u32_e32 v32, 0xa0, v142
	s_waitcnt lgkmcnt(0)
	v_ashrrev_i32_e32 v33, 31, v32
	v_lshlrev_b64 v[34:35], 10, v[32:33]
	v_lshl_add_u64 v[38:39], v[34:35], 0, v[140:141]
	v_lshl_add_u64 v[40:41], v[38:39], 2, s[6:7]
	global_load_dwordx4 v[34:37], v[40:41], off nt
	v_lshlrev_b64 v[38:39], 1, v[38:39]
	v_lshl_add_u64 v[42:43], s[76:77], 0, v[38:39]
	s_waitcnt vmcnt(0)
	v_pk_add_f32 v[30:31], v[30:31], v[36:37]
	v_pk_add_f32 v[28:29], v[28:29], v[34:35]
	global_store_dwordx4 v[40:41], v[28:31], off nt
	v_cvt_pk_bf16_f32 v34, v28, v29
	v_cvt_pk_bf16_f32 v35, v30, v31
	global_store_dwordx2 v[42:43], v[34:35], off
	global_load_dwordx4 v[34:37], v[40:41], off offset:64 nt
	v_or_b32_e32 v42, 32, v38
	v_mov_b32_e32 v43, v39
	v_lshl_add_u64 v[42:43], s[76:77], 0, v[42:43]
	v_mul_f32_e32 v29, v29, v29
	v_mul_f32_e32 v31, v31, v31
	v_fmac_f32_e32 v29, v28, v28
	v_fmac_f32_e32 v31, v30, v30
	v_add_f32_e32 v28, v29, v31
	s_waitcnt vmcnt(0)
	v_pk_add_f32 v[26:27], v[26:27], v[36:37]
	v_pk_add_f32 v[24:25], v[24:25], v[34:35]
	global_store_dwordx4 v[40:41], v[24:27], off offset:64 nt
	v_cvt_pk_bf16_f32 v34, v24, v25
	v_cvt_pk_bf16_f32 v35, v26, v27
	global_store_dwordx2 v[42:43], v[34:35], off
	global_load_dwordx4 v[34:37], v[40:41], off offset:512 nt
	v_or_b32_e32 v42, 0x100, v38
	v_mov_b32_e32 v43, v39
	v_lshl_add_u64 v[42:43], s[76:77], 0, v[42:43]
	v_mul_f32_e32 v25, v25, v25
	v_mul_f32_e32 v27, v27, v27
	v_fmac_f32_e32 v25, v24, v24
	v_fmac_f32_e32 v27, v26, v26
	v_add_f32_e32 v24, v25, v27
	v_add_f32_e32 v24, v28, v24
	v_or_b32_e32 v38, 0x120, v38
	s_waitcnt vmcnt(0)
	v_pk_add_f32 v[22:23], v[22:23], v[36:37]
	v_pk_add_f32 v[20:21], v[20:21], v[34:35]
	global_store_dwordx4 v[40:41], v[20:23], off offset:512 nt
	v_cvt_pk_bf16_f32 v34, v20, v21
	v_cvt_pk_bf16_f32 v35, v22, v23
	global_store_dwordx2 v[42:43], v[34:35], off
	global_load_dwordx4 v[34:37], v[40:41], off offset:576 nt
	v_mul_f32_e32 v21, v21, v21
	v_mul_f32_e32 v23, v23, v23
	v_fmac_f32_e32 v21, v20, v20
	v_fmac_f32_e32 v23, v22, v22
	v_add_f32_e32 v20, v21, v23
	v_add_f32_e32 v20, v24, v20
	s_waitcnt vmcnt(0)
	v_pk_add_f32 v[18:19], v[18:19], v[36:37]
	v_pk_add_f32 v[16:17], v[16:17], v[34:35]
	v_mul_f32_e32 v22, v19, v19
	v_mul_f32_e32 v21, v17, v17
	v_fmac_f32_e32 v21, v16, v16
	v_fmac_f32_e32 v22, v18, v18
	v_add_f32_e32 v21, v21, v22
	v_add_f32_e32 v21, v20, v21
	ds_bpermute_b32 v22, v116, v21
	global_store_dwordx4 v[40:41], v[16:19], off offset:576 nt
	v_cvt_pk_bf16_f32 v20, v16, v17
	s_waitcnt lgkmcnt(0)
	s_nop 0
	v_add_f32_e32 v16, v21, v22
	ds_bpermute_b32 v17, v114, v16
	v_cvt_pk_bf16_f32 v21, v18, v19
	v_lshl_add_u64 v[18:19], s[76:77], 0, v[38:39]
	global_store_dwordx2 v[18:19], v[20:21], off
	s_and_saveexec_b64 s[26:27], s[2:3]
	s_cbranch_execz .LBB0_1570
	v_lshlrev_b64 v[18:19], 6, v[32:33]
	v_lshl_add_u64 v[18:19], s[74:75], 0, v[18:19]
	v_lshl_add_u64 v[18:19], s[24:25], 2, v[18:19]
	s_lshl_b32 s8, s43, 2
	v_lshl_add_u64 v[18:19], v[18:19], 0, s[8:9]
	s_waitcnt lgkmcnt(0)
	v_add_f32_e32 v16, v16, v17
	global_store_dword v[18:19], v16, off
.LBB0_1570:
	s_or_b64 exec, exec, s[26:27]
	v_add_u32_e32 v16, 0xb0, v142
	s_waitcnt lgkmcnt(0)
	v_ashrrev_i32_e32 v17, 31, v16
	v_lshlrev_b64 v[18:19], 10, v[16:17]
	v_lshl_add_u64 v[22:23], v[18:19], 0, v[140:141]
	v_lshl_add_u64 v[24:25], v[22:23], 2, s[6:7]
	global_load_dwordx4 v[18:21], v[24:25], off nt
	v_lshlrev_b64 v[22:23], 1, v[22:23]
	v_lshl_add_u64 v[26:27], s[76:77], 0, v[22:23]
	s_waitcnt vmcnt(0)
	v_pk_add_f32 v[14:15], v[14:15], v[20:21]
	v_pk_add_f32 v[12:13], v[12:13], v[18:19]
	global_store_dwordx4 v[24:25], v[12:15], off nt
	v_cvt_pk_bf16_f32 v18, v12, v13
	v_cvt_pk_bf16_f32 v19, v14, v15
	global_store_dwordx2 v[26:27], v[18:19], off
	global_load_dwordx4 v[18:21], v[24:25], off offset:64 nt
	v_or_b32_e32 v26, 32, v22
	v_mov_b32_e32 v27, v23
	v_lshl_add_u64 v[26:27], s[76:77], 0, v[26:27]
	v_mul_f32_e32 v13, v13, v13
	v_mul_f32_e32 v15, v15, v15
	v_fmac_f32_e32 v13, v12, v12
	v_fmac_f32_e32 v15, v14, v14
	v_add_f32_e32 v12, v13, v15
	s_waitcnt vmcnt(0)
	v_pk_add_f32 v[10:11], v[10:11], v[20:21]
	v_pk_add_f32 v[8:9], v[8:9], v[18:19]
	global_store_dwordx4 v[24:25], v[8:11], off offset:64 nt
	v_cvt_pk_bf16_f32 v18, v8, v9
	v_cvt_pk_bf16_f32 v19, v10, v11
	global_store_dwordx2 v[26:27], v[18:19], off
	global_load_dwordx4 v[18:21], v[24:25], off offset:512 nt
	v_or_b32_e32 v26, 0x100, v22
	v_mov_b32_e32 v27, v23
	v_lshl_add_u64 v[26:27], s[76:77], 0, v[26:27]
	v_mul_f32_e32 v9, v9, v9
	v_mul_f32_e32 v11, v11, v11
	v_fmac_f32_e32 v9, v8, v8
	v_fmac_f32_e32 v11, v10, v10
	v_add_f32_e32 v8, v9, v11
	v_add_f32_e32 v8, v12, v8
	v_or_b32_e32 v22, 0x120, v22
	s_waitcnt vmcnt(0)
	v_pk_add_f32 v[6:7], v[6:7], v[20:21]
	v_pk_add_f32 v[4:5], v[4:5], v[18:19]
	global_store_dwordx4 v[24:25], v[4:7], off offset:512 nt
	v_cvt_pk_bf16_f32 v18, v4, v5
	v_cvt_pk_bf16_f32 v19, v6, v7
	global_store_dwordx2 v[26:27], v[18:19], off
	global_load_dwordx4 v[18:21], v[24:25], off offset:576 nt
	v_mul_f32_e32 v5, v5, v5
	v_mul_f32_e32 v7, v7, v7
	v_fmac_f32_e32 v5, v4, v4
	v_fmac_f32_e32 v7, v6, v6
	v_add_f32_e32 v4, v5, v7
	v_add_f32_e32 v4, v8, v4
	s_waitcnt vmcnt(0)
	v_pk_add_f32 v[2:3], v[2:3], v[20:21]
	v_pk_add_f32 v[0:1], v[0:1], v[18:19]
	v_mul_f32_e32 v6, v3, v3
	v_mul_f32_e32 v5, v1, v1
	v_fmac_f32_e32 v5, v0, v0
	v_fmac_f32_e32 v6, v2, v2
	v_add_f32_e32 v5, v5, v6
	v_add_f32_e32 v5, v4, v5
	ds_bpermute_b32 v6, v116, v5
	global_store_dwordx4 v[24:25], v[0:3], off offset:576 nt
	v_cvt_pk_bf16_f32 v4, v0, v1
	s_waitcnt lgkmcnt(0)
	s_nop 0
	v_add_f32_e32 v0, v5, v6
	ds_bpermute_b32 v1, v114, v0
	v_cvt_pk_bf16_f32 v5, v2, v3
	v_lshl_add_u64 v[2:3], s[76:77], 0, v[22:23]
	global_store_dwordx2 v[2:3], v[4:5], off
	s_and_saveexec_b64 s[26:27], s[2:3]
	s_cbranch_execz .LBB0_1572
	v_lshlrev_b64 v[2:3], 6, v[16:17]
	v_lshl_add_u64 v[2:3], s[74:75], 0, v[2:3]
	v_lshl_add_u64 v[2:3], s[24:25], 2, v[2:3]
	s_lshl_b32 s8, s43, 2
	v_lshl_add_u64 v[2:3], v[2:3], 0, s[8:9]
	s_waitcnt lgkmcnt(0)
	v_add_f32_e32 v0, v0, v1
	global_store_dword v[2:3], v0, off

.LBB0_1708:
	v_lshl_add_u32 v180, s54, 8, v142
	v_lshl_or_b32 v140, s55, 8, v144
	v_ashrrev_i32_e32 v181, 31, v180
	v_ashrrev_i32_e32 v141, 31, v140
	v_lshlrev_b64 v[148:149], 12, v[180:181]
	v_or_b32_e32 v164, 16, v180
	v_lshl_add_u64 v[148:149], s[6:7], 0, v[148:149]
	v_lshlrev_b64 v[182:183], 2, v[140:141]
	v_ashrrev_i32_e32 v165, 31, v164
	v_lshl_add_u64 v[140:141], v[148:149], 0, v[182:183]
	v_lshlrev_b64 v[164:165], 12, v[164:165]
	global_load_dwordx4 v[148:151], v[140:141], off nt
	global_load_dwordx4 v[152:155], v[140:141], off offset:64 nt
	global_load_dwordx4 v[156:159], v[140:141], off offset:512 nt
	global_load_dwordx4 v[160:163], v[140:141], off offset:576 nt
	v_lshl_add_u64 v[164:165], s[6:7], 0, v[164:165]
	v_lshl_add_u64 v[184:185], v[164:165], 0, v[182:183]
	global_load_dwordx4 v[164:167], v[184:185], off nt
	global_load_dwordx4 v[168:171], v[184:185], off offset:64 nt
	global_load_dwordx4 v[172:175], v[184:185], off offset:512 nt
	global_load_dwordx4 v[176:179], v[184:185], off offset:576 nt
	v_or_b32_e32 v186, 32, v180
	v_or_b32_e32 v180, 48, v180
	v_ashrrev_i32_e32 v187, 31, v186
	v_lshlrev_b64 v[186:187], 12, v[186:187]
	v_ashrrev_i32_e32 v181, 31, v180
	v_lshl_add_u64 v[186:187], s[6:7], 0, v[186:187]
	v_lshl_add_u64 v[186:187], v[186:187], 0, v[182:183]
	s_waitcnt vmcnt(0)
	v_pk_fma_f32 v[126:127], v[126:127], 0.5, v[150:151] op_sel_hi:[1,0,1]
	v_pk_fma_f32 v[124:125], v[124:125], 0.5, v[148:149] op_sel_hi:[1,0,1]
	v_pk_fma_f32 v[108:109], v[108:109], 0.5, v[156:157] op_sel_hi:[1,0,1]
	v_pk_fma_f32 v[106:107], v[106:107], 0.5, v[162:163] op_sel_hi:[1,0,1]
	v_pk_fma_f32 v[104:105], v[104:105], 0.5, v[160:161] op_sel_hi:[1,0,1]
	v_pk_fma_f32 v[122:123], v[122:123], 0.5, v[154:155] op_sel_hi:[1,0,1]
	v_pk_fma_f32 v[120:121], v[120:121], 0.5, v[152:153] op_sel_hi:[1,0,1]
	v_pk_fma_f32 v[110:111], v[110:111], 0.5, v[158:159] op_sel_hi:[1,0,1]
	global_store_dwordx4 v[140:141], v[124:127], off nt
	global_store_dwordx4 v[140:141], v[120:123], off offset:64 nt
	global_store_dwordx4 v[140:141], v[108:111], off offset:512 nt
	global_store_dwordx4 v[140:141], v[104:107], off offset:576 nt
	v_pk_fma_f32 v[102:103], v[102:103], 0.5, v[174:175] op_sel_hi:[1,0,1]
	v_pk_fma_f32 v[108:109], v[112:113], 0.5, v[168:169] op_sel_hi:[1,0,1]
	v_pk_fma_f32 v[106:107], v[118:119], 0.5, v[166:167] op_sel_hi:[1,0,1]
	v_pk_fma_f32 v[104:105], v[116:117], 0.5, v[164:165] op_sel_hi:[1,0,1]
	v_pk_fma_f32 v[110:111], v[114:115], 0.5, v[170:171] op_sel_hi:[1,0,1]
	v_pk_fma_f32 v[100:101], v[100:101], 0.5, v[172:173] op_sel_hi:[1,0,1]
	v_pk_fma_f32 v[98:99], v[98:99], 0.5, v[178:179] op_sel_hi:[1,0,1]
	v_pk_fma_f32 v[96:97], v[96:97], 0.5, v[176:177] op_sel_hi:[1,0,1]
	global_store_dwordx4 v[184:185], v[104:107], off nt
	global_store_dwordx4 v[184:185], v[108:111], off offset:64 nt
	global_store_dwordx4 v[184:185], v[100:103], off offset:512 nt
	global_store_dwordx4 v[184:185], v[96:99], off offset:576 nt
	v_lshlrev_b64 v[108:109], 12, v[180:181]
	v_lshl_add_u64 v[112:113], s[6:7], 0, v[108:109]
	global_load_dwordx4 v[96:99], v[186:187], off nt
	global_load_dwordx4 v[100:103], v[186:187], off offset:64 nt
	v_lshl_add_u64 v[148:149], v[112:113], 0, v[182:183]
	global_load_dwordx4 v[104:107], v[186:187], off offset:512 nt
	global_load_dwordx4 v[108:111], v[186:187], off offset:576 nt
	global_load_dwordx4 v[112:115], v[148:149], off nt
	global_load_dwordx4 v[116:119], v[148:149], off offset:64 nt
	global_load_dwordx4 v[120:123], v[148:149], off offset:512 nt
	global_load_dwordx4 v[124:127], v[148:149], off offset:576 nt
	v_add_co_u32_e32 v152, vcc, s48, v140
	v_lshl_add_u64 v[150:151], v[140:141], 0, s[16:17]
	s_nop 0
	v_addc_co_u32_e32 v153, vcc, 0, v141, vcc
	s_waitcnt vmcnt(7)
	v_pk_fma_f32 v[94:95], v[94:95], 0.5, v[98:99] op_sel_hi:[1,0,1]
	v_pk_fma_f32 v[92:93], v[92:93], 0.5, v[96:97] op_sel_hi:[1,0,1]
	s_waitcnt vmcnt(6)
	v_pk_fma_f32 v[90:91], v[90:91], 0.5, v[102:103] op_sel_hi:[1,0,1]
	v_pk_fma_f32 v[88:89], v[88:89], 0.5, v[100:101] op_sel_hi:[1,0,1]
	s_waitcnt vmcnt(5)
	v_pk_fma_f32 v[78:79], v[78:79], 0.5, v[106:107] op_sel_hi:[1,0,1]
	v_pk_fma_f32 v[76:77], v[76:77], 0.5, v[104:105] op_sel_hi:[1,0,1]
	s_waitcnt vmcnt(4)
	v_pk_fma_f32 v[74:75], v[74:75], 0.5, v[110:111] op_sel_hi:[1,0,1]
	v_pk_fma_f32 v[72:73], v[72:73], 0.5, v[108:109] op_sel_hi:[1,0,1]
	s_waitcnt vmcnt(3)
	v_pk_fma_f32 v[86:87], v[86:87], 0.5, v[114:115] op_sel_hi:[1,0,1]
	v_pk_fma_f32 v[84:85], v[84:85], 0.5, v[112:113] op_sel_hi:[1,0,1]
	s_waitcnt vmcnt(2)
	v_pk_fma_f32 v[82:83], v[82:83], 0.5, v[118:119] op_sel_hi:[1,0,1]
	v_pk_fma_f32 v[80:81], v[80:81], 0.5, v[116:117] op_sel_hi:[1,0,1]
	s_waitcnt vmcnt(1)
	v_pk_fma_f32 v[70:71], v[70:71], 0.5, v[122:123] op_sel_hi:[1,0,1]
	v_pk_fma_f32 v[68:69], v[68:69], 0.5, v[120:121] op_sel_hi:[1,0,1]
	s_waitcnt vmcnt(0)
	v_pk_fma_f32 v[66:67], v[66:67], 0.5, v[126:127] op_sel_hi:[1,0,1]
	v_pk_fma_f32 v[64:65], v[64:65], 0.5, v[124:125] op_sel_hi:[1,0,1]
	global_store_dwordx4 v[186:187], v[92:95], off nt
	global_store_dwordx4 v[186:187], v[88:91], off offset:64 nt
	global_store_dwordx4 v[186:187], v[76:79], off offset:512 nt
	global_store_dwordx4 v[186:187], v[72:75], off offset:576 nt
	global_store_dwordx4 v[148:149], v[84:87], off nt
	global_store_dwordx4 v[148:149], v[80:83], off offset:64 nt
	global_store_dwordx4 v[148:149], v[68:71], off offset:512 nt
	global_store_dwordx4 v[148:149], v[64:67], off offset:576 nt
	v_add_co_u32_e32 v96, vcc, s49, v140
	v_lshl_add_u64 v[98:99], v[140:141], 0, s[18:19]
	s_nop 0
	v_addc_co_u32_e32 v97, vcc, 0, v141, vcc
	global_load_dwordx4 v[64:67], v[152:153], off nt
	global_load_dwordx4 v[68:71], v[150:151], off offset:64 nt
	global_load_dwordx4 v[72:75], v[150:151], off offset:512 nt
	global_load_dwordx4 v[76:79], v[150:151], off offset:576 nt
	global_load_dwordx4 v[80:83], v[96:97], off nt
	global_load_dwordx4 v[84:87], v[98:99], off offset:64 nt
	global_load_dwordx4 v[88:91], v[98:99], off offset:512 nt
	global_load_dwordx4 v[92:95], v[98:99], off offset:576 nt
	v_add_co_u32_e32 v102, vcc, s50, v140
	v_lshl_add_u64 v[100:101], v[140:141], 0, s[20:21]
	s_nop 0
	v_addc_co_u32_e32 v103, vcc, 0, v141, vcc
	s_waitcnt vmcnt(7)
	v_pk_fma_f32 v[62:63], v[62:63], 0.5, v[66:67] op_sel_hi:[1,0,1]
	v_pk_fma_f32 v[60:61], v[60:61], 0.5, v[64:65] op_sel_hi:[1,0,1]
	s_waitcnt vmcnt(6)
	v_pk_fma_f32 v[58:59], v[58:59], 0.5, v[70:71] op_sel_hi:[1,0,1]
	v_pk_fma_f32 v[56:57], v[56:57], 0.5, v[68:69] op_sel_hi:[1,0,1]
	s_waitcnt vmcnt(5)
	v_pk_fma_f32 v[46:47], v[46:47], 0.5, v[74:75] op_sel_hi:[1,0,1]
	v_pk_fma_f32 v[44:45], v[44:45], 0.5, v[72:73] op_sel_hi:[1,0,1]
	s_waitcnt vmcnt(4)
	v_pk_fma_f32 v[42:43], v[42:43], 0.5, v[78:79] op_sel_hi:[1,0,1]
	v_pk_fma_f32 v[40:41], v[40:41], 0.5, v[76:77] op_sel_hi:[1,0,1]
	s_waitcnt vmcnt(3)
	v_pk_fma_f32 v[54:55], v[54:55], 0.5, v[82:83] op_sel_hi:[1,0,1]
	v_pk_fma_f32 v[52:53], v[52:53], 0.5, v[80:81] op_sel_hi:[1,0,1]
	s_waitcnt vmcnt(2)
	v_pk_fma_f32 v[50:51], v[50:51], 0.5, v[86:87] op_sel_hi:[1,0,1]
	v_pk_fma_f32 v[48:49], v[48:49], 0.5, v[84:85] op_sel_hi:[1,0,1]
	s_waitcnt vmcnt(1)
	v_pk_fma_f32 v[38:39], v[38:39], 0.5, v[90:91] op_sel_hi:[1,0,1]
	v_pk_fma_f32 v[36:37], v[36:37], 0.5, v[88:89] op_sel_hi:[1,0,1]
	s_waitcnt vmcnt(0)
	v_pk_fma_f32 v[34:35], v[34:35], 0.5, v[94:95] op_sel_hi:[1,0,1]
	v_pk_fma_f32 v[32:33], v[32:33], 0.5, v[92:93] op_sel_hi:[1,0,1]
	global_store_dwordx4 v[152:153], v[60:63], off nt
	global_store_dwordx4 v[150:151], v[56:59], off offset:64 nt
	global_store_dwordx4 v[150:151], v[44:47], off offset:512 nt
	global_store_dwordx4 v[150:151], v[40:43], off offset:576 nt
	global_store_dwordx4 v[96:97], v[52:55], off nt
	global_store_dwordx4 v[98:99], v[48:51], off offset:64 nt
	global_store_dwordx4 v[98:99], v[36:39], off offset:512 nt
	global_store_dwordx4 v[98:99], v[32:35], off offset:576 nt
	v_add_co_u32_e32 v64, vcc, s51, v140
	v_lshl_add_u64 v[66:67], v[140:141], 0, s[8:9]
	s_nop 0
	v_addc_co_u32_e32 v65, vcc, 0, v141, vcc
	global_load_dwordx4 v[32:35], v[102:103], off nt
	global_load_dwordx4 v[36:39], v[100:101], off offset:64 nt
	global_load_dwordx4 v[40:43], v[100:101], off offset:512 nt
	global_load_dwordx4 v[44:47], v[100:101], off offset:576 nt
	global_load_dwordx4 v[48:51], v[64:65], off nt
	global_load_dwordx4 v[52:55], v[66:67], off offset:64 nt
	global_load_dwordx4 v[56:59], v[66:67], off offset:512 nt
	global_load_dwordx4 v[60:63], v[66:67], off offset:576 nt
	s_and_b64 vcc, exec, s[2:3]
	s_mov_b64 s[2:3], -1
	s_waitcnt vmcnt(7)
	v_pk_fma_f32 v[30:31], v[30:31], 0.5, v[34:35] op_sel_hi:[1,0,1]
	v_pk_fma_f32 v[28:29], v[28:29], 0.5, v[32:33] op_sel_hi:[1,0,1]
	s_waitcnt vmcnt(6)
	v_pk_fma_f32 v[26:27], v[26:27], 0.5, v[38:39] op_sel_hi:[1,0,1]
	v_pk_fma_f32 v[24:25], v[24:25], 0.5, v[36:37] op_sel_hi:[1,0,1]
	s_waitcnt vmcnt(5)
	v_pk_fma_f32 v[14:15], v[14:15], 0.5, v[42:43] op_sel_hi:[1,0,1]
	v_pk_fma_f32 v[12:13], v[12:13], 0.5, v[40:41] op_sel_hi:[1,0,1]
	s_waitcnt vmcnt(4)
	v_pk_fma_f32 v[10:11], v[10:11], 0.5, v[46:47] op_sel_hi:[1,0,1]
	v_pk_fma_f32 v[8:9], v[8:9], 0.5, v[44:45] op_sel_hi:[1,0,1]
	s_waitcnt vmcnt(3)
	v_pk_fma_f32 v[22:23], v[22:23], 0.5, v[50:51] op_sel_hi:[1,0,1]
	v_pk_fma_f32 v[20:21], v[20:21], 0.5, v[48:49] op_sel_hi:[1,0,1]
	s_waitcnt vmcnt(2)
	v_pk_fma_f32 v[18:19], v[18:19], 0.5, v[54:55] op_sel_hi:[1,0,1]
	v_pk_fma_f32 v[16:17], v[16:17], 0.5, v[52:53] op_sel_hi:[1,0,1]
	s_waitcnt vmcnt(1)
	v_pk_fma_f32 v[6:7], v[6:7], 0.5, v[58:59] op_sel_hi:[1,0,1]
	v_pk_fma_f32 v[4:5], v[4:5], 0.5, v[56:57] op_sel_hi:[1,0,1]
	s_waitcnt vmcnt(0)
	v_pk_fma_f32 v[2:3], v[2:3], 0.5, v[62:63] op_sel_hi:[1,0,1]
	v_pk_fma_f32 v[0:1], v[0:1], 0.5, v[60:61] op_sel_hi:[1,0,1]
	global_store_dwordx4 v[102:103], v[28:31], off nt
	global_store_dwordx4 v[100:101], v[24:27], off offset:64 nt
	global_store_dwordx4 v[100:101], v[12:15], off offset:512 nt
	global_store_dwordx4 v[100:101], v[8:11], off offset:576 nt
	global_store_dwordx4 v[64:65], v[20:23], off nt
	global_store_dwordx4 v[66:67], v[16:19], off offset:64 nt
	global_store_dwordx4 v[66:67], v[4:7], off offset:512 nt
	global_store_dwordx4 v[66:67], v[0:3], off offset:576 nt
	s_cbranch_vccnz .LBB0_1693
	s_andn2_b64 vcc, exec, s[10:11]
	s_cbranch_vccnz .LBB0_1692
	s_barrier
	s_branch .LBB0_1692
